# speedup vs baseline: 1.0262x; 1.0262x over previous
; __device__ __forceinline__ uint4 pk8(f32x4 a, f32x4 b) { return make_uint4(cvt_pk_bf16(a[0], a[1]), cvt_pk_bf16(a[2], a[3]), cvt_pk_bf16(b[0], b[1]), cvt_pk_bf16(b[2], b[3])); }
;     __device__ __forceinline__ void operator()(AccRef acc, const Unit& u, int wr, int wc, int fr, int fq) const {
;         const int pi = u.pn / tpp; bf16_t* base = pi == 0 ? pl[0] : (pi == 1 ? pl[1] : (pi == 2 ? pl[2] : pl[3]));
;         const int cbase = (u.pn - pi * tpp) * 256 + wc * 32 + 8 * fq;
; #pragma unroll
;         for (int ai = 0; ai < 2; ++ai)
; #pragma unroll
;             for (int m = 0; m < 4; ++m) {
;                 const int r = u.pm * 256 + ai * 128 + wr * 64 + m * 16 + fr;
;                 float s = 1.f;
;                 if (SCALE == 1) s = rs[r];
;                 if (SCALE == 2) s = rsqrtf(rs[r] * (1.f / D) + EPS);
;                 bf16_t* rowp = base + (size_t)r * ldc + cbase;
; #pragma unroll
;                 for (int bj = 0; bj < 2; ++bj) *(uint4*)(rowp + bj * 128) = pk8(acc[ai][bj][m][0] * s, acc[ai][bj][m][1] * s);
;             }
;     }
.LBB0_107:
	s_lshl_b32 s11, s18, 8
	v_add_u32_e32 v138, s11, v158
	v_ashrrev_i32_e32 v139, 31, v138
	v_lshl_add_u64 v[136:137], v[138:139], 2, s[28:29]
	global_load_dword v168, v[136:137], off
	s_lshl_b32 s13, s13, 10
	s_lshl_b32 s18, s50, 8
	s_sub_i32 s13, s18, s13
	v_or_b32_e32 v136, s13, v163
	v_ashrrev_i32_e32 v137, 31, v136
	v_add_u32_e32 v170, s11, v160
	v_lshlrev_b64 v[172:173], 11, v[138:139]
	v_lshl_add_u64 v[136:137], v[136:137], 1, s[20:21]
	v_ashrrev_i32_e32 v171, 31, v170
	v_lshl_add_u64 v[172:173], v[136:137], 0, v[172:173]
	v_lshl_add_u64 v[174:175], v[170:171], 2, s[28:29]
	s_and_b64 vcc, exec, s[4:5]
	s_mov_b32 s50, s10
	s_mov_b32 s18, s12
	s_mov_b64 s[22:23], s[16:17]
	s_mov_b64 s[20:21], s[14:15]
	global_load_dword v178, v[174:175], off
	v_add_u32_e32 v200, s11, v161
	v_ashrrev_i32_e32 v201, 31, v200
	v_lshl_add_u64 v[202:203], v[200:201], 2, s[28:29]
	global_load_dword v180, v[202:203], off
	v_add_u32_e32 v200, s11, v162
	v_ashrrev_i32_e32 v201, 31, v200
	v_lshl_add_u64 v[202:203], v[200:201], 2, s[28:29]
	global_load_dword v182, v[202:203], off
	v_add_u32_e32 v200, 0x80, v138
	v_ashrrev_i32_e32 v201, 31, v200
	v_lshl_add_u64 v[202:203], v[200:201], 2, s[28:29]
	global_load_dword v184, v[202:203], off
	v_add_u32_e32 v200, 0x90, v138
	v_ashrrev_i32_e32 v201, 31, v200
	v_lshl_add_u64 v[202:203], v[200:201], 2, s[28:29]
	global_load_dword v186, v[202:203], off
	v_add_u32_e32 v200, 0xa0, v138
	v_ashrrev_i32_e32 v201, 31, v200
	v_lshl_add_u64 v[202:203], v[200:201], 2, s[28:29]
	global_load_dword v188, v[202:203], off
	v_add_u32_e32 v200, 0xb0, v138
	v_ashrrev_i32_e32 v201, 31, v200
	v_lshl_add_u64 v[202:203], v[200:201], 2, s[28:29]
	global_load_dword v190, v[202:203], off
	s_waitcnt vmcnt(7)
	v_pk_mul_f32 v[126:127], v[126:127], v[168:169] op_sel_hi:[1,0]
	v_pk_mul_f32 v[124:125], v[124:125], v[168:169] op_sel_hi:[1,0]
	v_pk_mul_f32 v[122:123], v[122:123], v[168:169] op_sel_hi:[1,0]
	v_pk_mul_f32 v[120:121], v[120:121], v[168:169] op_sel_hi:[1,0]
	v_pk_mul_f32 v[118:119], v[118:119], v[168:169] op_sel_hi:[1,0]
	v_pk_mul_f32 v[116:117], v[116:117], v[168:169] op_sel_hi:[1,0]
	v_pk_mul_f32 v[176:177], v[114:115], v[168:169] op_sel_hi:[1,0]
	v_pk_mul_f32 v[168:169], v[112:113], v[168:169] op_sel_hi:[1,0]
	v_cvt_pk_bf16_f32 v112, v124, v125
	v_cvt_pk_bf16_f32 v113, v126, v127
	v_cvt_pk_bf16_f32 v114, v120, v121
	v_cvt_pk_bf16_f32 v115, v122, v123
	global_store_dwordx4 v[172:173], v[112:115], off
	s_nop 1
	v_cvt_pk_bf16_f32 v112, v116, v117
	v_cvt_pk_bf16_f32 v113, v118, v119
	v_cvt_pk_bf16_f32 v114, v168, v169
	v_cvt_pk_bf16_f32 v115, v176, v177
	global_store_dwordx4 v[172:173], v[112:115], off offset:256
	v_lshlrev_b64 v[116:117], 11, v[170:171]
	v_add_u32_e32 v114, s11, v161
	v_ashrrev_i32_e32 v115, 31, v114
	v_lshl_add_u64 v[116:117], v[136:137], 0, v[116:117]
	v_lshl_add_u64 v[118:119], v[114:115], 2, s[28:29]
	s_waitcnt vmcnt(8)
	v_pk_mul_f32 v[110:111], v[110:111], v[178:179] op_sel_hi:[1,0]
	v_pk_mul_f32 v[108:109], v[108:109], v[178:179] op_sel_hi:[1,0]
	v_pk_mul_f32 v[106:107], v[106:107], v[178:179] op_sel_hi:[1,0]
	v_pk_mul_f32 v[104:105], v[104:105], v[178:179] op_sel_hi:[1,0]
	v_pk_mul_f32 v[102:103], v[102:103], v[178:179] op_sel_hi:[1,0]
	v_pk_mul_f32 v[100:101], v[100:101], v[178:179] op_sel_hi:[1,0]
	v_pk_mul_f32 v[120:121], v[98:99], v[178:179] op_sel_hi:[1,0]
	v_pk_mul_f32 v[112:113], v[96:97], v[178:179] op_sel_hi:[1,0]
	v_cvt_pk_bf16_f32 v96, v108, v109
	v_cvt_pk_bf16_f32 v97, v110, v111
	v_cvt_pk_bf16_f32 v98, v104, v105
	v_cvt_pk_bf16_f32 v99, v106, v107
	global_store_dwordx4 v[116:117], v[96:99], off
	s_nop 1
	v_cvt_pk_bf16_f32 v96, v100, v101
	v_cvt_pk_bf16_f32 v97, v102, v103
	v_cvt_pk_bf16_f32 v98, v112, v113
	v_cvt_pk_bf16_f32 v99, v120, v121
	global_store_dwordx4 v[116:117], v[96:99], off offset:256
	v_lshlrev_b64 v[100:101], 11, v[114:115]
	v_add_u32_e32 v98, s11, v162
	v_ashrrev_i32_e32 v99, 31, v98
	v_lshl_add_u64 v[100:101], v[136:137], 0, v[100:101]
	v_lshl_add_u64 v[102:103], v[98:99], 2, s[28:29]
	s_waitcnt vmcnt(9)
	v_pk_mul_f32 v[94:95], v[94:95], v[180:181] op_sel_hi:[1,0]
	v_pk_mul_f32 v[92:93], v[92:93], v[180:181] op_sel_hi:[1,0]
	v_pk_mul_f32 v[90:91], v[90:91], v[180:181] op_sel_hi:[1,0]
	v_pk_mul_f32 v[88:89], v[88:89], v[180:181] op_sel_hi:[1,0]
	v_pk_mul_f32 v[86:87], v[86:87], v[180:181] op_sel_hi:[1,0]
	v_pk_mul_f32 v[84:85], v[84:85], v[180:181] op_sel_hi:[1,0]
	v_pk_mul_f32 v[104:105], v[82:83], v[180:181] op_sel_hi:[1,0]
	v_pk_mul_f32 v[96:97], v[80:81], v[180:181] op_sel_hi:[1,0]
	v_cvt_pk_bf16_f32 v80, v92, v93
	v_cvt_pk_bf16_f32 v81, v94, v95
	v_cvt_pk_bf16_f32 v82, v88, v89
	v_cvt_pk_bf16_f32 v83, v90, v91
	global_store_dwordx4 v[100:101], v[80:83], off
	s_nop 1
	v_cvt_pk_bf16_f32 v80, v84, v85
	v_cvt_pk_bf16_f32 v81, v86, v87
	v_cvt_pk_bf16_f32 v82, v96, v97
	v_cvt_pk_bf16_f32 v83, v104, v105
	global_store_dwordx4 v[100:101], v[80:83], off offset:256
	v_lshlrev_b64 v[84:85], 11, v[98:99]
	v_add_u32_e32 v82, 0x80, v138
	v_ashrrev_i32_e32 v83, 31, v82
	v_lshl_add_u64 v[84:85], v[136:137], 0, v[84:85]
	v_lshl_add_u64 v[86:87], v[82:83], 2, s[28:29]
	s_waitcnt vmcnt(10)
; __device__ __forceinline__ uint4 pk8(f32x4 a, f32x4 b) { return make_uint4(cvt_pk_bf16(a[0], a[1]), cvt_pk_bf16(a[2], a[3]), cvt_pk_bf16(b[0], b[1]), cvt_pk_bf16(b[2], b[3])); }
;     __device__ __forceinline__ void operator()(AccRef acc, const Unit& u, int wr, int wc, int fr, int fq) const {
;         const int pi = u.pn / tpp; bf16_t* base = pi == 0 ? pl[0] : (pi == 1 ? pl[1] : (pi == 2 ? pl[2] : pl[3]));
;         const int cbase = (u.pn - pi * tpp) * 256 + wc * 32 + 8 * fq;
; #pragma unroll
;         for (int ai = 0; ai < 2; ++ai)
; #pragma unroll
;             for (int m = 0; m < 4; ++m) {
;                 const int r = u.pm * 256 + ai * 128 + wr * 64 + m * 16 + fr;
;                 float s = 1.f;
;                 if (SCALE == 1) s = rs[r];
;                 if (SCALE == 2) s = rsqrtf(rs[r] * (1.f / D) + EPS);
;                 bf16_t* rowp = base + (size_t)r * ldc + cbase;
; #pragma unroll
;                 for (int bj = 0; bj < 2; ++bj) *(uint4*)(rowp + bj * 128) = pk8(acc[ai][bj][m][0] * s, acc[ai][bj][m][1] * s);
;             }
;     }
	v_pk_mul_f32 v[78:79], v[78:79], v[182:183] op_sel_hi:[1,0]
	v_pk_mul_f32 v[76:77], v[76:77], v[182:183] op_sel_hi:[1,0]
	v_pk_mul_f32 v[74:75], v[74:75], v[182:183] op_sel_hi:[1,0]
	v_pk_mul_f32 v[72:73], v[72:73], v[182:183] op_sel_hi:[1,0]
	v_pk_mul_f32 v[70:71], v[70:71], v[182:183] op_sel_hi:[1,0]
	v_pk_mul_f32 v[68:69], v[68:69], v[182:183] op_sel_hi:[1,0]
	v_pk_mul_f32 v[88:89], v[66:67], v[182:183] op_sel_hi:[1,0]
	v_pk_mul_f32 v[80:81], v[64:65], v[182:183] op_sel_hi:[1,0]
	v_cvt_pk_bf16_f32 v64, v76, v77
	v_cvt_pk_bf16_f32 v65, v78, v79
	v_cvt_pk_bf16_f32 v66, v72, v73
	v_cvt_pk_bf16_f32 v67, v74, v75
	global_store_dwordx4 v[84:85], v[64:67], off
	s_nop 1
	v_cvt_pk_bf16_f32 v64, v68, v69
	v_cvt_pk_bf16_f32 v65, v70, v71
	v_cvt_pk_bf16_f32 v66, v80, v81
	v_cvt_pk_bf16_f32 v67, v88, v89
	global_store_dwordx4 v[84:85], v[64:67], off offset:256
	v_lshlrev_b64 v[68:69], 11, v[82:83]
	v_add_u32_e32 v66, 0x90, v138
	v_ashrrev_i32_e32 v67, 31, v66
	v_lshl_add_u64 v[68:69], v[136:137], 0, v[68:69]
	v_lshl_add_u64 v[70:71], v[66:67], 2, s[28:29]
	s_waitcnt vmcnt(11)
	v_pk_mul_f32 v[62:63], v[62:63], v[184:185] op_sel_hi:[1,0]
	v_pk_mul_f32 v[60:61], v[60:61], v[184:185] op_sel_hi:[1,0]
	v_pk_mul_f32 v[58:59], v[58:59], v[184:185] op_sel_hi:[1,0]
	v_pk_mul_f32 v[56:57], v[56:57], v[184:185] op_sel_hi:[1,0]
	v_pk_mul_f32 v[54:55], v[54:55], v[184:185] op_sel_hi:[1,0]
	v_pk_mul_f32 v[52:53], v[52:53], v[184:185] op_sel_hi:[1,0]
	v_pk_mul_f32 v[72:73], v[50:51], v[184:185] op_sel_hi:[1,0]
	v_pk_mul_f32 v[64:65], v[48:49], v[184:185] op_sel_hi:[1,0]
	v_cvt_pk_bf16_f32 v48, v60, v61
	v_cvt_pk_bf16_f32 v49, v62, v63
	v_cvt_pk_bf16_f32 v50, v56, v57
	v_cvt_pk_bf16_f32 v51, v58, v59
	global_store_dwordx4 v[68:69], v[48:51], off
	s_nop 1
	v_cvt_pk_bf16_f32 v48, v52, v53
	v_cvt_pk_bf16_f32 v49, v54, v55
	v_cvt_pk_bf16_f32 v50, v64, v65
	v_cvt_pk_bf16_f32 v51, v72, v73
	global_store_dwordx4 v[68:69], v[48:51], off offset:256
	v_lshlrev_b64 v[52:53], 11, v[66:67]
	v_add_u32_e32 v50, 0xa0, v138
	v_ashrrev_i32_e32 v51, 31, v50
	v_lshl_add_u64 v[52:53], v[136:137], 0, v[52:53]
	v_lshl_add_u64 v[54:55], v[50:51], 2, s[28:29]
	s_waitcnt vmcnt(12)
	v_pk_mul_f32 v[46:47], v[46:47], v[186:187] op_sel_hi:[1,0]
	v_pk_mul_f32 v[44:45], v[44:45], v[186:187] op_sel_hi:[1,0]
	v_pk_mul_f32 v[42:43], v[42:43], v[186:187] op_sel_hi:[1,0]
	v_pk_mul_f32 v[40:41], v[40:41], v[186:187] op_sel_hi:[1,0]
	v_pk_mul_f32 v[38:39], v[38:39], v[186:187] op_sel_hi:[1,0]
	v_pk_mul_f32 v[36:37], v[36:37], v[186:187] op_sel_hi:[1,0]
	v_pk_mul_f32 v[56:57], v[34:35], v[186:187] op_sel_hi:[1,0]
	v_pk_mul_f32 v[48:49], v[32:33], v[186:187] op_sel_hi:[1,0]
	v_cvt_pk_bf16_f32 v32, v44, v45
	v_cvt_pk_bf16_f32 v33, v46, v47
	v_cvt_pk_bf16_f32 v34, v40, v41
	v_cvt_pk_bf16_f32 v35, v42, v43
	global_store_dwordx4 v[52:53], v[32:35], off
	s_nop 1
	v_cvt_pk_bf16_f32 v32, v36, v37
	v_cvt_pk_bf16_f32 v33, v38, v39
	v_cvt_pk_bf16_f32 v34, v48, v49
	v_cvt_pk_bf16_f32 v35, v56, v57
	global_store_dwordx4 v[52:53], v[32:35], off offset:256
	v_lshlrev_b64 v[36:37], 11, v[50:51]
	v_add_u32_e32 v34, 0xb0, v138
	v_ashrrev_i32_e32 v35, 31, v34
	v_lshl_add_u64 v[36:37], v[136:137], 0, v[36:37]
	v_lshl_add_u64 v[38:39], v[34:35], 2, s[28:29]
	s_waitcnt vmcnt(13)
	v_pk_mul_f32 v[30:31], v[30:31], v[188:189] op_sel_hi:[1,0]
	v_pk_mul_f32 v[28:29], v[28:29], v[188:189] op_sel_hi:[1,0]
	v_pk_mul_f32 v[26:27], v[26:27], v[188:189] op_sel_hi:[1,0]
	v_pk_mul_f32 v[24:25], v[24:25], v[188:189] op_sel_hi:[1,0]
	v_pk_mul_f32 v[22:23], v[22:23], v[188:189] op_sel_hi:[1,0]
	v_pk_mul_f32 v[20:21], v[20:21], v[188:189] op_sel_hi:[1,0]
	v_pk_mul_f32 v[40:41], v[18:19], v[188:189] op_sel_hi:[1,0]
	v_pk_mul_f32 v[32:33], v[16:17], v[188:189] op_sel_hi:[1,0]
	v_cvt_pk_bf16_f32 v16, v28, v29
	v_cvt_pk_bf16_f32 v17, v30, v31
	v_cvt_pk_bf16_f32 v18, v24, v25
	v_cvt_pk_bf16_f32 v19, v26, v27
	global_store_dwordx4 v[36:37], v[16:19], off
	s_nop 1
	v_cvt_pk_bf16_f32 v16, v20, v21
	v_cvt_pk_bf16_f32 v17, v22, v23
	v_cvt_pk_bf16_f32 v18, v32, v33
	v_cvt_pk_bf16_f32 v19, v40, v41
	global_store_dwordx4 v[36:37], v[16:19], off offset:256
	s_waitcnt vmcnt(14)
	v_pk_mul_f32 v[14:15], v[14:15], v[190:191] op_sel_hi:[1,0]
	v_lshlrev_b64 v[18:19], 11, v[34:35]
	v_lshl_add_u64 v[18:19], v[136:137], 0, v[18:19]
	v_pk_mul_f32 v[12:13], v[12:13], v[190:191] op_sel_hi:[1,0]
	v_pk_mul_f32 v[10:11], v[10:11], v[190:191] op_sel_hi:[1,0]
	v_pk_mul_f32 v[8:9], v[8:9], v[190:191] op_sel_hi:[1,0]
	v_pk_mul_f32 v[6:7], v[6:7], v[190:191] op_sel_hi:[1,0]
	v_pk_mul_f32 v[4:5], v[4:5], v[190:191] op_sel_hi:[1,0]
	v_pk_mul_f32 v[20:21], v[2:3], v[190:191] op_sel_hi:[1,0]
	v_pk_mul_f32 v[16:17], v[0:1], v[190:191] op_sel_hi:[1,0]
	v_cvt_pk_bf16_f32 v0, v12, v13
	v_cvt_pk_bf16_f32 v1, v14, v15
	v_cvt_pk_bf16_f32 v2, v8, v9
	v_cvt_pk_bf16_f32 v3, v10, v11
	global_store_dwordx4 v[18:19], v[0:3], off
	s_nop 1
	v_cvt_pk_bf16_f32 v0, v4, v5
	v_cvt_pk_bf16_f32 v1, v6, v7
	v_cvt_pk_bf16_f32 v2, v16, v17
	v_cvt_pk_bf16_f32 v3, v20, v21
	global_store_dwordx4 v[18:19], v[0:3], off offset:256
	s_cbranch_vccnz .LBB0_126

; #define PG8_STAGE(bufoff, gbase, voff) do { _Pragma("unroll") for (int _i = 0; _i < 2; ++_i) \
;         __builtin_amdgcn_global_load_lds((const unsigned*)((const char*)(gbase) + (voff)[_i]), (PG8_LAS unsigned*)(lds + (bufoff) + ldsw + _i * 8192), 16, 0, 0); } while (0)
; #define PG8_LDA(dst, b, h) do { _Pragma("unroll") for (int m = 0; m < 4; ++m) _Pragma("unroll") for (int k = 0; k < 2; ++k) dst[m][k] = *(const PG8_LAS bf16x8*)(lds + PG8_SA(b, h) + aoff + m * 2048 + k * 1024); } while (0)
; #define PG8_LDB(dst, b, h) do { _Pragma("unroll") for (int n = 0; n < 2; ++n) _Pragma("unroll") for (int k = 0; k < 2; ++k) dst[n][k] = *(const PG8_LAS bf16x8*)(lds + PG8_SB(b, h) + boff + n * 2048 + k * 1024); } while (0)
; #define PG8_MMA(ai, bj, At, Bt) do { __builtin_amdgcn_s_setprio(1); _Pragma("unroll") for (int m = 0; m < 4; ++m) _Pragma("unroll") for (int n = 0; n < 2; ++n) _Pragma("unroll") for (int k = 0; k < 2; ++k) \
;         acc[ai][bj][m][n] = __builtin_amdgcn_mfma_f32_16x16x32_bf16(Bt[n][k], At[m][k], acc[ai][bj][m][n], 0, 0, 0); __builtin_amdgcn_s_setprio(0); } while (0)
; #define PG8_WAIT_V(n) asm volatile("s_waitcnt vmcnt(" #n ")" ::: "memory")
; #define PG8_WAIT_L(n) asm volatile("s_waitcnt lgkmcnt(" #n ")" ::: "memory")
; #define PG8_BAR __builtin_amdgcn_s_barrier()
; #define PG8_SCHED __builtin_amdgcn_sched_barrier(0)
; template <class Epi, class Sched>
; __device__ __forceinline__ void gemm_phase(PG8_LAS unsigned char* lds, const Gemm g, const Sched& S, const Epi& E) {
;     ...
;             PG8_LDB(B0, 0, 0); PG8_SCHED; PG8_LDA(At, 0, 0); PG8_STAGE(PG8_SA(1, 1), a1 + hstep, voffA);
;             PG8_WAIT_L(8); PG8_BAR; PG8_WAIT_L(0); PG8_MMA(0, 0, At, B0); PG8_BAR; PG8_SCHED;
;             PG8_LDB(B1, 0, 1); PG8_STAGE(PG8_SB(0, 0), b2, voffB);
;             PG8_BAR; PG8_WAIT_L(0); PG8_MMA(0, 1, At, B1); PG8_BAR;
;             PG8_LDA(At, 0, 1); PG8_STAGE(PG8_SA(0, 0), a2, voffA);
;             PG8_BAR; PG8_WAIT_L(0); PG8_MMA(1, 0, At, B0); PG8_BAR; PG8_SCHED;
;             PG8_STAGE(PG8_SB(0, 1), b2 + hstep, voffB);
;             PG8_WAIT_V(6); PG8_BAR; PG8_MMA(1, 1, At, B1); PG8_BAR;
;             PG8_LDB(B0, 1, 0); PG8_SCHED; PG8_LDA(At, 1, 0); PG8_STAGE(PG8_SA(0, 1), a2 + hstep, voffA);
;             PG8_WAIT_L(8); PG8_BAR; PG8_WAIT_L(0); PG8_MMA(0, 0, At, B0); PG8_BAR; PG8_SCHED;
.LBB0_144:
	ds_read_b128 v[128:131], v145
	ds_read_b128 v[132:135], v145 offset:1024
	ds_read_b128 v[136:139], v145 offset:2048
	ds_read_b128 v[140:143], v145 offset:3072
	s_add_u32 s20, s18, 0xfff80080
	s_addc_u32 s21, s19, -1
	s_cmp_eq_u32 s59, 28
	s_cselect_b32 s23, s11, s21
	s_cselect_b32 s22, s51, s20
	s_cselect_b32 s21, s9, s58
	s_cselect_b32 s20, s56, s57
	v_lshl_add_u64 v[200:201], s[18:19], 0, v[156:157]
	s_add_i32 m0, s17, 0xc000
	ds_read_b128 v[164:167], v170
	ds_read_b128 v[172:175], v170 offset:1024
	ds_read_b128 v[176:179], v170 offset:2048
	ds_read_b128 v[180:183], v170 offset:3072
	ds_read_b128 v[184:187], v170 offset:4096
	ds_read_b128 v[188:191], v170 offset:5120
	ds_read_b128 v[192:195], v170 offset:6144
	ds_read_b128 v[196:199], v170 offset:7168
	global_load_lds_dwordx4 v[200:201], off
	v_lshl_add_u64 v[200:201], s[18:19], 0, v[158:159]
	s_add_i32 m0, s17, 0xe000
	s_nop 0
	global_load_lds_dwordx4 v[200:201], off
	s_waitcnt lgkmcnt(8)
	s_barrier
	s_waitcnt lgkmcnt(0)
	s_setprio 1
	s_waitcnt lgkmcnt(0)
	v_mfma_f32_16x16x32_bf16 v[124:127], v[128:131], v[164:167], v[124:127]
	v_mfma_f32_16x16x32_bf16 v[120:123], v[136:139], v[164:167], v[120:123]
	v_mfma_f32_16x16x32_bf16 v[116:119], v[128:131], v[176:179], v[116:119]
	v_mfma_f32_16x16x32_bf16 v[112:115], v[136:139], v[176:179], v[112:115]
	v_mfma_f32_16x16x32_bf16 v[108:111], v[128:131], v[184:187], v[108:111]
	v_mfma_f32_16x16x32_bf16 v[100:103], v[136:139], v[184:187], v[100:103]
	v_mfma_f32_16x16x32_bf16 v[92:95], v[128:131], v[192:195], v[92:95]
	v_mfma_f32_16x16x32_bf16 v[80:83], v[136:139], v[192:195], v[80:83]
	v_mfma_f32_16x16x32_bf16 v[124:127], v[132:135], v[172:175], v[124:127]
	v_mfma_f32_16x16x32_bf16 v[120:123], v[140:143], v[172:175], v[120:123]
	v_mfma_f32_16x16x32_bf16 v[116:119], v[132:135], v[180:183], v[116:119]
	v_mfma_f32_16x16x32_bf16 v[112:115], v[140:143], v[180:183], v[112:115]
	v_mfma_f32_16x16x32_bf16 v[108:111], v[132:135], v[188:191], v[108:111]
	v_mfma_f32_16x16x32_bf16 v[100:103], v[140:143], v[188:191], v[100:103]
	v_mfma_f32_16x16x32_bf16 v[92:95], v[132:135], v[196:199], v[92:95]
	v_mfma_f32_16x16x32_bf16 v[80:83], v[140:143], v[196:199], v[80:83]
	s_setprio 0
	s_barrier
	s_add_i32 s30, s48, s27
	v_lshl_add_u64 v[216:217], s[20:21], 0, v[150:151]
	s_mov_b32 m0, s30
	ds_read_b128 v[200:203], v171
	ds_read_b128 v[204:207], v171 offset:1024
	ds_read_b128 v[208:211], v171 offset:2048
	ds_read_b128 v[212:215], v171 offset:3072
	global_load_lds_dwordx4 v[216:217], off
	v_lshl_add_u64 v[218:219], s[20:21], 0, v[154:155]
	s_add_i32 m0, s30, 0x2000
	s_nop 0
	global_load_lds_dwordx4 v[218:219], off
	s_barrier
	s_waitcnt lgkmcnt(0)
	s_setprio 1
	s_waitcnt lgkmcnt(0)
	v_mfma_f32_16x16x32_bf16 v[104:107], v[200:203], v[164:167], v[104:107]
	v_mfma_f32_16x16x32_bf16 v[96:99], v[208:211], v[164:167], v[96:99]
	v_mfma_f32_16x16x32_bf16 v[88:91], v[200:203], v[176:179], v[88:91]
	v_mfma_f32_16x16x32_bf16 v[84:87], v[208:211], v[176:179], v[84:87]
	v_mfma_f32_16x16x32_bf16 v[76:79], v[200:203], v[184:187], v[76:79]
	v_mfma_f32_16x16x32_bf16 v[72:75], v[208:211], v[184:187], v[72:75]
	v_mfma_f32_16x16x32_bf16 v[68:71], v[200:203], v[192:195], v[68:71]
	v_mfma_f32_16x16x32_bf16 v[64:67], v[208:211], v[192:195], v[64:67]
	v_mfma_f32_16x16x32_bf16 v[104:107], v[204:207], v[172:175], v[104:107]
	v_mfma_f32_16x16x32_bf16 v[96:99], v[212:215], v[172:175], v[96:99]
	v_mfma_f32_16x16x32_bf16 v[88:91], v[204:207], v[180:183], v[88:91]
	v_mfma_f32_16x16x32_bf16 v[84:87], v[212:215], v[180:183], v[84:87]
	v_mfma_f32_16x16x32_bf16 v[76:79], v[204:207], v[188:191], v[76:79]
	v_mfma_f32_16x16x32_bf16 v[72:75], v[212:215], v[188:191], v[72:75]
	v_mfma_f32_16x16x32_bf16 v[68:71], v[204:207], v[196:199], v[68:71]
	v_mfma_f32_16x16x32_bf16 v[64:67], v[212:215], v[196:199], v[64:67]
	s_setprio 0
	s_mov_b32 m0, s17
	v_lshl_add_u64 v[220:221], s[22:23], 0, v[148:149]
	s_barrier
	ds_read_b128 v[164:167], v170 offset:16384
	ds_read_b128 v[172:175], v170 offset:17408
	ds_read_b128 v[176:179], v170 offset:18432
	ds_read_b128 v[180:183], v170 offset:19456
	ds_read_b128 v[184:187], v170 offset:20480
	ds_read_b128 v[188:191], v170 offset:21504
	ds_read_b128 v[192:195], v170 offset:22528
	ds_read_b128 v[196:199], v170 offset:23552
	global_load_lds_dwordx4 v[220:221], off
	v_lshl_add_u64 v[222:223], s[22:23], 0, v[152:153]
	s_mov_b32 m0, s40
	s_nop 0
	global_load_lds_dwordx4 v[222:223], off
	s_barrier
	s_waitcnt lgkmcnt(0)
	s_setprio 1
	s_waitcnt lgkmcnt(0)
	v_mfma_f32_16x16x32_bf16 v[60:63], v[128:131], v[164:167], v[60:63]
	v_mfma_f32_16x16x32_bf16 v[56:59], v[136:139], v[164:167], v[56:59]
	v_mfma_f32_16x16x32_bf16 v[48:51], v[128:131], v[176:179], v[48:51]
	v_mfma_f32_16x16x32_bf16 v[40:43], v[136:139], v[176:179], v[40:43]
	v_mfma_f32_16x16x32_bf16 v[32:35], v[128:131], v[184:187], v[32:35]
	v_mfma_f32_16x16x32_bf16 v[24:27], v[136:139], v[184:187], v[24:27]
	v_mfma_f32_16x16x32_bf16 v[16:19], v[128:131], v[192:195], v[16:19]
	v_mfma_f32_16x16x32_bf16 v[8:11], v[136:139], v[192:195], v[8:11]
	v_mfma_f32_16x16x32_bf16 v[60:63], v[132:135], v[172:175], v[60:63]
	v_mfma_f32_16x16x32_bf16 v[56:59], v[140:143], v[172:175], v[56:59]
	v_mfma_f32_16x16x32_bf16 v[48:51], v[132:135], v[180:183], v[48:51]
	v_mfma_f32_16x16x32_bf16 v[40:43], v[140:143], v[180:183], v[40:43]
	v_mfma_f32_16x16x32_bf16 v[32:35], v[132:135], v[188:191], v[32:35]
	v_mfma_f32_16x16x32_bf16 v[24:27], v[140:143], v[188:191], v[24:27]
	v_mfma_f32_16x16x32_bf16 v[16:19], v[132:135], v[196:199], v[16:19]
	v_mfma_f32_16x16x32_bf16 v[8:11], v[140:143], v[196:199], v[8:11]
	s_setprio 0
	s_barrier
; #define PG8_STAGE(bufoff, gbase, voff) do { _Pragma("unroll") for (int _i = 0; _i < 2; ++_i) \
;         __builtin_amdgcn_global_load_lds((const unsigned*)((const char*)(gbase) + (voff)[_i]), (PG8_LAS unsigned*)(lds + (bufoff) + ldsw + _i * 8192), 16, 0, 0); } while (0)
; #define PG8_LDA(dst, b, h) do { _Pragma("unroll") for (int m = 0; m < 4; ++m) _Pragma("unroll") for (int k = 0; k < 2; ++k) dst[m][k] = *(const PG8_LAS bf16x8*)(lds + PG8_SA(b, h) + aoff + m * 2048 + k * 1024); } while (0)
; #define PG8_LDB(dst, b, h) do { _Pragma("unroll") for (int n = 0; n < 2; ++n) _Pragma("unroll") for (int k = 0; k < 2; ++k) dst[n][k] = *(const PG8_LAS bf16x8*)(lds + PG8_SB(b, h) + boff + n * 2048 + k * 1024); } while (0)
; #define PG8_MMA(ai, bj, At, Bt) do { __builtin_amdgcn_s_setprio(1); _Pragma("unroll") for (int m = 0; m < 4; ++m) _Pragma("unroll") for (int n = 0; n < 2; ++n) _Pragma("unroll") for (int k = 0; k < 2; ++k) \
;         acc[ai][bj][m][n] = __builtin_amdgcn_mfma_f32_16x16x32_bf16(Bt[n][k], At[m][k], acc[ai][bj][m][n], 0, 0, 0); __builtin_amdgcn_s_setprio(0); } while (0)
; #define PG8_WAIT_V(n) asm volatile("s_waitcnt vmcnt(" #n ")" ::: "memory")
; #define PG8_WAIT_L(n) asm volatile("s_waitcnt lgkmcnt(" #n ")" ::: "memory")
; #define PG8_BAR __builtin_amdgcn_s_barrier()
; #define PG8_SCHED __builtin_amdgcn_sched_barrier(0)
; template <class Epi, class Sched>
; __device__ __forceinline__ void gemm_phase(PG8_LAS unsigned char* lds, const Gemm g, const Sched& S, const Epi& E) {
;     ...
;             PG8_STAGE(PG8_SB(0, 1), b2 + hstep, voffB);
;             PG8_WAIT_V(6); PG8_BAR; PG8_MMA(1, 1, At, B1); PG8_BAR;
;             PG8_LDB(B0, 1, 0); PG8_SCHED; PG8_LDA(At, 1, 0); PG8_STAGE(PG8_SA(0, 1), a2 + hstep, voffA);
;             PG8_WAIT_L(8); PG8_BAR; PG8_WAIT_L(0); PG8_MMA(0, 0, At, B0); PG8_BAR; PG8_SCHED;
;             PG8_LDB(B1, 1, 1); PG8_STAGE(PG8_SB(1, 0), b3, voffB);
;             PG8_BAR; PG8_WAIT_L(0); PG8_MMA(0, 1, At, B1); PG8_BAR;
;             PG8_LDA(At, 1, 1); PG8_STAGE(PG8_SA(1, 0), a3, voffA);
;             PG8_BAR; PG8_WAIT_L(0); PG8_MMA(1, 0, At, B0); PG8_BAR; PG8_SCHED;
	s_add_u32 s60, s20, 0x80000
	s_addc_u32 s61, s21, 0
	s_add_i32 s30, s49, s27
	v_lshl_add_u64 v[128:129], s[60:61], 0, v[150:151]
	s_mov_b32 m0, s30
	s_nop 0
	global_load_lds_dwordx4 v[128:129], off
	v_lshl_add_u64 v[128:129], s[60:61], 0, v[154:155]
	s_add_i32 m0, s30, 0x2000
	s_nop 0
	global_load_lds_dwordx4 v[128:129], off
	s_waitcnt vmcnt(6)
	s_barrier
	s_setprio 1
	v_mfma_f32_16x16x32_bf16 v[52:55], v[200:203], v[164:167], v[52:55]
	v_mfma_f32_16x16x32_bf16 v[44:47], v[208:211], v[164:167], v[44:47]
	v_mfma_f32_16x16x32_bf16 v[36:39], v[200:203], v[176:179], v[36:39]
	v_mfma_f32_16x16x32_bf16 v[28:31], v[208:211], v[176:179], v[28:31]
	v_mfma_f32_16x16x32_bf16 v[20:23], v[200:203], v[184:187], v[20:23]
	v_mfma_f32_16x16x32_bf16 v[12:15], v[208:211], v[184:187], v[12:15]
	v_mfma_f32_16x16x32_bf16 v[4:7], v[200:203], v[192:195], v[4:7]
	v_mfma_f32_16x16x32_bf16 v[0:3], v[208:211], v[192:195], v[0:3]
	v_mfma_f32_16x16x32_bf16 v[52:55], v[204:207], v[172:175], v[52:55]
	v_mfma_f32_16x16x32_bf16 v[44:47], v[212:215], v[172:175], v[44:47]
	v_mfma_f32_16x16x32_bf16 v[36:39], v[204:207], v[180:183], v[36:39]
	v_mfma_f32_16x16x32_bf16 v[28:31], v[212:215], v[180:183], v[28:31]
	v_mfma_f32_16x16x32_bf16 v[20:23], v[204:207], v[188:191], v[20:23]
	v_mfma_f32_16x16x32_bf16 v[12:15], v[212:215], v[188:191], v[12:15]
	v_mfma_f32_16x16x32_bf16 v[4:7], v[204:207], v[196:199], v[4:7]
	v_mfma_f32_16x16x32_bf16 v[0:3], v[212:215], v[196:199], v[0:3]
	s_setprio 0
	s_add_i32 s30, 0, 0x18000
	v_add_u32_e32 v140, s30, v147
	s_barrier
	ds_read_b128 v[128:131], v140
	ds_read_b128 v[132:135], v140 offset:1024
	ds_read_b128 v[136:139], v140 offset:2048
	ds_read_b128 v[140:143], v140 offset:3072
	s_add_u32 s22, s22, 0x80000
	s_addc_u32 s23, s23, 0
	s_mov_b32 m0, s41
	v_lshl_add_u64 v[200:201], s[22:23], 0, v[148:149]
	ds_read_b128 v[164:167], v170 offset:32768
	ds_read_b128 v[172:175], v170 offset:33792
	ds_read_b128 v[176:179], v170 offset:34816
	ds_read_b128 v[180:183], v170 offset:35840
	ds_read_b128 v[184:187], v170 offset:36864
	ds_read_b128 v[188:191], v170 offset:37888
	ds_read_b128 v[192:195], v170 offset:38912
	ds_read_b128 v[196:199], v170 offset:39936
	global_load_lds_dwordx4 v[200:201], off
	v_lshl_add_u64 v[200:201], s[22:23], 0, v[152:153]
	s_mov_b32 m0, s42
	s_nop 0
	global_load_lds_dwordx4 v[200:201], off
	s_waitcnt lgkmcnt(8)
	s_barrier
	s_waitcnt lgkmcnt(0)
	s_setprio 1
	s_waitcnt lgkmcnt(0)
	v_mfma_f32_16x16x32_bf16 v[124:127], v[128:131], v[164:167], v[124:127]
	v_mfma_f32_16x16x32_bf16 v[120:123], v[136:139], v[164:167], v[120:123]
	v_mfma_f32_16x16x32_bf16 v[116:119], v[128:131], v[176:179], v[116:119]
	v_mfma_f32_16x16x32_bf16 v[112:115], v[136:139], v[176:179], v[112:115]
	v_mfma_f32_16x16x32_bf16 v[108:111], v[128:131], v[184:187], v[108:111]
	v_mfma_f32_16x16x32_bf16 v[100:103], v[136:139], v[184:187], v[100:103]
	v_mfma_f32_16x16x32_bf16 v[92:95], v[128:131], v[192:195], v[92:95]
	v_mfma_f32_16x16x32_bf16 v[80:83], v[136:139], v[192:195], v[80:83]
	v_mfma_f32_16x16x32_bf16 v[124:127], v[132:135], v[172:175], v[124:127]
	v_mfma_f32_16x16x32_bf16 v[120:123], v[140:143], v[172:175], v[120:123]
	v_mfma_f32_16x16x32_bf16 v[116:119], v[132:135], v[180:183], v[116:119]
	v_mfma_f32_16x16x32_bf16 v[112:115], v[140:143], v[180:183], v[112:115]
	v_mfma_f32_16x16x32_bf16 v[108:111], v[132:135], v[188:191], v[108:111]
	v_mfma_f32_16x16x32_bf16 v[100:103], v[140:143], v[188:191], v[100:103]
	v_mfma_f32_16x16x32_bf16 v[92:95], v[132:135], v[196:199], v[92:95]
	v_mfma_f32_16x16x32_bf16 v[80:83], v[140:143], v[196:199], v[80:83]
	s_setprio 0
	s_barrier
	s_add_i32 s22, 0, 0x1c000
	s_add_i32 s23, s30, s27
	v_add_u32_e32 v212, s22, v147
	v_lshl_add_u64 v[216:217], v[216:217], 0, s[6:7]
	s_mov_b32 m0, s23
	ds_read_b128 v[200:203], v212
	ds_read_b128 v[204:207], v212 offset:1024
	ds_read_b128 v[208:211], v212 offset:2048
	ds_read_b128 v[212:215], v212 offset:3072
	global_load_lds_dwordx4 v[216:217], off
	v_lshl_add_u64 v[216:217], v[218:219], 0, s[6:7]
	s_add_i32 m0, s23, 0x2000
	s_nop 0
	global_load_lds_dwordx4 v[216:217], off
	s_barrier
	s_waitcnt lgkmcnt(0)
	s_setprio 1
	s_waitcnt lgkmcnt(0)
	v_mfma_f32_16x16x32_bf16 v[104:107], v[200:203], v[164:167], v[104:107]
	v_mfma_f32_16x16x32_bf16 v[96:99], v[208:211], v[164:167], v[96:99]
	v_mfma_f32_16x16x32_bf16 v[88:91], v[200:203], v[176:179], v[88:91]
	v_mfma_f32_16x16x32_bf16 v[84:87], v[208:211], v[176:179], v[84:87]
	v_mfma_f32_16x16x32_bf16 v[76:79], v[200:203], v[184:187], v[76:79]
	v_mfma_f32_16x16x32_bf16 v[72:75], v[208:211], v[184:187], v[72:75]
	v_mfma_f32_16x16x32_bf16 v[68:71], v[200:203], v[192:195], v[68:71]
	v_mfma_f32_16x16x32_bf16 v[64:67], v[208:211], v[192:195], v[64:67]
	v_mfma_f32_16x16x32_bf16 v[104:107], v[204:207], v[172:175], v[104:107]
	v_mfma_f32_16x16x32_bf16 v[96:99], v[212:215], v[172:175], v[96:99]
	v_mfma_f32_16x16x32_bf16 v[88:91], v[204:207], v[180:183], v[88:91]
	v_mfma_f32_16x16x32_bf16 v[84:87], v[212:215], v[180:183], v[84:87]
	v_mfma_f32_16x16x32_bf16 v[76:79], v[204:207], v[188:191], v[76:79]
	v_mfma_f32_16x16x32_bf16 v[72:75], v[212:215], v[188:191], v[72:75]
	v_mfma_f32_16x16x32_bf16 v[68:71], v[204:207], v[196:199], v[68:71]
	v_mfma_f32_16x16x32_bf16 v[64:67], v[212:215], v[196:199], v[64:67]
	s_setprio 0
	s_mov_b32 m0, s44
	v_lshl_add_u64 v[216:217], v[220:221], 0, s[6:7]
	s_barrier
	ds_read_b128 v[164:167], v170 offset:49152
	ds_read_b128 v[172:175], v170 offset:50176
	ds_read_b128 v[176:179], v170 offset:51200
	ds_read_b128 v[180:183], v170 offset:52224
	ds_read_b128 v[184:187], v170 offset:53248
	ds_read_b128 v[188:191], v170 offset:54272
	ds_read_b128 v[192:195], v170 offset:55296
	ds_read_b128 v[196:199], v170 offset:56320
	global_load_lds_dwordx4 v[216:217], off
	v_lshl_add_u64 v[216:217], v[222:223], 0, s[6:7]
	s_mov_b32 m0, s45
	s_nop 0
	global_load_lds_dwordx4 v[216:217], off
	s_barrier
; #define PG8_STAGE(bufoff, gbase, voff) do { _Pragma("unroll") for (int _i = 0; _i < 2; ++_i) \
;         __builtin_amdgcn_global_load_lds((const unsigned*)((const char*)(gbase) + (voff)[_i]), (PG8_LAS unsigned*)(lds + (bufoff) + ldsw + _i * 8192), 16, 0, 0); } while (0)
; #define PG8_MMA(ai, bj, At, Bt) do { __builtin_amdgcn_s_setprio(1); _Pragma("unroll") for (int m = 0; m < 4; ++m) _Pragma("unroll") for (int n = 0; n < 2; ++n) _Pragma("unroll") for (int k = 0; k < 2; ++k) \
;         acc[ai][bj][m][n] = __builtin_amdgcn_mfma_f32_16x16x32_bf16(Bt[n][k], At[m][k], acc[ai][bj][m][n], 0, 0, 0); __builtin_amdgcn_s_setprio(0); } while (0)
; #define PG8_WAIT_V(n) asm volatile("s_waitcnt vmcnt(" #n ")" ::: "memory")
; #define PG8_WAIT_L(n) asm volatile("s_waitcnt lgkmcnt(" #n ")" ::: "memory")
; #define PG8_BAR __builtin_amdgcn_s_barrier()
; #define PG8_SCHED __builtin_amdgcn_sched_barrier(0)
; __device__ __forceinline__ uint4 pk8(f32x4 a, f32x4 b) { return make_uint4(cvt_pk_bf16(a[0], a[1]), cvt_pk_bf16(a[2], a[3]), cvt_pk_bf16(b[0], b[1]), cvt_pk_bf16(b[2], b[3])); }
; template <class Epi, class Sched>
; __device__ __forceinline__ void gemm_phase(PG8_LAS unsigned char* lds, const Gemm g, const Sched& S, const Epi& E) {
;     ...
;             PG8_BAR; PG8_WAIT_L(0); PG8_MMA(1, 0, At, B0); PG8_BAR; PG8_SCHED;
;             PG8_STAGE(PG8_SB(1, 1), b3 + hstep, voffB);
;             PG8_WAIT_V(6); PG8_BAR; PG8_MMA(1, 1, At, B1); PG8_BAR;
;     __device__ __forceinline__ void operator()(AccRef acc, const Unit& u, int wr, int wc, int fr, int fq) const {
;         const int c0 = u.pn * 256 + wc * 32 + 8 * fq;
;         f32x4 sc[2][2];
; #pragma unroll
;         for (int bj = 0; bj < 2; ++bj)
; #pragma unroll
;             for (int n = 0; n < 2; ++n) sc[bj][n] = *(const f32x4*)(rinv + c0 + bj * 128 + n * 4);
; #pragma unroll
;         for (int ai = 0; ai < 2; ++ai)
; #pragma unroll
;             for (int m = 0; m < 4; ++m) {
;                 const int r = u.pm * 256 + ai * 128 + wr * 64 + m * 16 + fr;
;                 bf16_t* rowp = O + (size_t)r * T + c0;
; #pragma unroll
;                 for (int bj = 0; bj < 2; ++bj) *(uint4*)(rowp + bj * 128) = pk8(acc[ai][bj][m][0] * sc[bj][0], acc[ai][bj][m][1] * sc[bj][1]);
;             }
	s_waitcnt lgkmcnt(0)
	s_setprio 1
	s_waitcnt lgkmcnt(0)
	v_mfma_f32_16x16x32_bf16 v[60:63], v[128:131], v[164:167], v[60:63]
	v_mfma_f32_16x16x32_bf16 v[56:59], v[136:139], v[164:167], v[56:59]
	v_mfma_f32_16x16x32_bf16 v[48:51], v[128:131], v[176:179], v[48:51]
	v_mfma_f32_16x16x32_bf16 v[40:43], v[136:139], v[176:179], v[40:43]
	v_mfma_f32_16x16x32_bf16 v[32:35], v[128:131], v[184:187], v[32:35]
	v_mfma_f32_16x16x32_bf16 v[24:27], v[136:139], v[184:187], v[24:27]
	v_mfma_f32_16x16x32_bf16 v[16:19], v[128:131], v[192:195], v[16:19]
	v_mfma_f32_16x16x32_bf16 v[8:11], v[136:139], v[192:195], v[8:11]
	v_mfma_f32_16x16x32_bf16 v[60:63], v[132:135], v[172:175], v[60:63]
	v_mfma_f32_16x16x32_bf16 v[56:59], v[140:143], v[172:175], v[56:59]
	v_mfma_f32_16x16x32_bf16 v[48:51], v[132:135], v[180:183], v[48:51]
	v_mfma_f32_16x16x32_bf16 v[40:43], v[140:143], v[180:183], v[40:43]
	v_mfma_f32_16x16x32_bf16 v[32:35], v[132:135], v[188:191], v[32:35]
	v_mfma_f32_16x16x32_bf16 v[24:27], v[140:143], v[188:191], v[24:27]
	v_mfma_f32_16x16x32_bf16 v[16:19], v[132:135], v[196:199], v[16:19]
	v_mfma_f32_16x16x32_bf16 v[8:11], v[140:143], v[196:199], v[8:11]
	s_setprio 0
	s_barrier
	s_add_u32 s20, s20, 0x80080
	s_addc_u32 s21, s21, 0
	s_add_i32 s22, s22, s27
	v_lshl_add_u64 v[128:129], s[20:21], 0, v[150:151]
	s_mov_b32 m0, s22
	s_nop 0
	global_load_lds_dwordx4 v[128:129], off
	v_lshl_add_u64 v[128:129], s[20:21], 0, v[154:155]
	s_add_i32 m0, s22, 0x2000
	s_nop 0
	global_load_lds_dwordx4 v[128:129], off
	s_waitcnt vmcnt(6)
	s_barrier
	s_setprio 1
	v_mfma_f32_16x16x32_bf16 v[52:55], v[200:203], v[164:167], v[52:55]
	v_mfma_f32_16x16x32_bf16 v[44:47], v[208:211], v[164:167], v[44:47]
	v_mfma_f32_16x16x32_bf16 v[36:39], v[200:203], v[176:179], v[36:39]
	v_mfma_f32_16x16x32_bf16 v[28:31], v[208:211], v[176:179], v[28:31]
	v_mfma_f32_16x16x32_bf16 v[20:23], v[200:203], v[184:187], v[20:23]
	v_mfma_f32_16x16x32_bf16 v[12:15], v[208:211], v[184:187], v[12:15]
	v_mfma_f32_16x16x32_bf16 v[4:7], v[200:203], v[192:195], v[4:7]
	v_mfma_f32_16x16x32_bf16 v[0:3], v[208:211], v[192:195], v[0:3]
	v_mfma_f32_16x16x32_bf16 v[52:55], v[204:207], v[172:175], v[52:55]
	v_mfma_f32_16x16x32_bf16 v[44:47], v[212:215], v[172:175], v[44:47]
	v_mfma_f32_16x16x32_bf16 v[36:39], v[204:207], v[180:183], v[36:39]
	v_mfma_f32_16x16x32_bf16 v[28:31], v[212:215], v[180:183], v[28:31]
	v_mfma_f32_16x16x32_bf16 v[20:23], v[204:207], v[188:191], v[20:23]
	v_mfma_f32_16x16x32_bf16 v[12:15], v[212:215], v[188:191], v[12:15]
	v_mfma_f32_16x16x32_bf16 v[4:7], v[204:207], v[196:199], v[4:7]
	v_mfma_f32_16x16x32_bf16 v[0:3], v[212:215], v[196:199], v[0:3]
	s_setprio 0
	s_add_i32 s59, s59, 2
	s_add_u32 s18, s18, 0x100
	s_addc_u32 s19, s19, 0
	s_add_u32 s57, s57, 0x100
	s_addc_u32 s58, s58, 0
	s_cmp_gt_u32 s59, 29
	s_barrier
	s_cbranch_scc0 .LBB0_144
	v_lshl_or_b32 v166, s50, 8, v169
	v_ashrrev_i32_e32 v167, 31, v166
	v_lshl_add_u64 v[128:129], v[166:167], 2, s[28:29]
	global_load_dwordx4 v[140:143], v[128:129], off
	global_load_dwordx4 v[136:139], v[128:129], off offset:16
	global_load_dwordx4 v[132:135], v[128:129], off offset:512
	s_nop 0
	global_load_dwordx4 v[128:131], v[128:129], off offset:528
	v_lshl_add_u32 v164, s16, 8, v168
	v_ashrrev_i32_e32 v165, 31, v164
	v_or_b32_e32 v172, 16, v164
	v_lshlrev_b64 v[240:241], 12, v[164:165]
	v_lshlrev_b64 v[242:243], 8, v[164:165]
	v_lshl_add_u64 v[240:241], v[240:241], 0, v[242:243]
	v_lshlrev_b64 v[178:179], 16, v[164:165]
	v_lshl_add_u64 v[178:179], v[178:179], 0, v[240:241]
	v_lshlrev_b64 v[166:167], 1, v[166:167]
	v_ashrrev_i32_e32 v173, 31, v172
	v_lshl_add_u64 v[178:179], s[0:1], 0, v[178:179]
	v_or_b32_e32 v174, 32, v164
	v_lshlrev_b64 v[240:241], 12, v[172:173]
	v_lshlrev_b64 v[242:243], 8, v[172:173]
	v_lshl_add_u64 v[240:241], v[240:241], 0, v[242:243]
	v_lshlrev_b64 v[172:173], 16, v[172:173]
	v_lshl_add_u64 v[172:173], v[172:173], 0, v[240:241]
	v_lshl_add_u64 v[178:179], v[178:179], 0, v[166:167]
	v_ashrrev_i32_e32 v175, 31, v174
	v_lshl_add_u64 v[172:173], s[0:1], 0, v[172:173]
	v_or_b32_e32 v176, 48, v164
	v_lshlrev_b64 v[240:241], 12, v[174:175]
	v_lshlrev_b64 v[242:243], 8, v[174:175]
	v_lshl_add_u64 v[240:241], v[240:241], 0, v[242:243]
	v_lshlrev_b64 v[174:175], 16, v[174:175]
	v_lshl_add_u64 v[174:175], v[174:175], 0, v[240:241]
	v_lshl_add_u64 v[172:173], v[172:173], 0, v[166:167]
	v_ashrrev_i32_e32 v177, 31, v176
	v_lshl_add_u64 v[174:175], s[0:1], 0, v[174:175]
	v_lshlrev_b64 v[240:241], 12, v[176:177]
	v_lshlrev_b64 v[242:243], 8, v[176:177]
	v_lshl_add_u64 v[240:241], v[240:241], 0, v[242:243]
	v_lshlrev_b64 v[176:177], 16, v[176:177]
	v_lshl_add_u64 v[176:177], v[176:177], 0, v[240:241]
	v_lshl_add_u64 v[174:175], v[174:175], 0, v[166:167]
	v_lshl_add_u64 v[176:177], s[0:1], 0, v[176:177]
	v_lshl_add_u64 v[176:177], v[176:177], 0, v[166:167]
	s_and_b64 vcc, exec, s[4:5]
	s_mov_b32 s50, s8
	s_mov_b32 s16, s10
	s_mov_b64 s[20:21], s[14:15]
	s_mov_b64 s[18:19], s[12:13]
	s_waitcnt vmcnt(0)
; __device__ __forceinline__ uint4 pk8(f32x4 a, f32x4 b) { return make_uint4(cvt_pk_bf16(a[0], a[1]), cvt_pk_bf16(a[2], a[3]), cvt_pk_bf16(b[0], b[1]), cvt_pk_bf16(b[2], b[3])); }
;     __device__ __forceinline__ void operator()(AccRef acc, const Unit& u, int wr, int wc, int fr, int fq) const {
;     ...
; #pragma unroll
;         for (int ai = 0; ai < 2; ++ai)
; #pragma unroll
;             for (int m = 0; m < 4; ++m) {
;                 const int r = u.pm * 256 + ai * 128 + wr * 64 + m * 16 + fr;
;                 bf16_t* rowp = O + (size_t)r * T + c0;
; #pragma unroll
;                 for (int bj = 0; bj < 2; ++bj) *(uint4*)(rowp + bj * 128) = pk8(acc[ai][bj][m][0] * sc[bj][0], acc[ai][bj][m][1] * sc[bj][1]);
;             }
	v_pk_mul_f32 v[126:127], v[126:127], v[142:143]
	v_pk_mul_f32 v[124:125], v[124:125], v[140:141]
	v_pk_mul_f32 v[182:183], v[70:71], v[134:135]
	v_cvt_pk_bf16_f32 v70, v124, v125
	v_cvt_pk_bf16_f32 v71, v126, v127
	v_pk_mul_f32 v[122:123], v[122:123], v[138:139]
	v_pk_mul_f32 v[120:121], v[120:121], v[136:137]
	v_pk_mul_f32 v[106:107], v[106:107], v[134:135]
	v_pk_mul_f32 v[104:105], v[104:105], v[132:133]
	v_pk_mul_f32 v[180:181], v[72:73], v[128:129]
	v_cvt_pk_bf16_f32 v72, v120, v121
	v_cvt_pk_bf16_f32 v73, v122, v123
	global_store_dwordx4 v[178:179], v[70:73], off
	v_pk_mul_f32 v[98:99], v[98:99], v[130:131]
	v_pk_mul_f32 v[96:97], v[96:97], v[128:129]
	v_cvt_pk_bf16_f32 v70, v104, v105
	v_cvt_pk_bf16_f32 v71, v106, v107
	v_pk_mul_f32 v[118:119], v[118:119], v[142:143]
	v_pk_mul_f32 v[116:117], v[116:117], v[140:141]
	v_cvt_pk_bf16_f32 v72, v96, v97
	v_cvt_pk_bf16_f32 v73, v98, v99
	global_store_dwordx4 v[178:179], v[70:73], off offset:256
	v_pk_mul_f32 v[114:115], v[114:115], v[138:139]
	v_pk_mul_f32 v[112:113], v[112:113], v[136:137]
	v_cvt_pk_bf16_f32 v70, v116, v117
	v_cvt_pk_bf16_f32 v71, v118, v119
	v_pk_mul_f32 v[90:91], v[90:91], v[134:135]
	v_pk_mul_f32 v[88:89], v[88:89], v[132:133]
	v_cvt_pk_bf16_f32 v72, v112, v113
	v_cvt_pk_bf16_f32 v73, v114, v115
	global_store_dwordx4 v[172:173], v[70:73], off
	v_pk_mul_f32 v[86:87], v[86:87], v[130:131]
	v_pk_mul_f32 v[84:85], v[84:85], v[128:129]
	v_cvt_pk_bf16_f32 v70, v88, v89
	v_cvt_pk_bf16_f32 v71, v90, v91
	v_pk_mul_f32 v[110:111], v[110:111], v[142:143]
	v_pk_mul_f32 v[108:109], v[108:109], v[140:141]
	v_cvt_pk_bf16_f32 v72, v84, v85
	v_cvt_pk_bf16_f32 v73, v86, v87
	global_store_dwordx4 v[172:173], v[70:73], off offset:256
	v_pk_mul_f32 v[102:103], v[102:103], v[138:139]
	v_pk_mul_f32 v[100:101], v[100:101], v[136:137]
	v_cvt_pk_bf16_f32 v70, v108, v109
	v_cvt_pk_bf16_f32 v71, v110, v111
	v_pk_mul_f32 v[78:79], v[78:79], v[134:135]
	v_pk_mul_f32 v[76:77], v[76:77], v[132:133]
	v_cvt_pk_bf16_f32 v72, v100, v101
	v_cvt_pk_bf16_f32 v73, v102, v103
	global_store_dwordx4 v[174:175], v[70:73], off
	v_pk_mul_f32 v[74:75], v[74:75], v[130:131]
	v_pk_mul_f32 v[94:95], v[94:95], v[142:143]
	v_cvt_pk_bf16_f32 v70, v76, v77
	v_cvt_pk_bf16_f32 v71, v78, v79
	v_pk_mul_f32 v[92:93], v[92:93], v[140:141]
	v_cvt_pk_bf16_f32 v72, v180, v181
	v_cvt_pk_bf16_f32 v73, v74, v75
	global_store_dwordx4 v[174:175], v[70:73], off offset:256
	v_pk_mul_f32 v[82:83], v[82:83], v[138:139]
	v_pk_mul_f32 v[80:81], v[80:81], v[136:137]
	v_cvt_pk_bf16_f32 v70, v92, v93
	v_cvt_pk_bf16_f32 v71, v94, v95
	v_pk_mul_f32 v[68:69], v[68:69], v[132:133]
	v_cvt_pk_bf16_f32 v72, v80, v81
	v_cvt_pk_bf16_f32 v73, v82, v83
	global_store_dwordx4 v[176:177], v[70:73], off
	v_pk_mul_f32 v[62:63], v[62:63], v[142:143]
	v_pk_mul_f32 v[60:61], v[60:61], v[140:141]
	v_pk_mul_f32 v[70:71], v[66:67], v[130:131]
	v_pk_mul_f32 v[66:67], v[64:65], v[128:129]
	v_cvt_pk_bf16_f32 v64, v68, v69
	v_cvt_pk_bf16_f32 v65, v182, v183
	v_pk_mul_f32 v[52:53], v[52:53], v[132:133]
	v_cvt_pk_bf16_f32 v66, v66, v67
	v_cvt_pk_bf16_f32 v67, v70, v71
	global_store_dwordx4 v[176:177], v[64:67], off offset:256
	v_pk_mul_f32 v[54:55], v[54:55], v[134:135]
	v_pk_mul_f32 v[48:49], v[48:49], v[140:141]
	v_add_u32_e32 v64, 0x80, v164
	v_ashrrev_i32_e32 v65, 31, v64
	v_lshlrev_b64 v[240:241], 12, v[64:65]
	v_lshlrev_b64 v[242:243], 8, v[64:65]
	v_lshl_add_u64 v[240:241], v[240:241], 0, v[242:243]
	v_lshlrev_b64 v[64:65], 16, v[64:65]
	v_lshl_add_u64 v[64:65], v[64:65], 0, v[240:241]
	v_lshl_add_u64 v[64:65], s[0:1], 0, v[64:65]
	v_lshl_add_u64 v[64:65], v[64:65], 0, v[166:167]
	v_pk_mul_f32 v[66:67], v[58:59], v[138:139]
	v_pk_mul_f32 v[58:59], v[56:57], v[136:137]
	v_cvt_pk_bf16_f32 v56, v60, v61
	v_cvt_pk_bf16_f32 v57, v62, v63
	v_pk_mul_f32 v[36:37], v[36:37], v[132:133]
; #define PG8_WAIT_V(n) asm volatile("s_waitcnt vmcnt(" #n ")" ::: "memory")
; #define PG8_BAR __builtin_amdgcn_s_barrier()
; __device__ __forceinline__ uint4 pk8(f32x4 a, f32x4 b) { return make_uint4(cvt_pk_bf16(a[0], a[1]), cvt_pk_bf16(a[2], a[3]), cvt_pk_bf16(b[0], b[1]), cvt_pk_bf16(b[2], b[3])); }
; template <class Epi, class Sched>
; __device__ __forceinline__ void gemm_phase(PG8_LAS unsigned char* lds, const Gemm g, const Sched& S, const Epi& E) {
;     ...
;     PG8_WAIT_V(0);
;     if (wr == 0) PG8_BAR;
;     PG8_BAR;
;     __device__ __forceinline__ void operator()(AccRef acc, const Unit& u, int wr, int wc, int fr, int fq) const {
;     ...
; #pragma unroll
;         for (int ai = 0; ai < 2; ++ai)
; #pragma unroll
;             for (int m = 0; m < 4; ++m) {
;                 const int r = u.pm * 256 + ai * 128 + wr * 64 + m * 16 + fr;
;                 bf16_t* rowp = O + (size_t)r * T + c0;
; #pragma unroll
;                 for (int bj = 0; bj < 2; ++bj) *(uint4*)(rowp + bj * 128) = pk8(acc[ai][bj][m][0] * sc[bj][0], acc[ai][bj][m][1] * sc[bj][1]);
;             }
	v_cvt_pk_bf16_f32 v58, v58, v59
	v_cvt_pk_bf16_f32 v59, v66, v67
	global_store_dwordx4 v[64:65], v[56:59], off
	v_pk_mul_f32 v[38:39], v[38:39], v[134:135]
	v_pk_mul_f32 v[32:33], v[32:33], v[140:141]
	v_pk_mul_f32 v[56:57], v[46:47], v[130:131]
	v_pk_mul_f32 v[46:47], v[44:45], v[128:129]
	v_cvt_pk_bf16_f32 v44, v52, v53
	v_cvt_pk_bf16_f32 v45, v54, v55
	v_pk_mul_f32 v[20:21], v[20:21], v[132:133]
	v_cvt_pk_bf16_f32 v46, v46, v47
	v_cvt_pk_bf16_f32 v47, v56, v57
	global_store_dwordx4 v[64:65], v[44:47], off offset:256
	v_pk_mul_f32 v[22:23], v[22:23], v[134:135]
	v_pk_mul_f32 v[16:17], v[16:17], v[140:141]
	v_add_u32_e32 v44, 0x90, v164
	v_ashrrev_i32_e32 v45, 31, v44
	v_lshlrev_b64 v[240:241], 12, v[44:45]
	v_lshlrev_b64 v[242:243], 8, v[44:45]
	v_lshl_add_u64 v[240:241], v[240:241], 0, v[242:243]
	v_lshlrev_b64 v[44:45], 16, v[44:45]
	v_lshl_add_u64 v[44:45], v[44:45], 0, v[240:241]
	v_lshl_add_u64 v[44:45], s[0:1], 0, v[44:45]
	v_lshl_add_u64 v[44:45], v[44:45], 0, v[166:167]
	v_pk_mul_f32 v[46:47], v[50:51], v[142:143]
	v_pk_mul_f32 v[50:51], v[42:43], v[138:139]
	v_pk_mul_f32 v[42:43], v[40:41], v[136:137]
	v_cvt_pk_bf16_f32 v40, v48, v49
	v_cvt_pk_bf16_f32 v41, v46, v47
	v_pk_mul_f32 v[6:7], v[6:7], v[134:135]
	v_cvt_pk_bf16_f32 v42, v42, v43
	v_cvt_pk_bf16_f32 v43, v50, v51
	global_store_dwordx4 v[44:45], v[40:43], off
	v_pk_mul_f32 v[4:5], v[4:5], v[132:133]
	s_nop 0
	v_pk_mul_f32 v[40:41], v[30:31], v[130:131]
	v_pk_mul_f32 v[30:31], v[28:29], v[128:129]
	v_cvt_pk_bf16_f32 v28, v36, v37
	v_cvt_pk_bf16_f32 v29, v38, v39
	s_nop 0
	v_cvt_pk_bf16_f32 v30, v30, v31
	v_cvt_pk_bf16_f32 v31, v40, v41
	global_store_dwordx4 v[44:45], v[28:31], off offset:256
	s_nop 1
	v_add_u32_e32 v28, 0xa0, v164
	v_ashrrev_i32_e32 v29, 31, v28
	v_lshlrev_b64 v[240:241], 12, v[28:29]
	v_lshlrev_b64 v[242:243], 8, v[28:29]
	v_lshl_add_u64 v[240:241], v[240:241], 0, v[242:243]
	v_lshlrev_b64 v[28:29], 16, v[28:29]
	v_lshl_add_u64 v[28:29], v[28:29], 0, v[240:241]
	v_lshl_add_u64 v[28:29], s[0:1], 0, v[28:29]
	v_lshl_add_u64 v[28:29], v[28:29], 0, v[166:167]
	v_pk_mul_f32 v[30:31], v[34:35], v[142:143]
	v_pk_mul_f32 v[34:35], v[26:27], v[138:139]
	v_pk_mul_f32 v[26:27], v[24:25], v[136:137]
	v_cvt_pk_bf16_f32 v24, v32, v33
	v_cvt_pk_bf16_f32 v25, v30, v31
	s_nop 0
	v_cvt_pk_bf16_f32 v26, v26, v27
	v_cvt_pk_bf16_f32 v27, v34, v35
	global_store_dwordx4 v[28:29], v[24:27], off
	s_nop 1
	v_pk_mul_f32 v[24:25], v[14:15], v[130:131]
	v_pk_mul_f32 v[14:15], v[12:13], v[128:129]
	v_cvt_pk_bf16_f32 v12, v20, v21
	v_cvt_pk_bf16_f32 v13, v22, v23
	s_nop 0
	v_cvt_pk_bf16_f32 v14, v14, v15
	v_cvt_pk_bf16_f32 v15, v24, v25
	global_store_dwordx4 v[28:29], v[12:15], off offset:256
	s_nop 1
	v_add_u32_e32 v12, 0xb0, v164
	v_ashrrev_i32_e32 v13, 31, v12
	v_lshlrev_b64 v[240:241], 12, v[12:13]
	v_lshlrev_b64 v[242:243], 8, v[12:13]
	v_lshl_add_u64 v[240:241], v[240:241], 0, v[242:243]
	v_lshlrev_b64 v[12:13], 16, v[12:13]
	v_lshl_add_u64 v[12:13], v[12:13], 0, v[240:241]
	v_lshl_add_u64 v[12:13], s[0:1], 0, v[12:13]
	v_lshl_add_u64 v[12:13], v[12:13], 0, v[166:167]
	v_pk_mul_f32 v[14:15], v[18:19], v[142:143]
	v_pk_mul_f32 v[18:19], v[10:11], v[138:139]
	v_pk_mul_f32 v[10:11], v[8:9], v[136:137]
	v_cvt_pk_bf16_f32 v8, v16, v17
	v_cvt_pk_bf16_f32 v9, v14, v15
	s_nop 0
	v_cvt_pk_bf16_f32 v10, v10, v11
	v_cvt_pk_bf16_f32 v11, v18, v19
	global_store_dwordx4 v[12:13], v[8:11], off
	s_nop 1
	v_pk_mul_f32 v[8:9], v[2:3], v[130:131]
	v_pk_mul_f32 v[2:3], v[0:1], v[128:129]
	v_cvt_pk_bf16_f32 v0, v4, v5
	v_cvt_pk_bf16_f32 v1, v6, v7
	s_nop 0
	v_cvt_pk_bf16_f32 v2, v2, v3
	v_cvt_pk_bf16_f32 v3, v8, v9
	global_store_dwordx4 v[12:13], v[0:3], off offset:256
	s_cbranch_vccz .LBB0_137
	s_waitcnt vmcnt(0)
	s_cmpk_gt_u32 s3, 0xff
	s_cbranch_scc1 .LBB0_148
	s_barrier

; __device__ void phase_na(const Params& P, unsigned char* smem) {
;     ...
;     const bf16_t* Kp = (const bf16_t*)P.out;
;     const bf16_t* Vt = (const bf16_t*)((const unsigned char*)P.out + 128 * MiB);
;     const int h = blockIdx.x & 7, nbh = ((int)gridDim.x - h + 7) >> 3;
;     const float scale = 0.08838834764831845f;
;     for (int uu = ((int)blockIdx.x >> 3) * 8 + wid; uu < 2048; uu += nbh * 8) {
;         const int grow = uu >> 2, j = uu & 3;
;         int rows, r, tokbase;
;         if (grow < 256) { rows = 256; r = grow; tokbase = 0; } else { const int s = (grow - 256) >> 6; r = (grow - 256) & 63; rows = 64; tokbase = TP + s * 4096; }
;         const int rs = min(max(r - 4, 0), rows - 8);
;         const int q0 = j * 16, k0 = min(max(q0 - 8, 0), 32);
;         const size_t qtok = (size_t)tokbase + r * 64 + q0 + l15;
;         const bf16_t* qptr = Qp + qtok * 1024 + h * 128 + l4 * 8;
;     ...
;             const bf16_t* vbase = Vt + (size_t)(h * 128 + l15) * T + tokbase + (rs + i) * 64 + k0 + l4 * 8;
; #pragma unroll
;             for (int dt = 0; dt < 8; ++dt) {
;                 const bf16_t* vp = vbase + (size_t)dt * 16 * T;
.LBB0_207:
	s_or_b64 exec, exec, s[0:1]
	s_and_b32 s0, s2, -8
	v_bfe_u32 v65, v144, 4, 2
	v_add_u32_e32 v84, s0, v146
	s_and_b32 s3, s2, 7
	v_lshlrev_b32_e32 v68, 3, v65
	s_movk_i32 s0, 0x800
	v_and_b32_e32 v64, 15, v144
	s_lshl_b32 s24, s3, 7
	v_lshlrev_b32_e32 v69, 2, v65
	v_cmp_gt_i32_e32 vcc, s0, v84
	v_lshlrev_b32_e32 v66, 1, v68
	s_waitcnt lgkmcnt(0)
	s_barrier
	s_and_saveexec_b64 s[4:5], vcc
	s_cbranch_execz .LBB0_338
	s_xor_b32 s8, s3, 7
	s_lshl_b32 s9, s24, 1
	v_lshlrev_b32_e32 v0, 1, v144
	s_add_u32 s0, s88, s9
	v_mov_b32_e32 v71, 0
	s_addc_u32 s1, s89, 0
	v_or_b32_sdwa v70, s24, v64 dst_sel:WORD_1 dst_unused:UNUSED_PAD src0_sel:DWORD src1_sel:DWORD
	v_mov_b32_e32 v67, v71
	v_and_b32_e32 v0, 24, v0
	v_and_or_b32 v85, v144, 3, v0
	v_lshl_add_u64 v[74:75], s[0:1], 0, v[66:67]
	v_lshl_add_u64 v[0:1], s[88:89], 0, v[70:71]
	s_mov_b64 s[0:1], 0x8000000
	v_lshl_add_u64 v[76:77], v[0:1], 0, s[0:1]
	v_lshrrev_b32_e32 v0, 4, v70
	v_mov_b32_e32 v1, 0
	v_lshl_add_u64 v[76:77], v[76:77], 0, v[0:1]
	v_lshrrev_b32_e32 v0, 8, v70
	v_lshl_add_u64 v[76:77], v[76:77], 0, v[0:1]
	v_mbcnt_lo_u32_b32 v0, -1, 0
	v_mbcnt_hi_u32_b32 v0, -1, v0
	v_and_b32_e32 v2, 64, v0
	s_add_u32 s6, s40, s9
	v_xor_b32_e32 v1, 16, v0
	v_add_u32_e32 v2, 64, v2
	s_addc_u32 s7, s41, 0
	s_add_i32 s10, s94, s8
	v_cmp_lt_i32_e32 vcc, v1, v2
	s_add_u32 s8, s36, s9
	s_addc_u32 s9, s37, 0
	v_cndmask_b32_e32 v1, v0, v1, vcc
	v_lshlrev_b32_e32 v86, 2, v1
	v_xor_b32_e32 v1, 32, v0
	s_lshl_b32 s0, s2, 4
	v_cmp_lt_i32_e32 vcc, v1, v2
	s_and_b32 s0, s0, 0xffffff80
	s_mul_i32 s25, s3, 15
	v_lshlrev_b32_e32 v70, 1, v69
	v_cndmask_b32_e32 v0, v0, v1, vcc
	v_lshl_add_u32 v88, v146, 4, s0
	s_lshl_b32 s0, s10, 4
	v_lshl_add_u64 v[72:73], s[8:9], 0, v[66:67]
	s_add_i32 s25, s25, 7
	s_and_b32 s26, s10, -8
	v_lshl_add_u64 v[78:79], s[6:7], 0, v[70:71]
	v_lshlrev_b32_e32 v87, 2, v0
	s_and_b32 s27, s0, 0xffffff80
	s_mov_b64 s[6:7], 0
	s_movk_i32 s42, 0x100
	v_mov_b32_e32 v89, 0xf8
	s_movk_i32 s43, 0x2000
	s_movk_i32 s44, 0x7c
	s_mov_b32 s45, 0xf149f2ca
	s_mov_b32 s46, 0x111000
	s_mov_b32 s47, 0x222000
	s_mov_b32 s48, 0x333000
	s_mov_b32 s49, 0x444000
	s_mov_b32 s50, 0x555000
	s_mov_b32 s51, 0x666000
	s_mov_b32 s56, 0x777000
	s_movk_i32 s57, 0x7ff
	s_branch .LBB0_210

; __device__ __forceinline__ unsigned cvt_pk_bf16(float lo, float hi) { unsigned r; asm volatile("v_cvt_pk_bf16_f32 %0, %1, %2" : "=v"(r) : "v"(lo), "v"(hi)); return r; }
; __device__ __forceinline__ float bf2f(bf16_t b) { return __uint_as_float(((unsigned)b) << 16); }
; template <int PASS> __device__ void phase_lru(const Params& P, unsigned char* smem) {
;     ...
;                     } else {
; #pragma unroll 8
;     ...
;                             sumt[(32 + tt) * 128 + sc_] = (bf16_t)(cvt_pk_bf16(h + bf2f(hbuf[((3 - step) * 32 + tt) * 128 + sc_]), 0.f) & 0xffffu); }
.LBB0_503:
	v_add_u32_e32 v136, 0xe800, v83
	v_add_u32_e32 v137, 0x1a000, v82
	ds_read_b64 v[104:105], v136 offset:7168
	ds_read_u16 v120, v137 offset:1792
	ds_read_b64 v[106:107], v136 offset:6144
	ds_read_u16 v121, v137 offset:1536
	ds_read_b64 v[108:109], v136 offset:5120
	ds_read_u16 v122, v137 offset:1280
	ds_read_b64 v[110:111], v136 offset:4096
	ds_read_u16 v123, v137 offset:1024
	v_add_u32_e32 v138, 0x24000, v84
	s_add_i32 s14, s14, 8
	v_add_u32_e32 v83, 0xffffe000, v83
	v_add_u32_e32 v82, 0xfffff800, v82
	v_add_u32_e32 v84, 0xfffff800, v84
	s_cmp_lg_u32 s14, 0
	ds_read_b64 v[112:113], v136 offset:3072
	ds_read_u16 v124, v137 offset:768
	s_waitcnt lgkmcnt(8)
	v_fmac_f32_e32 v105, v81, v104
	v_lshlrev_b32_e32 v120, 16, v120
	v_add_f32_e32 v128, v105, v120
	v_cvt_pk_bf16_f32 v128, v128, v174
	ds_write_b16 v138, v128 offset:1792
	ds_read_b64 v[114:115], v136 offset:2048
	ds_read_u16 v125, v137 offset:512
	s_waitcnt lgkmcnt(9)
	v_fmac_f32_e32 v107, v105, v106
	v_lshlrev_b32_e32 v121, 16, v121
	v_add_f32_e32 v129, v107, v121
	v_cvt_pk_bf16_f32 v129, v129, v174
	ds_write_b16 v138, v129 offset:1536
	ds_read_b64 v[116:117], v136 offset:1024
	ds_read_u16 v126, v137 offset:256
	s_waitcnt lgkmcnt(10)
	v_fmac_f32_e32 v109, v107, v108
	v_lshlrev_b32_e32 v122, 16, v122
	v_add_f32_e32 v130, v109, v122
	v_cvt_pk_bf16_f32 v130, v130, v174
	ds_write_b16 v138, v130 offset:1280
	ds_read_b64 v[118:119], v136 offset:0
	ds_read_u16 v127, v137 offset:0
	s_waitcnt lgkmcnt(11)
	v_fmac_f32_e32 v111, v109, v110
	v_lshlrev_b32_e32 v123, 16, v123
	v_add_f32_e32 v131, v111, v123
	v_cvt_pk_bf16_f32 v131, v131, v174
	ds_write_b16 v138, v131 offset:1024
	s_waitcnt lgkmcnt(10)
	v_fmac_f32_e32 v113, v111, v112
	v_lshlrev_b32_e32 v124, 16, v124
	v_add_f32_e32 v132, v113, v124
	v_cvt_pk_bf16_f32 v132, v132, v174
	ds_write_b16 v138, v132 offset:768
	s_waitcnt lgkmcnt(8)
	v_fmac_f32_e32 v115, v113, v114
	v_lshlrev_b32_e32 v125, 16, v125
	v_add_f32_e32 v133, v115, v125
	v_cvt_pk_bf16_f32 v133, v133, v174
	ds_write_b16 v138, v133 offset:512
	s_waitcnt lgkmcnt(6)
	v_fmac_f32_e32 v117, v115, v116
	v_lshlrev_b32_e32 v126, 16, v126
	v_add_f32_e32 v134, v117, v126
	v_cvt_pk_bf16_f32 v134, v134, v174
	ds_write_b16 v138, v134 offset:256
	s_waitcnt lgkmcnt(4)
	v_fmac_f32_e32 v119, v117, v118
	v_lshlrev_b32_e32 v127, 16, v127
	v_add_f32_e32 v135, v119, v127
	v_cvt_pk_bf16_f32 v135, v135, v174
	ds_write_b16 v138, v135 offset:0
	v_mov_b32_e32 v81, v119
	s_cbranch_scc1 .LBB0_503
	s_mov_b64 s[14:15], 0

; template <int PASS> __device__ void phase_lru(const Params& P, unsigned char* smem) {
;     ...
;                     if (step < 2) {
; #pragma unroll 8
.LBB0_507:
	v_add_u32_e32 v136, 0xe800, v81
	ds_read_b64 v[104:105], v136 offset:7168
	ds_read_b64 v[106:107], v136 offset:6144
	ds_read_b64 v[108:109], v136 offset:5120
	ds_read_b64 v[110:111], v136 offset:4096
	ds_read_b64 v[112:113], v136 offset:3072
	ds_read_b64 v[114:115], v136 offset:2048
	ds_read_b64 v[116:117], v136 offset:1024
	ds_read_b64 v[118:119], v136 offset:0
	v_add_u32_e32 v138, 0x1e000, v80
	s_add_i32 s14, s14, 8
	v_add_u32_e32 v81, 0xffffe000, v81
	v_add_u32_e32 v80, 0xfffff800, v80
	s_cmp_eq_u32 s14, 0
	s_waitcnt lgkmcnt(7)
	v_fmac_f32_e32 v105, v177, v104
	v_cvt_pk_bf16_f32 v128, v105, v174
	ds_write_b16 v138, v128 offset:1792
	s_waitcnt lgkmcnt(7)
	v_fmac_f32_e32 v107, v105, v106
	v_cvt_pk_bf16_f32 v129, v107, v174
	ds_write_b16 v138, v129 offset:1536
	s_waitcnt lgkmcnt(7)
	v_fmac_f32_e32 v109, v107, v108
	v_cvt_pk_bf16_f32 v130, v109, v174
	ds_write_b16 v138, v130 offset:1280
	s_waitcnt lgkmcnt(7)
	v_fmac_f32_e32 v111, v109, v110
	v_cvt_pk_bf16_f32 v131, v111, v174
	ds_write_b16 v138, v131 offset:1024
	s_waitcnt lgkmcnt(7)
	v_fmac_f32_e32 v113, v111, v112
	v_cvt_pk_bf16_f32 v132, v113, v174
	ds_write_b16 v138, v132 offset:768
	s_waitcnt lgkmcnt(7)
	v_fmac_f32_e32 v115, v113, v114
	v_cvt_pk_bf16_f32 v133, v115, v174
	ds_write_b16 v138, v133 offset:512
	s_waitcnt lgkmcnt(7)
	v_fmac_f32_e32 v117, v115, v116
	v_cvt_pk_bf16_f32 v134, v117, v174
	ds_write_b16 v138, v134 offset:256
	s_waitcnt lgkmcnt(7)
	v_fmac_f32_e32 v119, v117, v118
	v_cvt_pk_bf16_f32 v135, v119, v174
	ds_write_b16 v138, v135 offset:0
	v_mov_b32_e32 v177, v119
	s_cbranch_scc0 .LBB0_507
	v_mov_b32_e32 v81, v177

; __device__ __forceinline__ unsigned cvt_pk_bf16(float lo, float hi) { unsigned r; asm volatile("v_cvt_pk_bf16_f32 %0, %1, %2" : "=v"(r) : "v"(lo), "v"(hi)); return r; }
; __device__ __forceinline__ float bf2f(bf16_t b) { return __uint_as_float(((unsigned)b) << 16); }
; template <int PASS> __device__ void phase_lru(const Params& P, unsigned char* smem) {
;     ...
; #pragma unroll 8
;                         for (int tt = 0; tt < 32; ++tt) { const float2 e = aus[tt * 128]; h = e.x * h + e.y;
;                             sumt[tt * 128 + sc_] = (bf16_t)(cvt_pk_bf16(h + bf2f(hbuf[(64 + (3 - step) * 32 + tt) * 128 + sc_]), 0.f) & 0xffffu); }
.LBB0_513:
	v_add_u32_e32 v136, 0, v84
	v_add_u32_e32 v137, 0x1c800, v82
	ds_read_b64 v[104:105], v136 offset:0
	ds_read_u16 v120, v137 offset:0
	ds_read_b64 v[106:107], v136 offset:1024
	ds_read_u16 v121, v137 offset:256
	ds_read_b64 v[108:109], v136 offset:2048
	ds_read_u16 v122, v137 offset:512
	ds_read_b64 v[110:111], v136 offset:3072
	ds_read_u16 v123, v137 offset:768
	v_add_u32_e32 v138, 0x20800, v83
	s_add_i32 s8, s8, -8
	v_add_u32_e32 v84, 0x2000, v84
	v_add_u32_e32 v82, 0x800, v82
	v_add_u32_e32 v83, 0x800, v83
	s_cmp_eq_u32 s8, 0
	ds_read_b64 v[112:113], v136 offset:4096
	ds_read_u16 v124, v137 offset:1024
	s_waitcnt lgkmcnt(8)
	v_fmac_f32_e32 v105, v81, v104
	v_lshlrev_b32_e32 v120, 16, v120
	v_add_f32_e32 v128, v105, v120
	v_cvt_pk_bf16_f32 v128, v128, v174
	ds_write_b16 v138, v128 offset:0
	ds_read_b64 v[114:115], v136 offset:5120
	ds_read_u16 v125, v137 offset:1280
	s_waitcnt lgkmcnt(9)
	v_fmac_f32_e32 v107, v105, v106
	v_lshlrev_b32_e32 v121, 16, v121
	v_add_f32_e32 v129, v107, v121
	v_cvt_pk_bf16_f32 v129, v129, v174
	ds_write_b16 v138, v129 offset:256
	ds_read_b64 v[116:117], v136 offset:6144
	ds_read_u16 v126, v137 offset:1536
	s_waitcnt lgkmcnt(10)
	v_fmac_f32_e32 v109, v107, v108
	v_lshlrev_b32_e32 v122, 16, v122
	v_add_f32_e32 v130, v109, v122
	v_cvt_pk_bf16_f32 v130, v130, v174
	ds_write_b16 v138, v130 offset:512
	ds_read_b64 v[118:119], v136 offset:7168
	ds_read_u16 v127, v137 offset:1792
	s_waitcnt lgkmcnt(11)
	v_fmac_f32_e32 v111, v109, v110
	v_lshlrev_b32_e32 v123, 16, v123
	v_add_f32_e32 v131, v111, v123
	v_cvt_pk_bf16_f32 v131, v131, v174
	ds_write_b16 v138, v131 offset:768
	s_waitcnt lgkmcnt(10)
	v_fmac_f32_e32 v113, v111, v112
	v_lshlrev_b32_e32 v124, 16, v124
	v_add_f32_e32 v132, v113, v124
	v_cvt_pk_bf16_f32 v132, v132, v174
	ds_write_b16 v138, v132 offset:1024
	s_waitcnt lgkmcnt(8)
	v_fmac_f32_e32 v115, v113, v114
	v_lshlrev_b32_e32 v125, 16, v125
	v_add_f32_e32 v133, v115, v125
	v_cvt_pk_bf16_f32 v133, v133, v174
	ds_write_b16 v138, v133 offset:1280
	s_waitcnt lgkmcnt(6)
	v_fmac_f32_e32 v117, v115, v116
	v_lshlrev_b32_e32 v126, 16, v126
	v_add_f32_e32 v134, v117, v126
	v_cvt_pk_bf16_f32 v134, v134, v174
	ds_write_b16 v138, v134 offset:1536
	s_waitcnt lgkmcnt(4)
	v_fmac_f32_e32 v119, v117, v118
	v_lshlrev_b32_e32 v127, 16, v127
	v_add_f32_e32 v135, v119, v127
	v_cvt_pk_bf16_f32 v135, v135, v174
	ds_write_b16 v138, v135 offset:1792
	v_mov_b32_e32 v81, v119
	s_cbranch_scc0 .LBB0_513
	s_mov_b64 s[8:9], 0

; __device__ __forceinline__ unsigned cvt_pk_bf16(float lo, float hi) { unsigned r; asm volatile("v_cvt_pk_bf16_f32 %0, %1, %2" : "=v"(r) : "v"(lo), "v"(hi)); return r; }
; template <int PASS> __device__ void phase_lru(const Params& P, unsigned char* smem) {
;     ...
; #pragma unroll 8
;                         for (int tt = 0; tt < 32; ++tt) { const float2 e = aus[tt * 128]; h = e.x * h + e.y; hbuf[(step * 32 + tt) * 128 + sc_] = (bf16_t)(cvt_pk_bf16(h, 0.f) & 0xffffu); }
.LBB0_517:
	v_add_u32_e32 v136, 0, v81
	ds_read_b64 v[104:105], v136 offset:0
	ds_read_b64 v[106:107], v136 offset:1024
	ds_read_b64 v[108:109], v136 offset:2048
	ds_read_b64 v[110:111], v136 offset:3072
	ds_read_b64 v[112:113], v136 offset:4096
	ds_read_b64 v[114:115], v136 offset:5120
	ds_read_b64 v[116:117], v136 offset:6144
	ds_read_b64 v[118:119], v136 offset:7168
	v_add_u32_e32 v138, 0x18800, v80
	s_add_i32 s8, s8, -8
	v_add_u32_e32 v81, 0x2000, v81
	v_add_u32_e32 v80, 0x800, v80
	s_cmp_eq_u32 s8, 0
	s_waitcnt lgkmcnt(7)
	v_fmac_f32_e32 v105, v177, v104
	v_cvt_pk_bf16_f32 v128, v105, v174
	ds_write_b16 v138, v128 offset:0
	s_waitcnt lgkmcnt(7)
	v_fmac_f32_e32 v107, v105, v106
	v_cvt_pk_bf16_f32 v129, v107, v174
	ds_write_b16 v138, v129 offset:256
	s_waitcnt lgkmcnt(7)
	v_fmac_f32_e32 v109, v107, v108
	v_cvt_pk_bf16_f32 v130, v109, v174
	ds_write_b16 v138, v130 offset:512
	s_waitcnt lgkmcnt(7)
	v_fmac_f32_e32 v111, v109, v110
	v_cvt_pk_bf16_f32 v131, v111, v174
	ds_write_b16 v138, v131 offset:768
	s_waitcnt lgkmcnt(7)
	v_fmac_f32_e32 v113, v111, v112
	v_cvt_pk_bf16_f32 v132, v113, v174
	ds_write_b16 v138, v132 offset:1024
	s_waitcnt lgkmcnt(7)
	v_fmac_f32_e32 v115, v113, v114
	v_cvt_pk_bf16_f32 v133, v115, v174
	ds_write_b16 v138, v133 offset:1280
	s_waitcnt lgkmcnt(7)
	v_fmac_f32_e32 v117, v115, v116
	v_cvt_pk_bf16_f32 v134, v117, v174
	ds_write_b16 v138, v134 offset:1536
	s_waitcnt lgkmcnt(7)
	v_fmac_f32_e32 v119, v117, v118
	v_cvt_pk_bf16_f32 v135, v119, v174
	ds_write_b16 v138, v135 offset:1792
	v_mov_b32_e32 v177, v119
	s_cbranch_scc0 .LBB0_517
	v_mov_b32_e32 v81, v177

; #define PG8_STAGE(bufoff, gbase, voff) do { _Pragma("unroll") for (int _i = 0; _i < 2; ++_i) \
;         __builtin_amdgcn_global_load_lds((const unsigned*)((const char*)(gbase) + (voff)[_i]), (PG8_LAS unsigned*)(lds + (bufoff) + ldsw + _i * 8192), 16, 0, 0); } while (0)
; #define PG8_LDA(dst, b, h) do { _Pragma("unroll") for (int m = 0; m < 4; ++m) _Pragma("unroll") for (int k = 0; k < 2; ++k) dst[m][k] = *(const PG8_LAS bf16x8*)(lds + PG8_SA(b, h) + aoff + m * 2048 + k * 1024); } while (0)
; #define PG8_LDB(dst, b, h) do { _Pragma("unroll") for (int n = 0; n < 2; ++n) _Pragma("unroll") for (int k = 0; k < 2; ++k) dst[n][k] = *(const PG8_LAS bf16x8*)(lds + PG8_SB(b, h) + boff + n * 2048 + k * 1024); } while (0)
; #define PG8_MMA(ai, bj, At, Bt) do { __builtin_amdgcn_s_setprio(1); _Pragma("unroll") for (int m = 0; m < 4; ++m) _Pragma("unroll") for (int n = 0; n < 2; ++n) _Pragma("unroll") for (int k = 0; k < 2; ++k) \
;         acc[ai][bj][m][n] = __builtin_amdgcn_mfma_f32_16x16x32_bf16(Bt[n][k], At[m][k], acc[ai][bj][m][n], 0, 0, 0); __builtin_amdgcn_s_setprio(0); } while (0)
; #define PG8_WAIT_V(n) asm volatile("s_waitcnt vmcnt(" #n ")" ::: "memory")
; #define PG8_WAIT_L(n) asm volatile("s_waitcnt lgkmcnt(" #n ")" ::: "memory")
; #define PG8_BAR __builtin_amdgcn_s_barrier()
; #define PG8_SCHED __builtin_amdgcn_sched_barrier(0)
; template <class Epi, class Sched>
; __device__ __forceinline__ void gemm_phase(PG8_LAS unsigned char* lds, const Gemm g, const Sched& S, const Epi& E) {
;     ...
;             PG8_LDB(B0, 0, 0); PG8_SCHED; PG8_LDA(At, 0, 0); PG8_STAGE(PG8_SA(1, 1), a1 + hstep, voffA);
;             PG8_WAIT_L(8); PG8_BAR; PG8_WAIT_L(0); PG8_MMA(0, 0, At, B0); PG8_BAR; PG8_SCHED;
;             PG8_LDB(B1, 0, 1); PG8_STAGE(PG8_SB(0, 0), b2, voffB);
;             PG8_BAR; PG8_WAIT_L(0); PG8_MMA(0, 1, At, B1); PG8_BAR;
;             PG8_LDA(At, 0, 1); PG8_STAGE(PG8_SA(0, 0), a2, voffA);
;             PG8_BAR; PG8_WAIT_L(0); PG8_MMA(1, 0, At, B0); PG8_BAR; PG8_SCHED;
;             PG8_STAGE(PG8_SB(0, 1), b2 + hstep, voffB);
;             PG8_WAIT_V(6); PG8_BAR; PG8_MMA(1, 1, At, B1); PG8_BAR;
;             PG8_LDB(B0, 1, 0); PG8_SCHED; PG8_LDA(At, 1, 0); PG8_STAGE(PG8_SA(0, 1), a2 + hstep, voffA);
;             PG8_WAIT_L(8); PG8_BAR; PG8_WAIT_L(0); PG8_MMA(0, 0, At, B0); PG8_BAR; PG8_SCHED;
.LBB0_766:
	ds_read_b128 v[150:153], v157
	ds_read_b128 v[160:163], v157 offset:1024
	ds_read_b128 v[164:167], v157 offset:2048
	ds_read_b128 v[168:171], v157 offset:3072
	s_add_u32 s20, s18, 0xfff80080
	s_addc_u32 s21, s19, -1
	s_cmp_eq_u32 s58, 28
	s_cselect_b32 s23, s9, s21
	s_cselect_b32 s22, s15, s20
	s_cselect_b32 s21, s7, s57
	s_cselect_b32 s20, s17, s56
	v_lshl_add_u64 v[154:155], s[18:19], 0, v[138:139]
	s_add_i32 m0, s27, 0xc000
	ds_read_b128 v[172:175], v158
	ds_read_b128 v[176:179], v158 offset:1024
	ds_read_b128 v[180:183], v158 offset:2048
	ds_read_b128 v[184:187], v158 offset:3072
	ds_read_b128 v[188:191], v158 offset:4096
	ds_read_b128 v[192:195], v158 offset:5120
	ds_read_b128 v[196:199], v158 offset:6144
	ds_read_b128 v[200:203], v158 offset:7168
	global_load_lds_dwordx4 v[154:155], off
	v_lshl_add_u64 v[154:155], s[18:19], 0, v[140:141]
	s_add_i32 m0, s27, 0xe000
	s_nop 0
	global_load_lds_dwordx4 v[154:155], off
	s_waitcnt lgkmcnt(8)
	s_barrier
	s_waitcnt lgkmcnt(0)
	s_setprio 1
	s_waitcnt lgkmcnt(0)
	v_mfma_f32_16x16x32_bf16 v[124:127], v[150:153], v[172:175], v[124:127]
	v_mfma_f32_16x16x32_bf16 v[120:123], v[164:167], v[172:175], v[120:123]
	v_mfma_f32_16x16x32_bf16 v[108:111], v[150:153], v[180:183], v[108:111]
	v_mfma_f32_16x16x32_bf16 v[104:107], v[164:167], v[180:183], v[104:107]
	v_mfma_f32_16x16x32_bf16 v[92:95], v[150:153], v[188:191], v[92:95]
	v_mfma_f32_16x16x32_bf16 v[88:91], v[164:167], v[188:191], v[88:91]
	v_mfma_f32_16x16x32_bf16 v[76:79], v[150:153], v[196:199], v[76:79]
	v_mfma_f32_16x16x32_bf16 v[72:75], v[164:167], v[196:199], v[72:75]
	v_mfma_f32_16x16x32_bf16 v[124:127], v[160:163], v[176:179], v[124:127]
	v_mfma_f32_16x16x32_bf16 v[120:123], v[168:171], v[176:179], v[120:123]
	v_mfma_f32_16x16x32_bf16 v[108:111], v[160:163], v[184:187], v[108:111]
	v_mfma_f32_16x16x32_bf16 v[104:107], v[168:171], v[184:187], v[104:107]
	v_mfma_f32_16x16x32_bf16 v[92:95], v[160:163], v[192:195], v[92:95]
	v_mfma_f32_16x16x32_bf16 v[88:91], v[168:171], v[192:195], v[88:91]
	v_mfma_f32_16x16x32_bf16 v[76:79], v[160:163], v[200:203], v[76:79]
	v_mfma_f32_16x16x32_bf16 v[72:75], v[168:171], v[200:203], v[72:75]
	s_setprio 0
	s_barrier
	s_add_i32 s30, s49, s26
	v_lshl_add_u64 v[154:155], s[20:21], 0, v[130:131]
	s_mov_b32 m0, s30
	ds_read_b128 v[204:207], v159
	ds_read_b128 v[208:211], v159 offset:1024
	ds_read_b128 v[212:215], v159 offset:2048
	ds_read_b128 v[216:219], v159 offset:3072
	global_load_lds_dwordx4 v[154:155], off
	v_lshl_add_u64 v[220:221], s[20:21], 0, v[134:135]
	s_add_i32 m0, s30, 0x2000
	s_nop 0
	global_load_lds_dwordx4 v[220:221], off
	s_barrier
	s_waitcnt lgkmcnt(0)
	s_setprio 1
	s_waitcnt lgkmcnt(0)
	v_mfma_f32_16x16x32_bf16 v[116:119], v[204:207], v[172:175], v[116:119]
	v_mfma_f32_16x16x32_bf16 v[112:115], v[212:215], v[172:175], v[112:115]
	v_mfma_f32_16x16x32_bf16 v[100:103], v[204:207], v[180:183], v[100:103]
	v_mfma_f32_16x16x32_bf16 v[96:99], v[212:215], v[180:183], v[96:99]
	v_mfma_f32_16x16x32_bf16 v[84:87], v[204:207], v[188:191], v[84:87]
	v_mfma_f32_16x16x32_bf16 v[80:83], v[212:215], v[188:191], v[80:83]
	v_mfma_f32_16x16x32_bf16 v[68:71], v[204:207], v[196:199], v[68:71]
	v_mfma_f32_16x16x32_bf16 v[64:67], v[212:215], v[196:199], v[64:67]
	v_mfma_f32_16x16x32_bf16 v[116:119], v[208:211], v[176:179], v[116:119]
	v_mfma_f32_16x16x32_bf16 v[112:115], v[216:219], v[176:179], v[112:115]
	v_mfma_f32_16x16x32_bf16 v[100:103], v[208:211], v[184:187], v[100:103]
	v_mfma_f32_16x16x32_bf16 v[96:99], v[216:219], v[184:187], v[96:99]
	v_mfma_f32_16x16x32_bf16 v[84:87], v[208:211], v[192:195], v[84:87]
	v_mfma_f32_16x16x32_bf16 v[80:83], v[216:219], v[192:195], v[80:83]
	v_mfma_f32_16x16x32_bf16 v[68:71], v[208:211], v[200:203], v[68:71]
	v_mfma_f32_16x16x32_bf16 v[64:67], v[216:219], v[200:203], v[64:67]
	s_setprio 0
	s_mov_b32 m0, s27
	v_lshl_add_u64 v[222:223], s[22:23], 0, v[128:129]
	s_barrier
	ds_read_b128 v[172:175], v158 offset:16384
	ds_read_b128 v[176:179], v158 offset:17408
	ds_read_b128 v[180:183], v158 offset:18432
	ds_read_b128 v[184:187], v158 offset:19456
	ds_read_b128 v[188:191], v158 offset:20480
	ds_read_b128 v[192:195], v158 offset:21504
	ds_read_b128 v[196:199], v158 offset:22528
	ds_read_b128 v[200:203], v158 offset:23552
	global_load_lds_dwordx4 v[222:223], off
	v_lshl_add_u64 v[224:225], s[22:23], 0, v[132:133]
	s_mov_b32 m0, s28
	s_nop 0
	global_load_lds_dwordx4 v[224:225], off
	s_barrier
	s_waitcnt lgkmcnt(0)
	s_setprio 1
	s_waitcnt lgkmcnt(0)
	v_mfma_f32_16x16x32_bf16 v[60:63], v[150:153], v[172:175], v[60:63]
	v_mfma_f32_16x16x32_bf16 v[56:59], v[164:167], v[172:175], v[56:59]
	v_mfma_f32_16x16x32_bf16 v[44:47], v[150:153], v[180:183], v[44:47]
	v_mfma_f32_16x16x32_bf16 v[40:43], v[164:167], v[180:183], v[40:43]
	v_mfma_f32_16x16x32_bf16 v[28:31], v[150:153], v[188:191], v[28:31]
	v_mfma_f32_16x16x32_bf16 v[24:27], v[164:167], v[188:191], v[24:27]
	v_mfma_f32_16x16x32_bf16 v[12:15], v[150:153], v[196:199], v[12:15]
	v_mfma_f32_16x16x32_bf16 v[8:11], v[164:167], v[196:199], v[8:11]
	v_mfma_f32_16x16x32_bf16 v[60:63], v[160:163], v[176:179], v[60:63]
	v_mfma_f32_16x16x32_bf16 v[56:59], v[168:171], v[176:179], v[56:59]
	v_mfma_f32_16x16x32_bf16 v[44:47], v[160:163], v[184:187], v[44:47]
	v_mfma_f32_16x16x32_bf16 v[40:43], v[168:171], v[184:187], v[40:43]
	v_mfma_f32_16x16x32_bf16 v[28:31], v[160:163], v[192:195], v[28:31]
	v_mfma_f32_16x16x32_bf16 v[24:27], v[168:171], v[192:195], v[24:27]
	v_mfma_f32_16x16x32_bf16 v[12:15], v[160:163], v[200:203], v[12:15]
	v_mfma_f32_16x16x32_bf16 v[8:11], v[168:171], v[200:203], v[8:11]
	s_setprio 0
	s_barrier
; #define PG8_STAGE(bufoff, gbase, voff) do { _Pragma("unroll") for (int _i = 0; _i < 2; ++_i) \
;         __builtin_amdgcn_global_load_lds((const unsigned*)((const char*)(gbase) + (voff)[_i]), (PG8_LAS unsigned*)(lds + (bufoff) + ldsw + _i * 8192), 16, 0, 0); } while (0)
; #define PG8_LDA(dst, b, h) do { _Pragma("unroll") for (int m = 0; m < 4; ++m) _Pragma("unroll") for (int k = 0; k < 2; ++k) dst[m][k] = *(const PG8_LAS bf16x8*)(lds + PG8_SA(b, h) + aoff + m * 2048 + k * 1024); } while (0)
; #define PG8_LDB(dst, b, h) do { _Pragma("unroll") for (int n = 0; n < 2; ++n) _Pragma("unroll") for (int k = 0; k < 2; ++k) dst[n][k] = *(const PG8_LAS bf16x8*)(lds + PG8_SB(b, h) + boff + n * 2048 + k * 1024); } while (0)
; #define PG8_MMA(ai, bj, At, Bt) do { __builtin_amdgcn_s_setprio(1); _Pragma("unroll") for (int m = 0; m < 4; ++m) _Pragma("unroll") for (int n = 0; n < 2; ++n) _Pragma("unroll") for (int k = 0; k < 2; ++k) \
;         acc[ai][bj][m][n] = __builtin_amdgcn_mfma_f32_16x16x32_bf16(Bt[n][k], At[m][k], acc[ai][bj][m][n], 0, 0, 0); __builtin_amdgcn_s_setprio(0); } while (0)
; #define PG8_WAIT_V(n) asm volatile("s_waitcnt vmcnt(" #n ")" ::: "memory")
; #define PG8_WAIT_L(n) asm volatile("s_waitcnt lgkmcnt(" #n ")" ::: "memory")
; #define PG8_BAR __builtin_amdgcn_s_barrier()
; #define PG8_SCHED __builtin_amdgcn_sched_barrier(0)
; template <class Epi, class Sched>
; __device__ __forceinline__ void gemm_phase(PG8_LAS unsigned char* lds, const Gemm g, const Sched& S, const Epi& E) {
;     ...
;             PG8_STAGE(PG8_SB(0, 1), b2 + hstep, voffB);
;             PG8_WAIT_V(6); PG8_BAR; PG8_MMA(1, 1, At, B1); PG8_BAR;
;             PG8_LDB(B0, 1, 0); PG8_SCHED; PG8_LDA(At, 1, 0); PG8_STAGE(PG8_SA(0, 1), a2 + hstep, voffA);
;             PG8_WAIT_L(8); PG8_BAR; PG8_WAIT_L(0); PG8_MMA(0, 0, At, B0); PG8_BAR; PG8_SCHED;
;             PG8_LDB(B1, 1, 1); PG8_STAGE(PG8_SB(1, 0), b3, voffB);
;             PG8_BAR; PG8_WAIT_L(0); PG8_MMA(0, 1, At, B1); PG8_BAR;
;             PG8_LDA(At, 1, 1); PG8_STAGE(PG8_SA(1, 0), a3, voffA);
;             PG8_BAR; PG8_WAIT_L(0); PG8_MMA(1, 0, At, B0); PG8_BAR; PG8_SCHED;
	s_add_u32 s30, s20, 0x80000
	s_addc_u32 s31, s21, 0
	s_add_i32 s38, s50, s26
	v_lshl_add_u64 v[150:151], s[30:31], 0, v[130:131]
	s_mov_b32 m0, s38
	s_nop 0
	global_load_lds_dwordx4 v[150:151], off
	v_lshl_add_u64 v[150:151], s[30:31], 0, v[134:135]
	s_add_i32 m0, s38, 0x2000
	s_nop 0
	global_load_lds_dwordx4 v[150:151], off
	s_waitcnt vmcnt(6)
	s_barrier
	s_setprio 1
	v_mfma_f32_16x16x32_bf16 v[52:55], v[204:207], v[172:175], v[52:55]
	v_mfma_f32_16x16x32_bf16 v[48:51], v[212:215], v[172:175], v[48:51]
	v_mfma_f32_16x16x32_bf16 v[36:39], v[204:207], v[180:183], v[36:39]
	v_mfma_f32_16x16x32_bf16 v[32:35], v[212:215], v[180:183], v[32:35]
	v_mfma_f32_16x16x32_bf16 v[20:23], v[204:207], v[188:191], v[20:23]
	v_mfma_f32_16x16x32_bf16 v[16:19], v[212:215], v[188:191], v[16:19]
	v_mfma_f32_16x16x32_bf16 v[4:7], v[204:207], v[196:199], v[4:7]
	v_mfma_f32_16x16x32_bf16 v[0:3], v[212:215], v[196:199], v[0:3]
	v_mfma_f32_16x16x32_bf16 v[52:55], v[208:211], v[176:179], v[52:55]
	v_mfma_f32_16x16x32_bf16 v[48:51], v[216:219], v[176:179], v[48:51]
	v_mfma_f32_16x16x32_bf16 v[36:39], v[208:211], v[184:187], v[36:39]
	v_mfma_f32_16x16x32_bf16 v[32:35], v[216:219], v[184:187], v[32:35]
	v_mfma_f32_16x16x32_bf16 v[20:23], v[208:211], v[192:195], v[20:23]
	v_mfma_f32_16x16x32_bf16 v[16:19], v[216:219], v[192:195], v[16:19]
	v_mfma_f32_16x16x32_bf16 v[4:7], v[208:211], v[200:203], v[4:7]
	v_mfma_f32_16x16x32_bf16 v[0:3], v[216:219], v[200:203], v[0:3]
	s_setprio 0
	s_add_i32 s30, 0, 0x18000
	v_add_u32_e32 v136, s30, v147
	s_barrier
	ds_read_b128 v[150:153], v136
	ds_read_b128 v[160:163], v136 offset:1024
	ds_read_b128 v[164:167], v136 offset:2048
	ds_read_b128 v[168:171], v136 offset:3072
	s_add_u32 s22, s22, 0x80000
	s_addc_u32 s23, s23, 0
	s_mov_b32 m0, s29
	v_lshl_add_u64 v[204:205], s[22:23], 0, v[128:129]
	ds_read_b128 v[172:175], v158 offset:32768
	ds_read_b128 v[176:179], v158 offset:33792
	ds_read_b128 v[180:183], v158 offset:34816
	ds_read_b128 v[184:187], v158 offset:35840
	ds_read_b128 v[188:191], v158 offset:36864
	ds_read_b128 v[192:195], v158 offset:37888
	ds_read_b128 v[196:199], v158 offset:38912
	ds_read_b128 v[200:203], v158 offset:39936
	global_load_lds_dwordx4 v[204:205], off
	v_lshl_add_u64 v[204:205], s[22:23], 0, v[132:133]
	s_mov_b32 m0, s42
	s_nop 0
	global_load_lds_dwordx4 v[204:205], off
	s_waitcnt lgkmcnt(8)
	s_barrier
	s_waitcnt lgkmcnt(0)
	s_setprio 1
	s_waitcnt lgkmcnt(0)
	v_mfma_f32_16x16x32_bf16 v[124:127], v[150:153], v[172:175], v[124:127]
	v_mfma_f32_16x16x32_bf16 v[120:123], v[164:167], v[172:175], v[120:123]
	v_mfma_f32_16x16x32_bf16 v[108:111], v[150:153], v[180:183], v[108:111]
	v_mfma_f32_16x16x32_bf16 v[104:107], v[164:167], v[180:183], v[104:107]
	v_mfma_f32_16x16x32_bf16 v[92:95], v[150:153], v[188:191], v[92:95]
	v_mfma_f32_16x16x32_bf16 v[88:91], v[164:167], v[188:191], v[88:91]
	v_mfma_f32_16x16x32_bf16 v[76:79], v[150:153], v[196:199], v[76:79]
	v_mfma_f32_16x16x32_bf16 v[72:75], v[164:167], v[196:199], v[72:75]
	v_mfma_f32_16x16x32_bf16 v[124:127], v[160:163], v[176:179], v[124:127]
	v_mfma_f32_16x16x32_bf16 v[120:123], v[168:171], v[176:179], v[120:123]
	v_mfma_f32_16x16x32_bf16 v[108:111], v[160:163], v[184:187], v[108:111]
	v_mfma_f32_16x16x32_bf16 v[104:107], v[168:171], v[184:187], v[104:107]
	v_mfma_f32_16x16x32_bf16 v[92:95], v[160:163], v[192:195], v[92:95]
	v_mfma_f32_16x16x32_bf16 v[88:91], v[168:171], v[192:195], v[88:91]
	v_mfma_f32_16x16x32_bf16 v[76:79], v[160:163], v[200:203], v[76:79]
	v_mfma_f32_16x16x32_bf16 v[72:75], v[168:171], v[200:203], v[72:75]
	s_setprio 0
	s_barrier
	s_add_i32 s22, 0, 0x1c000
	s_add_i32 s23, s30, s26
	v_add_u32_e32 v136, s22, v147
	v_lshl_add_u64 v[154:155], v[154:155], 0, s[0:1]
	s_mov_b32 m0, s23
	ds_read_b128 v[204:207], v136
	ds_read_b128 v[208:211], v136 offset:1024
	ds_read_b128 v[212:215], v136 offset:2048
	ds_read_b128 v[216:219], v136 offset:3072
	global_load_lds_dwordx4 v[154:155], off
	v_lshl_add_u64 v[154:155], v[220:221], 0, s[0:1]
	s_add_i32 m0, s23, 0x2000
	s_nop 0
	global_load_lds_dwordx4 v[154:155], off
	s_barrier
	s_waitcnt lgkmcnt(0)
	s_setprio 1
	s_waitcnt lgkmcnt(0)
	v_mfma_f32_16x16x32_bf16 v[116:119], v[204:207], v[172:175], v[116:119]
	v_mfma_f32_16x16x32_bf16 v[112:115], v[212:215], v[172:175], v[112:115]
	v_mfma_f32_16x16x32_bf16 v[100:103], v[204:207], v[180:183], v[100:103]
	v_mfma_f32_16x16x32_bf16 v[96:99], v[212:215], v[180:183], v[96:99]
	v_mfma_f32_16x16x32_bf16 v[84:87], v[204:207], v[188:191], v[84:87]
	v_mfma_f32_16x16x32_bf16 v[80:83], v[212:215], v[188:191], v[80:83]
	v_mfma_f32_16x16x32_bf16 v[68:71], v[204:207], v[196:199], v[68:71]
	v_mfma_f32_16x16x32_bf16 v[64:67], v[212:215], v[196:199], v[64:67]
	v_mfma_f32_16x16x32_bf16 v[116:119], v[208:211], v[176:179], v[116:119]
	v_mfma_f32_16x16x32_bf16 v[112:115], v[216:219], v[176:179], v[112:115]
	v_mfma_f32_16x16x32_bf16 v[100:103], v[208:211], v[184:187], v[100:103]
	v_mfma_f32_16x16x32_bf16 v[96:99], v[216:219], v[184:187], v[96:99]
	v_mfma_f32_16x16x32_bf16 v[84:87], v[208:211], v[192:195], v[84:87]
	v_mfma_f32_16x16x32_bf16 v[80:83], v[216:219], v[192:195], v[80:83]
	v_mfma_f32_16x16x32_bf16 v[68:71], v[208:211], v[200:203], v[68:71]
	v_mfma_f32_16x16x32_bf16 v[64:67], v[216:219], v[200:203], v[64:67]
	s_setprio 0
	s_mov_b32 m0, s44
	v_lshl_add_u64 v[154:155], v[222:223], 0, s[0:1]
	s_barrier
	ds_read_b128 v[172:175], v158 offset:49152
	ds_read_b128 v[176:179], v158 offset:50176
	ds_read_b128 v[180:183], v158 offset:51200
	ds_read_b128 v[184:187], v158 offset:52224
	ds_read_b128 v[188:191], v158 offset:53248
	ds_read_b128 v[192:195], v158 offset:54272
	ds_read_b128 v[196:199], v158 offset:55296
	ds_read_b128 v[200:203], v158 offset:56320
	global_load_lds_dwordx4 v[154:155], off
	v_lshl_add_u64 v[154:155], v[224:225], 0, s[0:1]
	s_mov_b32 m0, s45
	s_nop 0
	global_load_lds_dwordx4 v[154:155], off
	s_barrier
; #define PG8_STAGE(bufoff, gbase, voff) do { _Pragma("unroll") for (int _i = 0; _i < 2; ++_i) \
;         __builtin_amdgcn_global_load_lds((const unsigned*)((const char*)(gbase) + (voff)[_i]), (PG8_LAS unsigned*)(lds + (bufoff) + ldsw + _i * 8192), 16, 0, 0); } while (0)
; #define PG8_MMA(ai, bj, At, Bt) do { __builtin_amdgcn_s_setprio(1); _Pragma("unroll") for (int m = 0; m < 4; ++m) _Pragma("unroll") for (int n = 0; n < 2; ++n) _Pragma("unroll") for (int k = 0; k < 2; ++k) \
;         acc[ai][bj][m][n] = __builtin_amdgcn_mfma_f32_16x16x32_bf16(Bt[n][k], At[m][k], acc[ai][bj][m][n], 0, 0, 0); __builtin_amdgcn_s_setprio(0); } while (0)
; #define PG8_WAIT_V(n) asm volatile("s_waitcnt vmcnt(" #n ")" ::: "memory")
; #define PG8_WAIT_L(n) asm volatile("s_waitcnt lgkmcnt(" #n ")" ::: "memory")
; #define PG8_BAR __builtin_amdgcn_s_barrier()
; #define PG8_SCHED __builtin_amdgcn_sched_barrier(0)
; template <class Epi, class Sched>
; __device__ __forceinline__ void gemm_phase(PG8_LAS unsigned char* lds, const Gemm g, const Sched& S, const Epi& E) {
;     ...
;             PG8_BAR; PG8_WAIT_L(0); PG8_MMA(1, 0, At, B0); PG8_BAR; PG8_SCHED;
;             PG8_STAGE(PG8_SB(1, 1), b3 + hstep, voffB);
;             PG8_WAIT_V(6); PG8_BAR; PG8_MMA(1, 1, At, B1); PG8_BAR;
;     __device__ __forceinline__ void operator()(AccRef acc, const Unit& u, int wr, int wc, int fr, int fq) const {
;         const int c0 = u.pn * 256 + wc * 32 + 8 * fq;
; #pragma unroll
;         for (int ai = 0; ai < 2; ++ai)
; #pragma unroll
;             for (int m = 0; m < 4; ++m) {
;                 const int r = u.pm * 256 + ai * 128 + wr * 64 + m * 16 + fr;
;                 const float* xrow = r < TP ? xp + (size_t)r * D : xs + (size_t)(r - TP) * D;
;                 float ss = 0.f;
; #pragma unroll
;                 for (int bj = 0; bj < 2; ++bj) {
;                     const int c = c0 + bj * 128;
;                     const f32x4 v0 = *(const f32x4*)(xrow + c) + acc[ai][bj][m][0], v1 = *(const f32x4*)(xrow + c + 4) + acc[ai][bj][m][1];
;                     ss += v0[0] * v0[0] + v0[1] * v0[1] + v0[2] * v0[2] + v0[3] * v0[3] + v1[0] * v1[0] + v1[1] * v1[1] + v1[2] * v1[2] + v1[3] * v1[3];
;                     *(uint4*)(Hb + (size_t)r * D + c) = pk8(v0, v1);
;                 }
	s_waitcnt lgkmcnt(0)
	s_setprio 1
	s_waitcnt lgkmcnt(0)
	v_mfma_f32_16x16x32_bf16 v[60:63], v[150:153], v[172:175], v[60:63]
	v_mfma_f32_16x16x32_bf16 v[56:59], v[164:167], v[172:175], v[56:59]
	v_mfma_f32_16x16x32_bf16 v[44:47], v[150:153], v[180:183], v[44:47]
	v_mfma_f32_16x16x32_bf16 v[40:43], v[164:167], v[180:183], v[40:43]
	v_mfma_f32_16x16x32_bf16 v[28:31], v[150:153], v[188:191], v[28:31]
	v_mfma_f32_16x16x32_bf16 v[24:27], v[164:167], v[188:191], v[24:27]
	v_mfma_f32_16x16x32_bf16 v[12:15], v[150:153], v[196:199], v[12:15]
	v_mfma_f32_16x16x32_bf16 v[8:11], v[164:167], v[196:199], v[8:11]
	v_mfma_f32_16x16x32_bf16 v[60:63], v[160:163], v[176:179], v[60:63]
	v_mfma_f32_16x16x32_bf16 v[56:59], v[168:171], v[176:179], v[56:59]
	v_mfma_f32_16x16x32_bf16 v[44:47], v[160:163], v[184:187], v[44:47]
	v_mfma_f32_16x16x32_bf16 v[40:43], v[168:171], v[184:187], v[40:43]
	v_mfma_f32_16x16x32_bf16 v[28:31], v[160:163], v[192:195], v[28:31]
	v_mfma_f32_16x16x32_bf16 v[24:27], v[168:171], v[192:195], v[24:27]
	v_mfma_f32_16x16x32_bf16 v[12:15], v[160:163], v[200:203], v[12:15]
	v_mfma_f32_16x16x32_bf16 v[8:11], v[168:171], v[200:203], v[8:11]
	s_setprio 0
	s_barrier
	s_add_u32 s20, s20, 0x80080
	s_addc_u32 s21, s21, 0
	s_add_i32 s22, s22, s26
	v_lshl_add_u64 v[150:151], s[20:21], 0, v[130:131]
	s_mov_b32 m0, s22
	s_nop 0
	global_load_lds_dwordx4 v[150:151], off
	v_lshl_add_u64 v[150:151], s[20:21], 0, v[134:135]
	s_add_i32 m0, s22, 0x2000
	s_nop 0
	global_load_lds_dwordx4 v[150:151], off
	s_waitcnt vmcnt(6)
	s_barrier
	s_setprio 1
	v_mfma_f32_16x16x32_bf16 v[52:55], v[204:207], v[172:175], v[52:55]
	v_mfma_f32_16x16x32_bf16 v[48:51], v[212:215], v[172:175], v[48:51]
	v_mfma_f32_16x16x32_bf16 v[36:39], v[204:207], v[180:183], v[36:39]
	v_mfma_f32_16x16x32_bf16 v[32:35], v[212:215], v[180:183], v[32:35]
	v_mfma_f32_16x16x32_bf16 v[20:23], v[204:207], v[188:191], v[20:23]
	v_mfma_f32_16x16x32_bf16 v[16:19], v[212:215], v[188:191], v[16:19]
	v_mfma_f32_16x16x32_bf16 v[4:7], v[204:207], v[196:199], v[4:7]
	v_mfma_f32_16x16x32_bf16 v[0:3], v[212:215], v[196:199], v[0:3]
	v_mfma_f32_16x16x32_bf16 v[52:55], v[208:211], v[176:179], v[52:55]
	v_mfma_f32_16x16x32_bf16 v[48:51], v[216:219], v[176:179], v[48:51]
	v_mfma_f32_16x16x32_bf16 v[36:39], v[208:211], v[184:187], v[36:39]
	v_mfma_f32_16x16x32_bf16 v[32:35], v[216:219], v[184:187], v[32:35]
	v_mfma_f32_16x16x32_bf16 v[20:23], v[208:211], v[192:195], v[20:23]
	v_mfma_f32_16x16x32_bf16 v[16:19], v[216:219], v[192:195], v[16:19]
	v_mfma_f32_16x16x32_bf16 v[4:7], v[208:211], v[200:203], v[4:7]
	v_mfma_f32_16x16x32_bf16 v[0:3], v[216:219], v[200:203], v[0:3]
	s_setprio 0
	s_add_i32 s58, s58, 2
	s_add_u32 s18, s18, 0x100
	s_addc_u32 s19, s19, 0
	s_add_u32 s56, s56, 0x100
	s_addc_u32 s57, s57, 0
	s_cmp_gt_u32 s58, 29
	s_barrier
	s_cbranch_scc0 .LBB0_766
	v_lshl_add_u32 v152, s16, 8, v145
	v_cmp_lt_i32_e32 vcc, s51, v152
	s_and_saveexec_b64 s[16:17], vcc
	s_xor_b64 s[16:17], exec, s[16:17]
	v_add_u32_e32 v136, 0xffffc000, v152
	v_lshlrev_b64 v[150:151], 13, v[136:137]
	v_lshl_add_u64 v[154:155], s[54:55], 0, v[150:151]
	v_mov_b32_e32 v153, v137
	s_andn2_saveexec_b64 s[16:17], s[16:17]
	v_ashrrev_i32_e32 v153, 31, v152
	v_lshlrev_b64 v[150:151], 13, v[152:153]
	v_lshl_add_u64 v[154:155], s[52:53], 0, v[150:151]
	s_or_b64 exec, exec, s[16:17]
	v_lshl_or_b32 v150, s14, 8, v156
	v_ashrrev_i32_e32 v151, 31, v150
	v_lshl_add_u64 v[154:155], v[150:151], 2, v[154:155]
	global_load_dwordx4 v[160:163], v[154:155], off
	global_load_dwordx4 v[164:167], v[154:155], off offset:16
	v_lshlrev_b64 v[168:169], 12, v[152:153]
	v_lshl_add_u64 v[168:169], s[34:35], 0, v[168:169]
	v_lshl_add_u64 v[168:169], v[150:151], 1, v[168:169]
	v_mov_b32_e32 v238, 0x20000
	v_mov_b32_e32 v239, 0
	v_mov_b32_e32 v240, 0xa0000
	v_mov_b32_e32 v241, 0
	v_lshl_add_u64 v[236:237], v[154:155], 0, 0
	global_load_dwordx4 v[170:173], v[236:237], off offset:512
	global_load_dwordx4 v[174:177], v[236:237], off offset:528
	v_lshl_add_u64 v[236:237], v[236:237], 0, v[238:239]
	global_load_dwordx4 v[178:181], v[236:237], off
	global_load_dwordx4 v[182:185], v[236:237], off offset:16
	global_load_dwordx4 v[186:189], v[236:237], off offset:512
	global_load_dwordx4 v[190:193], v[236:237], off offset:528
	v_lshl_add_u64 v[236:237], v[236:237], 0, v[238:239]
	global_load_dwordx4 v[194:197], v[236:237], off
	global_load_dwordx4 v[198:201], v[236:237], off offset:16
	global_load_dwordx4 v[202:205], v[236:237], off offset:512
	global_load_dwordx4 v[206:209], v[236:237], off offset:528
	v_lshl_add_u64 v[236:237], v[236:237], 0, v[238:239]
	global_load_dwordx4 v[210:213], v[236:237], off
	global_load_dwordx4 v[214:217], v[236:237], off offset:16
	global_load_dwordx4 v[218:221], v[236:237], off offset:512
	global_load_dwordx4 v[222:225], v[236:237], off offset:528
	s_waitcnt vmcnt(14)
	v_pk_add_f32 v[124:125], v[124:125], v[160:161]
	v_pk_add_f32 v[160:161], v[122:123], v[166:167]
	v_pk_add_f32 v[122:123], v[120:121], v[164:165]
	v_pk_add_f32 v[126:127], v[126:127], v[162:163]
	v_cvt_pk_bf16_f32 v120, v124, v125
	s_nop 0
	v_cvt_pk_bf16_f32 v121, v126, v127
	v_cvt_pk_bf16_f32 v122, v122, v123
	v_cvt_pk_bf16_f32 v123, v160, v161
	global_store_dwordx4 v[168:169], v[120:123], off
	s_nop 0
	v_or_b32_e32 v120, 16, v152
	v_cmp_lt_i32_e32 vcc, s51, v120
	v_lshl_add_u64 v[236:237], v[236:237], 0, v[240:241]
	global_load_dwordx4 v[226:229], v[236:237], off
	global_load_dwordx4 v[230:233], v[236:237], off offset:16
	s_waitcnt vmcnt(15)
; __device__ __forceinline__ uint4 pk8(f32x4 a, f32x4 b) { return make_uint4(cvt_pk_bf16(a[0], a[1]), cvt_pk_bf16(a[2], a[3]), cvt_pk_bf16(b[0], b[1]), cvt_pk_bf16(b[2], b[3])); }
;     __device__ __forceinline__ void operator()(AccRef acc, const Unit& u, int wr, int wc, int fr, int fq) const {
;     ...
;         for (int ai = 0; ai < 2; ++ai)
; #pragma unroll
;             for (int m = 0; m < 4; ++m) {
;                 const int r = u.pm * 256 + ai * 128 + wr * 64 + m * 16 + fr;
;                 const float* xrow = r < TP ? xp + (size_t)r * D : xs + (size_t)(r - TP) * D;
;                 float ss = 0.f;
; #pragma unroll
;                 for (int bj = 0; bj < 2; ++bj) {
;                     const int c = c0 + bj * 128;
;                     const f32x4 v0 = *(const f32x4*)(xrow + c) + acc[ai][bj][m][0], v1 = *(const f32x4*)(xrow + c + 4) + acc[ai][bj][m][1];
;                     ss += v0[0] * v0[0] + v0[1] * v0[1] + v0[2] * v0[2] + v0[3] * v0[3] + v1[0] * v1[0] + v1[1] * v1[1] + v1[2] * v1[2] + v1[3] * v1[3];
;                     *(uint4*)(Hb + (size_t)r * D + c) = pk8(v0, v1);
;                 }
	v_pk_add_f32 v[118:119], v[118:119], v[172:173]
	v_pk_add_f32 v[116:117], v[116:117], v[170:171]
	v_pk_add_f32 v[122:123], v[114:115], v[176:177]
	v_pk_add_f32 v[114:115], v[112:113], v[174:175]
	v_cvt_pk_bf16_f32 v112, v116, v117
	v_cvt_pk_bf16_f32 v113, v118, v119
	s_nop 0
	v_cvt_pk_bf16_f32 v114, v114, v115
	v_cvt_pk_bf16_f32 v115, v122, v123
	global_store_dwordx4 v[168:169], v[112:115], off offset:256
	s_and_saveexec_b64 s[14:15], vcc
	s_xor_b64 s[14:15], exec, s[14:15]
	v_add_u32_e32 v136, 0xffffc010, v152
	v_lshlrev_b64 v[112:113], 13, v[136:137]
	v_lshl_add_u64 v[112:113], s[54:55], 0, v[112:113]
	v_mov_b32_e32 v121, v137
	s_andn2_saveexec_b64 s[14:15], s[14:15]
	v_ashrrev_i32_e32 v121, 31, v120
	v_lshlrev_b64 v[112:113], 13, v[120:121]
	v_lshl_add_u64 v[112:113], s[52:53], 0, v[112:113]
	s_or_b64 exec, exec, s[14:15]
	v_lshl_add_u64 v[122:123], v[150:151], 2, v[112:113]
	v_lshlrev_b64 v[120:121], 12, v[120:121]
	v_lshl_add_u64 v[120:121], s[34:35], 0, v[120:121]
	v_lshl_add_u64 v[120:121], v[150:151], 1, v[120:121]
	global_load_dwordx4 v[170:173], v[236:237], off offset:512
	global_load_dwordx4 v[174:177], v[236:237], off offset:528
	s_waitcnt vmcnt(16)
	v_pk_add_f32 v[108:109], v[108:109], v[178:179]
	v_pk_add_f32 v[112:113], v[106:107], v[184:185]
	v_pk_add_f32 v[106:107], v[104:105], v[182:183]
	v_pk_add_f32 v[110:111], v[110:111], v[180:181]
	v_cvt_pk_bf16_f32 v104, v108, v109
	s_nop 0
	v_cvt_pk_bf16_f32 v105, v110, v111
	v_cvt_pk_bf16_f32 v106, v106, v107
	v_cvt_pk_bf16_f32 v107, v112, v113
	global_store_dwordx4 v[120:121], v[104:107], off
	s_nop 0
	v_or_b32_e32 v104, 32, v152
	v_cmp_lt_i32_e32 vcc, s51, v104
	v_lshl_add_u64 v[236:237], v[236:237], 0, v[238:239]
	global_load_dwordx4 v[178:181], v[236:237], off
	global_load_dwordx4 v[182:185], v[236:237], off offset:16
	s_waitcnt vmcnt(17)
	v_pk_add_f32 v[102:103], v[102:103], v[188:189]
	v_pk_add_f32 v[100:101], v[100:101], v[186:187]
	v_pk_add_f32 v[106:107], v[98:99], v[192:193]
	v_pk_add_f32 v[98:99], v[96:97], v[190:191]
	v_cvt_pk_bf16_f32 v96, v100, v101
	v_cvt_pk_bf16_f32 v97, v102, v103
	s_nop 0
	v_cvt_pk_bf16_f32 v98, v98, v99
	v_cvt_pk_bf16_f32 v99, v106, v107
	global_store_dwordx4 v[120:121], v[96:99], off offset:256
	s_and_saveexec_b64 s[14:15], vcc
	s_xor_b64 s[14:15], exec, s[14:15]
	v_add_u32_e32 v136, 0xffffc020, v152
	v_lshlrev_b64 v[96:97], 13, v[136:137]
	v_lshl_add_u64 v[96:97], s[54:55], 0, v[96:97]
	v_mov_b32_e32 v105, v137
	s_andn2_saveexec_b64 s[14:15], s[14:15]
	v_ashrrev_i32_e32 v105, 31, v104
	v_lshlrev_b64 v[96:97], 13, v[104:105]
	v_lshl_add_u64 v[96:97], s[52:53], 0, v[96:97]
	s_or_b64 exec, exec, s[14:15]
	v_lshl_add_u64 v[106:107], v[150:151], 2, v[96:97]
	v_lshlrev_b64 v[104:105], 12, v[104:105]
	v_lshl_add_u64 v[104:105], s[34:35], 0, v[104:105]
	v_lshl_add_u64 v[104:105], v[150:151], 1, v[104:105]
	global_load_dwordx4 v[186:189], v[236:237], off offset:512
	global_load_dwordx4 v[190:193], v[236:237], off offset:528
	s_waitcnt vmcnt(18)
	v_pk_add_f32 v[92:93], v[92:93], v[194:195]
	v_pk_add_f32 v[96:97], v[90:91], v[200:201]
	v_pk_add_f32 v[90:91], v[88:89], v[198:199]
	v_pk_add_f32 v[94:95], v[94:95], v[196:197]
	v_cvt_pk_bf16_f32 v88, v92, v93
	s_nop 0
	v_cvt_pk_bf16_f32 v89, v94, v95
	v_cvt_pk_bf16_f32 v90, v90, v91
	v_cvt_pk_bf16_f32 v91, v96, v97
	global_store_dwordx4 v[104:105], v[88:91], off
	s_nop 0
	v_or_b32_e32 v88, 48, v152
	v_cmp_lt_i32_e32 vcc, s51, v88
	v_lshl_add_u64 v[236:237], v[236:237], 0, v[238:239]
	global_load_dwordx4 v[194:197], v[236:237], off
	global_load_dwordx4 v[198:201], v[236:237], off offset:16
	s_waitcnt vmcnt(19)
	v_pk_add_f32 v[86:87], v[86:87], v[204:205]
	v_pk_add_f32 v[84:85], v[84:85], v[202:203]
	v_pk_add_f32 v[90:91], v[82:83], v[208:209]
	v_pk_add_f32 v[82:83], v[80:81], v[206:207]
	v_cvt_pk_bf16_f32 v80, v84, v85
	v_cvt_pk_bf16_f32 v81, v86, v87
	s_nop 0
	v_cvt_pk_bf16_f32 v82, v82, v83
	v_cvt_pk_bf16_f32 v83, v90, v91
	global_store_dwordx4 v[104:105], v[80:83], off offset:256
	s_and_saveexec_b64 s[14:15], vcc
	s_xor_b64 s[14:15], exec, s[14:15]
	v_add_u32_e32 v136, 0xffffc030, v152
	v_lshlrev_b64 v[80:81], 13, v[136:137]
	v_lshl_add_u64 v[80:81], s[54:55], 0, v[80:81]
	v_mov_b32_e32 v89, v137
	s_andn2_saveexec_b64 s[14:15], s[14:15]
	v_ashrrev_i32_e32 v89, 31, v88
	v_lshlrev_b64 v[80:81], 13, v[88:89]
	v_lshl_add_u64 v[80:81], s[52:53], 0, v[80:81]
	s_or_b64 exec, exec, s[14:15]
	v_lshl_add_u64 v[90:91], v[150:151], 2, v[80:81]
	v_lshlrev_b64 v[88:89], 12, v[88:89]
	v_lshl_add_u64 v[88:89], s[34:35], 0, v[88:89]
	v_lshl_add_u64 v[88:89], v[150:151], 1, v[88:89]
	global_load_dwordx4 v[202:205], v[236:237], off offset:512
	global_load_dwordx4 v[206:209], v[236:237], off offset:528
	s_waitcnt vmcnt(20)
	v_pk_add_f32 v[76:77], v[76:77], v[210:211]
	v_pk_add_f32 v[80:81], v[74:75], v[216:217]
	v_pk_add_f32 v[74:75], v[72:73], v[214:215]
	v_pk_add_f32 v[78:79], v[78:79], v[212:213]
	v_cvt_pk_bf16_f32 v72, v76, v77
	s_nop 0
	v_cvt_pk_bf16_f32 v73, v78, v79
	v_cvt_pk_bf16_f32 v74, v74, v75
	v_cvt_pk_bf16_f32 v75, v80, v81
	global_store_dwordx4 v[88:89], v[72:75], off
	s_nop 0
	v_add_u32_e32 v72, 0x80, v152
	v_cmp_lt_i32_e32 vcc, s51, v72
	s_waitcnt vmcnt(19)
; __device__ __forceinline__ uint4 pk8(f32x4 a, f32x4 b) { return make_uint4(cvt_pk_bf16(a[0], a[1]), cvt_pk_bf16(a[2], a[3]), cvt_pk_bf16(b[0], b[1]), cvt_pk_bf16(b[2], b[3])); }
;     __device__ __forceinline__ void operator()(AccRef acc, const Unit& u, int wr, int wc, int fr, int fq) const {
;     ...
;         for (int ai = 0; ai < 2; ++ai)
; #pragma unroll
;             for (int m = 0; m < 4; ++m) {
;                 const int r = u.pm * 256 + ai * 128 + wr * 64 + m * 16 + fr;
;                 const float* xrow = r < TP ? xp + (size_t)r * D : xs + (size_t)(r - TP) * D;
;                 float ss = 0.f;
; #pragma unroll
;                 for (int bj = 0; bj < 2; ++bj) {
;                     const int c = c0 + bj * 128;
;                     const f32x4 v0 = *(const f32x4*)(xrow + c) + acc[ai][bj][m][0], v1 = *(const f32x4*)(xrow + c + 4) + acc[ai][bj][m][1];
;                     ss += v0[0] * v0[0] + v0[1] * v0[1] + v0[2] * v0[2] + v0[3] * v0[3] + v1[0] * v1[0] + v1[1] * v1[1] + v1[2] * v1[2] + v1[3] * v1[3];
;                     *(uint4*)(Hb + (size_t)r * D + c) = pk8(v0, v1);
;                 }
	v_pk_add_f32 v[70:71], v[70:71], v[220:221]
	v_pk_add_f32 v[68:69], v[68:69], v[218:219]
	v_pk_add_f32 v[74:75], v[66:67], v[224:225]
	v_pk_add_f32 v[66:67], v[64:65], v[222:223]
	v_cvt_pk_bf16_f32 v64, v68, v69
	v_cvt_pk_bf16_f32 v65, v70, v71
	s_nop 0
	v_cvt_pk_bf16_f32 v66, v66, v67
	v_cvt_pk_bf16_f32 v67, v74, v75
	global_store_dwordx4 v[88:89], v[64:67], off offset:256
	s_and_saveexec_b64 s[14:15], vcc
	s_xor_b64 s[14:15], exec, s[14:15]
	v_add_u32_e32 v136, 0xffffc080, v152
	v_lshlrev_b64 v[64:65], 13, v[136:137]
	v_lshl_add_u64 v[64:65], s[54:55], 0, v[64:65]
	v_mov_b32_e32 v73, v137
	s_andn2_saveexec_b64 s[14:15], s[14:15]
	v_ashrrev_i32_e32 v73, 31, v72
	v_lshlrev_b64 v[64:65], 13, v[72:73]
	v_lshl_add_u64 v[64:65], s[52:53], 0, v[64:65]
	s_or_b64 exec, exec, s[14:15]
	v_lshl_add_u64 v[74:75], v[150:151], 2, v[64:65]
	v_lshlrev_b64 v[72:73], 12, v[72:73]
	v_lshl_add_u64 v[72:73], s[34:35], 0, v[72:73]
	v_lshl_add_u64 v[72:73], v[150:151], 1, v[72:73]
	s_waitcnt vmcnt(17)
	v_pk_add_f32 v[60:61], v[60:61], v[226:227]
	v_pk_add_f32 v[64:65], v[58:59], v[232:233]
	v_pk_add_f32 v[58:59], v[56:57], v[230:231]
	v_pk_add_f32 v[62:63], v[62:63], v[228:229]
	v_cvt_pk_bf16_f32 v56, v60, v61
	s_nop 0
	v_cvt_pk_bf16_f32 v57, v62, v63
	v_cvt_pk_bf16_f32 v58, v58, v59
	v_cvt_pk_bf16_f32 v59, v64, v65
	global_store_dwordx4 v[72:73], v[56:59], off
	s_nop 0
	v_add_u32_e32 v56, 0x90, v152
	v_cmp_lt_i32_e32 vcc, s51, v56
	s_waitcnt vmcnt(15)
	v_pk_add_f32 v[54:55], v[54:55], v[172:173]
	v_pk_add_f32 v[52:53], v[52:53], v[170:171]
	v_pk_add_f32 v[58:59], v[50:51], v[176:177]
	v_pk_add_f32 v[50:51], v[48:49], v[174:175]
	v_cvt_pk_bf16_f32 v48, v52, v53
	v_cvt_pk_bf16_f32 v49, v54, v55
	s_nop 0
	v_cvt_pk_bf16_f32 v50, v50, v51
	v_cvt_pk_bf16_f32 v51, v58, v59
	global_store_dwordx4 v[72:73], v[48:51], off offset:256
	s_and_saveexec_b64 s[14:15], vcc
	s_xor_b64 s[14:15], exec, s[14:15]
	v_add_u32_e32 v136, 0xffffc090, v152
	v_lshlrev_b64 v[48:49], 13, v[136:137]
	v_lshl_add_u64 v[48:49], s[54:55], 0, v[48:49]
	v_mov_b32_e32 v57, v137
	s_andn2_saveexec_b64 s[14:15], s[14:15]
	v_ashrrev_i32_e32 v57, 31, v56
	v_lshlrev_b64 v[48:49], 13, v[56:57]
	v_lshl_add_u64 v[48:49], s[52:53], 0, v[48:49]
	s_or_b64 exec, exec, s[14:15]
	v_lshl_add_u64 v[58:59], v[150:151], 2, v[48:49]
	v_lshlrev_b64 v[56:57], 12, v[56:57]
	v_lshl_add_u64 v[56:57], s[34:35], 0, v[56:57]
	v_lshl_add_u64 v[56:57], v[150:151], 1, v[56:57]
	s_waitcnt vmcnt(13)
	v_pk_add_f32 v[44:45], v[44:45], v[178:179]
	v_pk_add_f32 v[48:49], v[42:43], v[184:185]
	v_pk_add_f32 v[42:43], v[40:41], v[182:183]
	v_pk_add_f32 v[46:47], v[46:47], v[180:181]
	v_cvt_pk_bf16_f32 v40, v44, v45
	s_nop 0
	v_cvt_pk_bf16_f32 v41, v46, v47
	v_cvt_pk_bf16_f32 v42, v42, v43
	v_cvt_pk_bf16_f32 v43, v48, v49
	global_store_dwordx4 v[56:57], v[40:43], off
	s_nop 0
	v_add_u32_e32 v40, 0xa0, v152
	v_cmp_lt_i32_e32 vcc, s51, v40
	s_waitcnt vmcnt(11)
	v_pk_add_f32 v[38:39], v[38:39], v[188:189]
	v_pk_add_f32 v[36:37], v[36:37], v[186:187]
	v_pk_add_f32 v[42:43], v[34:35], v[192:193]
	v_pk_add_f32 v[34:35], v[32:33], v[190:191]
	v_cvt_pk_bf16_f32 v32, v36, v37
	v_cvt_pk_bf16_f32 v33, v38, v39
	s_nop 0
	v_cvt_pk_bf16_f32 v34, v34, v35
	v_cvt_pk_bf16_f32 v35, v42, v43
	global_store_dwordx4 v[56:57], v[32:35], off offset:256
	s_and_saveexec_b64 s[14:15], vcc
	s_xor_b64 s[14:15], exec, s[14:15]
	v_add_u32_e32 v136, 0xffffc0a0, v152
	v_lshlrev_b64 v[32:33], 13, v[136:137]
	v_lshl_add_u64 v[32:33], s[54:55], 0, v[32:33]
	v_mov_b32_e32 v41, v137
	s_andn2_saveexec_b64 s[14:15], s[14:15]
	v_ashrrev_i32_e32 v41, 31, v40
	v_lshlrev_b64 v[32:33], 13, v[40:41]
	v_lshl_add_u64 v[32:33], s[52:53], 0, v[32:33]
	s_or_b64 exec, exec, s[14:15]
	v_lshl_add_u64 v[42:43], v[150:151], 2, v[32:33]
	v_lshlrev_b64 v[40:41], 12, v[40:41]
	v_lshl_add_u64 v[40:41], s[34:35], 0, v[40:41]
	v_lshl_add_u64 v[40:41], v[150:151], 1, v[40:41]
	s_waitcnt vmcnt(9)
	v_pk_add_f32 v[28:29], v[28:29], v[194:195]
	v_pk_add_f32 v[32:33], v[26:27], v[200:201]
	v_pk_add_f32 v[26:27], v[24:25], v[198:199]
	v_pk_add_f32 v[30:31], v[30:31], v[196:197]
	v_cvt_pk_bf16_f32 v24, v28, v29
	s_nop 0
	v_cvt_pk_bf16_f32 v25, v30, v31
	v_cvt_pk_bf16_f32 v26, v26, v27
	v_cvt_pk_bf16_f32 v27, v32, v33
	global_store_dwordx4 v[40:41], v[24:27], off
	s_nop 0
	v_add_u32_e32 v24, 0xb0, v152
	v_cmp_lt_i32_e32 vcc, s51, v24
	s_waitcnt vmcnt(7)
	v_pk_add_f32 v[22:23], v[22:23], v[204:205]
	v_pk_add_f32 v[20:21], v[20:21], v[202:203]
	v_pk_add_f32 v[26:27], v[18:19], v[208:209]
	v_pk_add_f32 v[18:19], v[16:17], v[206:207]
	v_cvt_pk_bf16_f32 v16, v20, v21
	v_cvt_pk_bf16_f32 v17, v22, v23
	s_nop 0
	v_cvt_pk_bf16_f32 v18, v18, v19
	v_cvt_pk_bf16_f32 v19, v26, v27
	global_store_dwordx4 v[40:41], v[16:19], off offset:256
	s_and_saveexec_b64 s[14:15], vcc
	s_xor_b64 s[14:15], exec, s[14:15]
	v_add_u32_e32 v136, 0xffffc0b0, v152
	v_lshlrev_b64 v[16:17], 13, v[136:137]
	v_lshl_add_u64 v[16:17], s[54:55], 0, v[16:17]
	v_mov_b32_e32 v25, v137
	s_andn2_saveexec_b64 s[14:15], s[14:15]
	s_cbranch_execz .LBB0_758
	v_ashrrev_i32_e32 v25, 31, v24
	v_lshlrev_b64 v[16:17], 13, v[24:25]
	v_lshl_add_u64 v[16:17], s[52:53], 0, v[16:17]
	s_branch .LBB0_758

; #define PG8_STAGE(bufoff, gbase, voff) do { _Pragma("unroll") for (int _i = 0; _i < 2; ++_i) \
;         __builtin_amdgcn_global_load_lds((const unsigned*)((const char*)(gbase) + (voff)[_i]), (PG8_LAS unsigned*)(lds + (bufoff) + ldsw + _i * 8192), 16, 0, 0); } while (0)
; #define PG8_LDA(dst, b, h) do { _Pragma("unroll") for (int m = 0; m < 4; ++m) _Pragma("unroll") for (int k = 0; k < 2; ++k) dst[m][k] = *(const PG8_LAS bf16x8*)(lds + PG8_SA(b, h) + aoff + m * 2048 + k * 1024); } while (0)
; #define PG8_LDB(dst, b, h) do { _Pragma("unroll") for (int n = 0; n < 2; ++n) _Pragma("unroll") for (int k = 0; k < 2; ++k) dst[n][k] = *(const PG8_LAS bf16x8*)(lds + PG8_SB(b, h) + boff + n * 2048 + k * 1024); } while (0)
; #define PG8_MMA(ai, bj, At, Bt) do { __builtin_amdgcn_s_setprio(1); _Pragma("unroll") for (int m = 0; m < 4; ++m) _Pragma("unroll") for (int n = 0; n < 2; ++n) _Pragma("unroll") for (int k = 0; k < 2; ++k) \
;         acc[ai][bj][m][n] = __builtin_amdgcn_mfma_f32_16x16x32_bf16(Bt[n][k], At[m][k], acc[ai][bj][m][n], 0, 0, 0); __builtin_amdgcn_s_setprio(0); } while (0)
; #define PG8_WAIT_V(n) asm volatile("s_waitcnt vmcnt(" #n ")" ::: "memory")
; #define PG8_WAIT_L(n) asm volatile("s_waitcnt lgkmcnt(" #n ")" ::: "memory")
; #define PG8_BAR __builtin_amdgcn_s_barrier()
; #define PG8_SCHED __builtin_amdgcn_sched_barrier(0)
; template <class Epi, class Sched>
; __device__ __forceinline__ void gemm_phase(PG8_LAS unsigned char* lds, const Gemm g, const Sched& S, const Epi& E) {
;     ...
;             PG8_LDB(B0, 0, 0); PG8_SCHED; PG8_LDA(At, 0, 0); PG8_STAGE(PG8_SA(1, 1), a1 + hstep, voffA);
;             PG8_WAIT_L(8); PG8_BAR; PG8_WAIT_L(0); PG8_MMA(0, 0, At, B0); PG8_BAR; PG8_SCHED;
;             PG8_LDB(B1, 0, 1); PG8_STAGE(PG8_SB(0, 0), b2, voffB);
;             PG8_BAR; PG8_WAIT_L(0); PG8_MMA(0, 1, At, B1); PG8_BAR;
;             PG8_LDA(At, 0, 1); PG8_STAGE(PG8_SA(0, 0), a2, voffA);
;             PG8_BAR; PG8_WAIT_L(0); PG8_MMA(1, 0, At, B0); PG8_BAR; PG8_SCHED;
;             PG8_STAGE(PG8_SB(0, 1), b2 + hstep, voffB);
;             PG8_WAIT_V(6); PG8_BAR; PG8_MMA(1, 1, At, B1); PG8_BAR;
;             PG8_LDB(B0, 1, 0); PG8_SCHED; PG8_LDA(At, 1, 0); PG8_STAGE(PG8_SA(0, 1), a2 + hstep, voffA);
;             PG8_WAIT_L(8); PG8_BAR; PG8_WAIT_L(0); PG8_MMA(0, 0, At, B0); PG8_BAR; PG8_SCHED;
.LBB0_1059:
	ds_read_b128 v[148:151], v153
	ds_read_b128 v[156:159], v153 offset:1024
	ds_read_b128 v[160:163], v153 offset:2048
	ds_read_b128 v[164:167], v153 offset:3072
	s_add_u32 s18, s16, 0xfff80080
	s_addc_u32 s19, s17, -1
	s_cmp_eq_u32 s53, 28
	s_cselect_b32 s21, s9, s19
	s_cselect_b32 s20, s49, s18
	s_cselect_b32 s19, s7, s52
	s_cselect_b32 s18, s50, s51
	v_lshl_add_u64 v[200:201], s[16:17], 0, v[136:137]
	s_add_i32 m0, s15, 0xc000
	ds_read_b128 v[168:171], v154
	ds_read_b128 v[172:175], v154 offset:1024
	ds_read_b128 v[176:179], v154 offset:2048
	ds_read_b128 v[180:183], v154 offset:3072
	ds_read_b128 v[184:187], v154 offset:4096
	ds_read_b128 v[188:191], v154 offset:5120
	ds_read_b128 v[192:195], v154 offset:6144
	ds_read_b128 v[196:199], v154 offset:7168
	global_load_lds_dwordx4 v[200:201], off
	v_lshl_add_u64 v[200:201], s[16:17], 0, v[138:139]
	s_add_i32 m0, s15, 0xe000
	s_nop 0
	global_load_lds_dwordx4 v[200:201], off
	s_waitcnt lgkmcnt(8)
	s_barrier
	s_waitcnt lgkmcnt(0)
	s_setprio 1
	s_waitcnt lgkmcnt(0)
	v_mfma_f32_16x16x32_bf16 v[124:127], v[148:151], v[168:171], v[124:127]
	v_mfma_f32_16x16x32_bf16 v[120:123], v[160:163], v[168:171], v[120:123]
	v_mfma_f32_16x16x32_bf16 v[108:111], v[148:151], v[176:179], v[108:111]
	v_mfma_f32_16x16x32_bf16 v[104:107], v[160:163], v[176:179], v[104:107]
	v_mfma_f32_16x16x32_bf16 v[92:95], v[148:151], v[184:187], v[92:95]
	v_mfma_f32_16x16x32_bf16 v[88:91], v[160:163], v[184:187], v[88:91]
	v_mfma_f32_16x16x32_bf16 v[76:79], v[148:151], v[192:195], v[76:79]
	v_mfma_f32_16x16x32_bf16 v[72:75], v[160:163], v[192:195], v[72:75]
	v_mfma_f32_16x16x32_bf16 v[124:127], v[156:159], v[172:175], v[124:127]
	v_mfma_f32_16x16x32_bf16 v[120:123], v[164:167], v[172:175], v[120:123]
	v_mfma_f32_16x16x32_bf16 v[108:111], v[156:159], v[180:183], v[108:111]
	v_mfma_f32_16x16x32_bf16 v[104:107], v[164:167], v[180:183], v[104:107]
	v_mfma_f32_16x16x32_bf16 v[92:95], v[156:159], v[188:191], v[92:95]
	v_mfma_f32_16x16x32_bf16 v[88:91], v[164:167], v[188:191], v[88:91]
	v_mfma_f32_16x16x32_bf16 v[76:79], v[156:159], v[196:199], v[76:79]
	v_mfma_f32_16x16x32_bf16 v[72:75], v[164:167], v[196:199], v[72:75]
	s_setprio 0
	s_barrier
	s_add_i32 s30, s46, s25
	v_lshl_add_u64 v[216:217], s[18:19], 0, v[130:131]
	s_mov_b32 m0, s30
	ds_read_b128 v[200:203], v155
	ds_read_b128 v[204:207], v155 offset:1024
	ds_read_b128 v[208:211], v155 offset:2048
	ds_read_b128 v[212:215], v155 offset:3072
	global_load_lds_dwordx4 v[216:217], off
	v_lshl_add_u64 v[218:219], s[18:19], 0, v[134:135]
	s_add_i32 m0, s30, 0x2000
	s_nop 0
	global_load_lds_dwordx4 v[218:219], off
	s_barrier
	s_waitcnt lgkmcnt(0)
	s_setprio 1
	s_waitcnt lgkmcnt(0)
	v_mfma_f32_16x16x32_bf16 v[116:119], v[200:203], v[168:171], v[116:119]
	v_mfma_f32_16x16x32_bf16 v[112:115], v[208:211], v[168:171], v[112:115]
	v_mfma_f32_16x16x32_bf16 v[100:103], v[200:203], v[176:179], v[100:103]
	v_mfma_f32_16x16x32_bf16 v[96:99], v[208:211], v[176:179], v[96:99]
	v_mfma_f32_16x16x32_bf16 v[84:87], v[200:203], v[184:187], v[84:87]
	v_mfma_f32_16x16x32_bf16 v[80:83], v[208:211], v[184:187], v[80:83]
	v_mfma_f32_16x16x32_bf16 v[68:71], v[200:203], v[192:195], v[68:71]
	v_mfma_f32_16x16x32_bf16 v[64:67], v[208:211], v[192:195], v[64:67]
	v_mfma_f32_16x16x32_bf16 v[116:119], v[204:207], v[172:175], v[116:119]
	v_mfma_f32_16x16x32_bf16 v[112:115], v[212:215], v[172:175], v[112:115]
	v_mfma_f32_16x16x32_bf16 v[100:103], v[204:207], v[180:183], v[100:103]
	v_mfma_f32_16x16x32_bf16 v[96:99], v[212:215], v[180:183], v[96:99]
	v_mfma_f32_16x16x32_bf16 v[84:87], v[204:207], v[188:191], v[84:87]
	v_mfma_f32_16x16x32_bf16 v[80:83], v[212:215], v[188:191], v[80:83]
	v_mfma_f32_16x16x32_bf16 v[68:71], v[204:207], v[196:199], v[68:71]
	v_mfma_f32_16x16x32_bf16 v[64:67], v[212:215], v[196:199], v[64:67]
	s_setprio 0
	s_mov_b32 m0, s15
	v_lshl_add_u64 v[220:221], s[20:21], 0, v[128:129]
	s_barrier
	ds_read_b128 v[168:171], v154 offset:16384
	ds_read_b128 v[172:175], v154 offset:17408
	ds_read_b128 v[176:179], v154 offset:18432
	ds_read_b128 v[180:183], v154 offset:19456
	ds_read_b128 v[184:187], v154 offset:20480
	ds_read_b128 v[188:191], v154 offset:21504
	ds_read_b128 v[192:195], v154 offset:22528
	ds_read_b128 v[196:199], v154 offset:23552
	global_load_lds_dwordx4 v[220:221], off
	v_lshl_add_u64 v[222:223], s[20:21], 0, v[132:133]
	s_mov_b32 m0, s28
	s_nop 0
	global_load_lds_dwordx4 v[222:223], off
	s_barrier
	s_waitcnt lgkmcnt(0)
	s_setprio 1
	s_waitcnt lgkmcnt(0)
	v_mfma_f32_16x16x32_bf16 v[60:63], v[148:151], v[168:171], v[60:63]
	v_mfma_f32_16x16x32_bf16 v[56:59], v[160:163], v[168:171], v[56:59]
	v_mfma_f32_16x16x32_bf16 v[44:47], v[148:151], v[176:179], v[44:47]
	v_mfma_f32_16x16x32_bf16 v[40:43], v[160:163], v[176:179], v[40:43]
	v_mfma_f32_16x16x32_bf16 v[28:31], v[148:151], v[184:187], v[28:31]
	v_mfma_f32_16x16x32_bf16 v[24:27], v[160:163], v[184:187], v[24:27]
	v_mfma_f32_16x16x32_bf16 v[12:15], v[148:151], v[192:195], v[12:15]
	v_mfma_f32_16x16x32_bf16 v[8:11], v[160:163], v[192:195], v[8:11]
	v_mfma_f32_16x16x32_bf16 v[60:63], v[156:159], v[172:175], v[60:63]
	v_mfma_f32_16x16x32_bf16 v[56:59], v[164:167], v[172:175], v[56:59]
	v_mfma_f32_16x16x32_bf16 v[44:47], v[156:159], v[180:183], v[44:47]
	v_mfma_f32_16x16x32_bf16 v[40:43], v[164:167], v[180:183], v[40:43]
	v_mfma_f32_16x16x32_bf16 v[28:31], v[156:159], v[188:191], v[28:31]
	v_mfma_f32_16x16x32_bf16 v[24:27], v[164:167], v[188:191], v[24:27]
	v_mfma_f32_16x16x32_bf16 v[12:15], v[156:159], v[196:199], v[12:15]
	v_mfma_f32_16x16x32_bf16 v[8:11], v[164:167], v[196:199], v[8:11]
	s_setprio 0
	s_barrier
; #define PG8_STAGE(bufoff, gbase, voff) do { _Pragma("unroll") for (int _i = 0; _i < 2; ++_i) \
;         __builtin_amdgcn_global_load_lds((const unsigned*)((const char*)(gbase) + (voff)[_i]), (PG8_LAS unsigned*)(lds + (bufoff) + ldsw + _i * 8192), 16, 0, 0); } while (0)
; #define PG8_LDA(dst, b, h) do { _Pragma("unroll") for (int m = 0; m < 4; ++m) _Pragma("unroll") for (int k = 0; k < 2; ++k) dst[m][k] = *(const PG8_LAS bf16x8*)(lds + PG8_SA(b, h) + aoff + m * 2048 + k * 1024); } while (0)
; #define PG8_LDB(dst, b, h) do { _Pragma("unroll") for (int n = 0; n < 2; ++n) _Pragma("unroll") for (int k = 0; k < 2; ++k) dst[n][k] = *(const PG8_LAS bf16x8*)(lds + PG8_SB(b, h) + boff + n * 2048 + k * 1024); } while (0)
; #define PG8_MMA(ai, bj, At, Bt) do { __builtin_amdgcn_s_setprio(1); _Pragma("unroll") for (int m = 0; m < 4; ++m) _Pragma("unroll") for (int n = 0; n < 2; ++n) _Pragma("unroll") for (int k = 0; k < 2; ++k) \
;         acc[ai][bj][m][n] = __builtin_amdgcn_mfma_f32_16x16x32_bf16(Bt[n][k], At[m][k], acc[ai][bj][m][n], 0, 0, 0); __builtin_amdgcn_s_setprio(0); } while (0)
; #define PG8_WAIT_V(n) asm volatile("s_waitcnt vmcnt(" #n ")" ::: "memory")
; #define PG8_WAIT_L(n) asm volatile("s_waitcnt lgkmcnt(" #n ")" ::: "memory")
; #define PG8_BAR __builtin_amdgcn_s_barrier()
; #define PG8_SCHED __builtin_amdgcn_sched_barrier(0)
; template <class Epi, class Sched>
; __device__ __forceinline__ void gemm_phase(PG8_LAS unsigned char* lds, const Gemm g, const Sched& S, const Epi& E) {
;     ...
;             PG8_STAGE(PG8_SB(0, 1), b2 + hstep, voffB);
;             PG8_WAIT_V(6); PG8_BAR; PG8_MMA(1, 1, At, B1); PG8_BAR;
;             PG8_LDB(B0, 1, 0); PG8_SCHED; PG8_LDA(At, 1, 0); PG8_STAGE(PG8_SA(0, 1), a2 + hstep, voffA);
;             PG8_WAIT_L(8); PG8_BAR; PG8_WAIT_L(0); PG8_MMA(0, 0, At, B0); PG8_BAR; PG8_SCHED;
;             PG8_LDB(B1, 1, 1); PG8_STAGE(PG8_SB(1, 0), b3, voffB);
;             PG8_BAR; PG8_WAIT_L(0); PG8_MMA(0, 1, At, B1); PG8_BAR;
;             PG8_LDA(At, 1, 1); PG8_STAGE(PG8_SA(1, 0), a3, voffA);
;             PG8_BAR; PG8_WAIT_L(0); PG8_MMA(1, 0, At, B0); PG8_BAR; PG8_SCHED;
	s_add_u32 s30, s18, 0x80000
	s_addc_u32 s31, s19, 0
	s_add_i32 s54, s47, s25
	v_lshl_add_u64 v[148:149], s[30:31], 0, v[130:131]
	s_mov_b32 m0, s54
	s_nop 0
	global_load_lds_dwordx4 v[148:149], off
	v_lshl_add_u64 v[148:149], s[30:31], 0, v[134:135]
	s_add_i32 m0, s54, 0x2000
	s_nop 0
	global_load_lds_dwordx4 v[148:149], off
	s_waitcnt vmcnt(6)
	s_barrier
	s_setprio 1
	v_mfma_f32_16x16x32_bf16 v[52:55], v[200:203], v[168:171], v[52:55]
	v_mfma_f32_16x16x32_bf16 v[48:51], v[208:211], v[168:171], v[48:51]
	v_mfma_f32_16x16x32_bf16 v[36:39], v[200:203], v[176:179], v[36:39]
	v_mfma_f32_16x16x32_bf16 v[32:35], v[208:211], v[176:179], v[32:35]
	v_mfma_f32_16x16x32_bf16 v[20:23], v[200:203], v[184:187], v[20:23]
	v_mfma_f32_16x16x32_bf16 v[16:19], v[208:211], v[184:187], v[16:19]
	v_mfma_f32_16x16x32_bf16 v[4:7], v[200:203], v[192:195], v[4:7]
	v_mfma_f32_16x16x32_bf16 v[0:3], v[208:211], v[192:195], v[0:3]
	v_mfma_f32_16x16x32_bf16 v[52:55], v[204:207], v[172:175], v[52:55]
	v_mfma_f32_16x16x32_bf16 v[48:51], v[212:215], v[172:175], v[48:51]
	v_mfma_f32_16x16x32_bf16 v[36:39], v[204:207], v[180:183], v[36:39]
	v_mfma_f32_16x16x32_bf16 v[32:35], v[212:215], v[180:183], v[32:35]
	v_mfma_f32_16x16x32_bf16 v[20:23], v[204:207], v[188:191], v[20:23]
	v_mfma_f32_16x16x32_bf16 v[16:19], v[212:215], v[188:191], v[16:19]
	v_mfma_f32_16x16x32_bf16 v[4:7], v[204:207], v[196:199], v[4:7]
	v_mfma_f32_16x16x32_bf16 v[0:3], v[212:215], v[196:199], v[0:3]
	s_setprio 0
	s_add_i32 s30, 0, 0x18000
	v_add_u32_e32 v164, s30, v147
	s_barrier
	ds_read_b128 v[148:151], v164
	ds_read_b128 v[156:159], v164 offset:1024
	ds_read_b128 v[160:163], v164 offset:2048
	ds_read_b128 v[164:167], v164 offset:3072
	s_add_u32 s20, s20, 0x80000
	s_addc_u32 s21, s21, 0
	s_mov_b32 m0, s29
	v_lshl_add_u64 v[200:201], s[20:21], 0, v[128:129]
	ds_read_b128 v[168:171], v154 offset:32768
	ds_read_b128 v[172:175], v154 offset:33792
	ds_read_b128 v[176:179], v154 offset:34816
	ds_read_b128 v[180:183], v154 offset:35840
	ds_read_b128 v[184:187], v154 offset:36864
	ds_read_b128 v[188:191], v154 offset:37888
	ds_read_b128 v[192:195], v154 offset:38912
	ds_read_b128 v[196:199], v154 offset:39936
	global_load_lds_dwordx4 v[200:201], off
	v_lshl_add_u64 v[200:201], s[20:21], 0, v[132:133]
	s_mov_b32 m0, s38
	s_nop 0
	global_load_lds_dwordx4 v[200:201], off
	s_waitcnt lgkmcnt(8)
	s_barrier
	s_waitcnt lgkmcnt(0)
	s_setprio 1
	s_waitcnt lgkmcnt(0)
	v_mfma_f32_16x16x32_bf16 v[124:127], v[148:151], v[168:171], v[124:127]
	v_mfma_f32_16x16x32_bf16 v[120:123], v[160:163], v[168:171], v[120:123]
	v_mfma_f32_16x16x32_bf16 v[108:111], v[148:151], v[176:179], v[108:111]
	v_mfma_f32_16x16x32_bf16 v[104:107], v[160:163], v[176:179], v[104:107]
	v_mfma_f32_16x16x32_bf16 v[92:95], v[148:151], v[184:187], v[92:95]
	v_mfma_f32_16x16x32_bf16 v[88:91], v[160:163], v[184:187], v[88:91]
	v_mfma_f32_16x16x32_bf16 v[76:79], v[148:151], v[192:195], v[76:79]
	v_mfma_f32_16x16x32_bf16 v[72:75], v[160:163], v[192:195], v[72:75]
	v_mfma_f32_16x16x32_bf16 v[124:127], v[156:159], v[172:175], v[124:127]
	v_mfma_f32_16x16x32_bf16 v[120:123], v[164:167], v[172:175], v[120:123]
	v_mfma_f32_16x16x32_bf16 v[108:111], v[156:159], v[180:183], v[108:111]
	v_mfma_f32_16x16x32_bf16 v[104:107], v[164:167], v[180:183], v[104:107]
	v_mfma_f32_16x16x32_bf16 v[92:95], v[156:159], v[188:191], v[92:95]
	v_mfma_f32_16x16x32_bf16 v[88:91], v[164:167], v[188:191], v[88:91]
	v_mfma_f32_16x16x32_bf16 v[76:79], v[156:159], v[196:199], v[76:79]
	v_mfma_f32_16x16x32_bf16 v[72:75], v[164:167], v[196:199], v[72:75]
	s_setprio 0
	s_barrier
	s_add_i32 s20, 0, 0x1c000
	s_add_i32 s21, s30, s25
	v_add_u32_e32 v212, s20, v147
	v_lshl_add_u64 v[216:217], v[216:217], 0, s[0:1]
	s_mov_b32 m0, s21
	ds_read_b128 v[200:203], v212
	ds_read_b128 v[204:207], v212 offset:1024
	ds_read_b128 v[208:211], v212 offset:2048
	ds_read_b128 v[212:215], v212 offset:3072
	global_load_lds_dwordx4 v[216:217], off
	v_lshl_add_u64 v[216:217], v[218:219], 0, s[0:1]
	s_add_i32 m0, s21, 0x2000
	s_nop 0
	global_load_lds_dwordx4 v[216:217], off
	s_barrier
	s_waitcnt lgkmcnt(0)
	s_setprio 1
	s_waitcnt lgkmcnt(0)
	v_mfma_f32_16x16x32_bf16 v[116:119], v[200:203], v[168:171], v[116:119]
	v_mfma_f32_16x16x32_bf16 v[112:115], v[208:211], v[168:171], v[112:115]
	v_mfma_f32_16x16x32_bf16 v[100:103], v[200:203], v[176:179], v[100:103]
	v_mfma_f32_16x16x32_bf16 v[96:99], v[208:211], v[176:179], v[96:99]
	v_mfma_f32_16x16x32_bf16 v[84:87], v[200:203], v[184:187], v[84:87]
	v_mfma_f32_16x16x32_bf16 v[80:83], v[208:211], v[184:187], v[80:83]
	v_mfma_f32_16x16x32_bf16 v[68:71], v[200:203], v[192:195], v[68:71]
	v_mfma_f32_16x16x32_bf16 v[64:67], v[208:211], v[192:195], v[64:67]
	v_mfma_f32_16x16x32_bf16 v[116:119], v[204:207], v[172:175], v[116:119]
	v_mfma_f32_16x16x32_bf16 v[112:115], v[212:215], v[172:175], v[112:115]
	v_mfma_f32_16x16x32_bf16 v[100:103], v[204:207], v[180:183], v[100:103]
	v_mfma_f32_16x16x32_bf16 v[96:99], v[212:215], v[180:183], v[96:99]
	v_mfma_f32_16x16x32_bf16 v[84:87], v[204:207], v[188:191], v[84:87]
	v_mfma_f32_16x16x32_bf16 v[80:83], v[212:215], v[188:191], v[80:83]
	v_mfma_f32_16x16x32_bf16 v[68:71], v[204:207], v[196:199], v[68:71]
	v_mfma_f32_16x16x32_bf16 v[64:67], v[212:215], v[196:199], v[64:67]
	s_setprio 0
	s_mov_b32 m0, s42
	v_lshl_add_u64 v[216:217], v[220:221], 0, s[0:1]
	s_barrier
	ds_read_b128 v[168:171], v154 offset:49152
	ds_read_b128 v[172:175], v154 offset:50176
	ds_read_b128 v[176:179], v154 offset:51200
	ds_read_b128 v[180:183], v154 offset:52224
	ds_read_b128 v[184:187], v154 offset:53248
	ds_read_b128 v[188:191], v154 offset:54272
	ds_read_b128 v[192:195], v154 offset:55296
	ds_read_b128 v[196:199], v154 offset:56320
	global_load_lds_dwordx4 v[216:217], off
	v_lshl_add_u64 v[216:217], v[222:223], 0, s[0:1]
	s_mov_b32 m0, s43
	s_nop 0
	global_load_lds_dwordx4 v[216:217], off
	s_barrier
; #define PG8_STAGE(bufoff, gbase, voff) do { _Pragma("unroll") for (int _i = 0; _i < 2; ++_i) \
;         __builtin_amdgcn_global_load_lds((const unsigned*)((const char*)(gbase) + (voff)[_i]), (PG8_LAS unsigned*)(lds + (bufoff) + ldsw + _i * 8192), 16, 0, 0); } while (0)
; #define PG8_MMA(ai, bj, At, Bt) do { __builtin_amdgcn_s_setprio(1); _Pragma("unroll") for (int m = 0; m < 4; ++m) _Pragma("unroll") for (int n = 0; n < 2; ++n) _Pragma("unroll") for (int k = 0; k < 2; ++k) \
;         acc[ai][bj][m][n] = __builtin_amdgcn_mfma_f32_16x16x32_bf16(Bt[n][k], At[m][k], acc[ai][bj][m][n], 0, 0, 0); __builtin_amdgcn_s_setprio(0); } while (0)
; #define PG8_BAR __builtin_amdgcn_s_barrier()
; template <class Epi, class Sched>
; __device__ __forceinline__ void gemm_phase(PG8_LAS unsigned char* lds, const Gemm g, const Sched& S, const Epi& E) {
;     ...
;             PG8_BAR; PG8_WAIT_L(0); PG8_MMA(1, 0, At, B0); PG8_BAR; PG8_SCHED;
;             PG8_STAGE(PG8_SB(1, 1), b3 + hstep, voffB);
;             PG8_WAIT_V(6); PG8_BAR; PG8_MMA(1, 1, At, B1); PG8_BAR;
;     __device__ __forceinline__ void operator()(AccRef acc, const Unit& u, int wr, int wc, int fr, int fq) const {
;         const int c0 = u.pn * 256 + wc * 32 + 8 * fq;
; #pragma unroll
;         for (int ai = 0; ai < 2; ++ai)
; #pragma unroll
;             for (int m = 0; m < 4; ++m) {
;                 const int r = u.pm * 256 + ai * 128 + wr * 64 + m * 16 + fr;
;                 const float s = rinv[r];
;                 float ss = 0.f;
; #pragma unroll
;                 for (int bj = 0; bj < 2; ++bj) {
;                     const size_t o = (size_t)r * D + c0 + bj * 128;
;                     const uint4 h8 = *(const uint4*)(H2 + o);
;                     f32x4 v0 = unpk4(make_uint2(h8.x, h8.y)), v1 = unpk4(make_uint2(h8.z, h8.w));
;                     const uint4 pp8 = *(const uint4*)(PPb + o);
;                     const f32x4 p0 = unpk4(make_uint2(pp8.x, pp8.y)), p1 = unpk4(make_uint2(pp8.z, pp8.w));
; #pragma unroll
;                     for (int e = 0; e < 4; ++e) { v0[e] += sigm(acc[ai][bj][m][0][e] * s) * p0[e]; v1[e] += sigm(acc[ai][bj][m][1][e] * s) * p1[e]; }
;                     ss += v0[0] * v0[0] + v0[1] * v0[1] + v0[2] * v0[2] + v0[3] * v0[3] + v1[0] * v1[0] + v1[1] * v1[1] + v1[2] * v1[2] + v1[3] * v1[3];
;                     *(uint4*)(H3 + o) = pk8(v0, v1);
;                 }
	s_waitcnt lgkmcnt(0)
	s_setprio 1
	s_waitcnt lgkmcnt(0)
	v_mfma_f32_16x16x32_bf16 v[60:63], v[148:151], v[168:171], v[60:63]
	v_mfma_f32_16x16x32_bf16 v[56:59], v[160:163], v[168:171], v[56:59]
	v_mfma_f32_16x16x32_bf16 v[44:47], v[148:151], v[176:179], v[44:47]
	v_mfma_f32_16x16x32_bf16 v[40:43], v[160:163], v[176:179], v[40:43]
	v_mfma_f32_16x16x32_bf16 v[28:31], v[148:151], v[184:187], v[28:31]
	v_mfma_f32_16x16x32_bf16 v[24:27], v[160:163], v[184:187], v[24:27]
	v_mfma_f32_16x16x32_bf16 v[12:15], v[148:151], v[192:195], v[12:15]
	v_mfma_f32_16x16x32_bf16 v[8:11], v[160:163], v[192:195], v[8:11]
	v_mfma_f32_16x16x32_bf16 v[60:63], v[156:159], v[172:175], v[60:63]
	v_mfma_f32_16x16x32_bf16 v[56:59], v[164:167], v[172:175], v[56:59]
	v_mfma_f32_16x16x32_bf16 v[44:47], v[156:159], v[180:183], v[44:47]
	v_mfma_f32_16x16x32_bf16 v[40:43], v[164:167], v[180:183], v[40:43]
	v_mfma_f32_16x16x32_bf16 v[28:31], v[156:159], v[188:191], v[28:31]
	v_mfma_f32_16x16x32_bf16 v[24:27], v[164:167], v[188:191], v[24:27]
	v_mfma_f32_16x16x32_bf16 v[12:15], v[156:159], v[196:199], v[12:15]
	v_mfma_f32_16x16x32_bf16 v[8:11], v[164:167], v[196:199], v[8:11]
	s_setprio 0
	s_barrier
	s_add_u32 s18, s18, 0x80080
	s_addc_u32 s19, s19, 0
	s_add_i32 s20, s20, s25
	v_lshl_add_u64 v[148:149], s[18:19], 0, v[130:131]
	s_mov_b32 m0, s20
	s_nop 0
	global_load_lds_dwordx4 v[148:149], off
	v_lshl_add_u64 v[148:149], s[18:19], 0, v[134:135]
	s_add_i32 m0, s20, 0x2000
	s_nop 0
	global_load_lds_dwordx4 v[148:149], off
	s_waitcnt vmcnt(6)
	s_barrier
	s_setprio 1
	v_mfma_f32_16x16x32_bf16 v[52:55], v[200:203], v[168:171], v[52:55]
	v_mfma_f32_16x16x32_bf16 v[48:51], v[208:211], v[168:171], v[48:51]
	v_mfma_f32_16x16x32_bf16 v[36:39], v[200:203], v[176:179], v[36:39]
	v_mfma_f32_16x16x32_bf16 v[32:35], v[208:211], v[176:179], v[32:35]
	v_mfma_f32_16x16x32_bf16 v[20:23], v[200:203], v[184:187], v[20:23]
	v_mfma_f32_16x16x32_bf16 v[16:19], v[208:211], v[184:187], v[16:19]
	v_mfma_f32_16x16x32_bf16 v[4:7], v[200:203], v[192:195], v[4:7]
	v_mfma_f32_16x16x32_bf16 v[0:3], v[208:211], v[192:195], v[0:3]
	v_mfma_f32_16x16x32_bf16 v[52:55], v[204:207], v[172:175], v[52:55]
	v_mfma_f32_16x16x32_bf16 v[48:51], v[212:215], v[172:175], v[48:51]
	v_mfma_f32_16x16x32_bf16 v[36:39], v[204:207], v[180:183], v[36:39]
	v_mfma_f32_16x16x32_bf16 v[32:35], v[212:215], v[180:183], v[32:35]
	v_mfma_f32_16x16x32_bf16 v[20:23], v[204:207], v[188:191], v[20:23]
	v_mfma_f32_16x16x32_bf16 v[16:19], v[212:215], v[188:191], v[16:19]
	v_mfma_f32_16x16x32_bf16 v[4:7], v[204:207], v[196:199], v[4:7]
	v_mfma_f32_16x16x32_bf16 v[0:3], v[212:215], v[196:199], v[0:3]
	s_setprio 0
	s_add_i32 s53, s53, 2
	s_add_u32 s16, s16, 0x100
	s_addc_u32 s17, s17, 0
	s_add_u32 s51, s51, 0x100
	s_addc_u32 s52, s52, 0
	s_cmp_gt_u32 s53, 29
	s_barrier
	s_cbranch_scc0 .LBB0_1059
	v_lshl_add_u32 v148, s14, 8, v145
	v_ashrrev_i32_e32 v149, 31, v148
	v_lshl_add_u64 v[150:151], v[148:149], 2, s[26:27]
	global_load_dword v170, v[150:151], off
	v_lshl_or_b32 v150, s48, 8, v152
	v_ashrrev_i32_e32 v151, 31, v150
	v_lshlrev_b64 v[156:157], 11, v[148:149]
	v_lshl_add_u64 v[156:157], v[156:157], 0, v[150:151]
	v_lshlrev_b64 v[164:165], 1, v[156:157]
	v_lshl_add_u64 v[156:157], s[34:35], 0, v[164:165]
	v_lshl_add_u64 v[160:161], s[36:37], 0, v[164:165]
	global_load_dwordx4 v[156:159], v[156:157], off
	v_lshl_add_u64 v[166:167], s[40:41], 0, v[164:165]
	global_load_dwordx4 v[160:163], v[160:161], off
	v_or_b32_e32 v164, 0x100, v164
	v_lshl_add_u64 v[168:169], s[34:35], 0, v[164:165]
	s_and_b64 vcc, exec, s[4:5]
	s_mov_b32 s48, s6
	s_mov_b32 s14, s8
	s_mov_b64 s[18:19], s[12:13]
	s_mov_b64 s[16:17], s[10:11]
	global_load_dwordx4 v[178:181], v[168:169], off
	v_lshl_add_u64 v[236:237], s[36:37], 0, v[164:165]
	global_load_dwordx4 v[182:185], v[236:237], off
	v_or_b32_e32 v240, 16, v148
	v_ashrrev_i32_e32 v241, 31, v240
	v_lshlrev_b64 v[238:239], 11, v[240:241]
	v_lshl_add_u64 v[238:239], v[238:239], 0, v[150:151]
	v_lshlrev_b64 v[238:239], 1, v[238:239]
	v_lshl_add_u64 v[236:237], s[36:37], 0, v[238:239]
	global_load_dwordx4 v[186:189], v[236:237], off
	v_or_b32_e32 v238, 16, v148
	v_ashrrev_i32_e32 v239, 31, v238
	v_lshl_add_u64 v[236:237], v[238:239], 2, s[26:27]
	global_load_dword v190, v[236:237], off
	v_or_b32_e32 v238, 16, v148
	v_ashrrev_i32_e32 v239, 31, v238
	v_lshlrev_b64 v[236:237], 11, v[238:239]
	v_lshl_add_u64 v[236:237], v[236:237], 0, v[150:151]
	v_lshlrev_b64 v[236:237], 1, v[236:237]
	v_lshl_add_u64 v[240:241], s[34:35], 0, v[236:237]
	global_load_dwordx4 v[192:195], v[240:241], off
	v_or_b32_e32 v240, 16, v148
	v_ashrrev_i32_e32 v241, 31, v240
	v_lshlrev_b64 v[236:237], 11, v[240:241]
	v_lshl_add_u64 v[236:237], v[236:237], 0, v[150:151]
	v_lshlrev_b64 v[236:237], 1, v[236:237]
	v_or_b32_e32 v236, 0x100, v236
	v_lshl_add_u64 v[238:239], s[34:35], 0, v[236:237]
	global_load_dwordx4 v[196:199], v[238:239], off
	v_or_b32_e32 v240, 16, v148
	v_ashrrev_i32_e32 v241, 31, v240
	v_lshlrev_b64 v[238:239], 11, v[240:241]
	v_lshl_add_u64 v[238:239], v[238:239], 0, v[150:151]
	v_lshlrev_b64 v[238:239], 1, v[238:239]
	v_or_b32_e32 v238, 0x100, v238
	v_lshl_add_u64 v[236:237], s[36:37], 0, v[238:239]
	global_load_dwordx4 v[200:203], v[236:237], off
	v_or_b32_e32 v240, 32, v148
	v_ashrrev_i32_e32 v241, 31, v240
	v_lshlrev_b64 v[238:239], 11, v[240:241]
	v_lshl_add_u64 v[238:239], v[238:239], 0, v[150:151]
	v_lshlrev_b64 v[238:239], 1, v[238:239]
	v_lshl_add_u64 v[236:237], s[36:37], 0, v[238:239]
	global_load_dwordx4 v[204:207], v[236:237], off
	v_or_b32_e32 v238, 32, v148
	v_ashrrev_i32_e32 v239, 31, v238
	v_lshl_add_u64 v[236:237], v[238:239], 2, s[26:27]
	global_load_dword v191, v[236:237], off
	v_or_b32_e32 v238, 32, v148
	v_ashrrev_i32_e32 v239, 31, v238
	v_lshlrev_b64 v[236:237], 11, v[238:239]
	v_lshl_add_u64 v[236:237], v[236:237], 0, v[150:151]
	v_lshlrev_b64 v[236:237], 1, v[236:237]
	v_lshl_add_u64 v[240:241], s[34:35], 0, v[236:237]
	global_load_dwordx4 v[208:211], v[240:241], off
	v_or_b32_e32 v240, 32, v148
	v_ashrrev_i32_e32 v241, 31, v240
	v_lshlrev_b64 v[236:237], 11, v[240:241]
	v_lshl_add_u64 v[236:237], v[236:237], 0, v[150:151]
	v_lshlrev_b64 v[236:237], 1, v[236:237]
	v_or_b32_e32 v236, 0x100, v236
	v_lshl_add_u64 v[238:239], s[34:35], 0, v[236:237]
	global_load_dwordx4 v[212:215], v[238:239], off
	v_or_b32_e32 v240, 32, v148
	v_ashrrev_i32_e32 v241, 31, v240
	v_lshlrev_b64 v[238:239], 11, v[240:241]
	v_lshl_add_u64 v[238:239], v[238:239], 0, v[150:151]
	v_lshlrev_b64 v[238:239], 1, v[238:239]
	v_or_b32_e32 v238, 0x100, v238
	v_lshl_add_u64 v[236:237], s[36:37], 0, v[238:239]
	global_load_dwordx4 v[216:219], v[236:237], off
	s_waitcnt vmcnt(12)
; __device__ __forceinline__ f32x4 unpk4(uint2 u) { f32x4 r; r[0] = __uint_as_float(u.x << 16); r[1] = __uint_as_float(u.x & 0xffff0000u); r[2] = __uint_as_float(u.y << 16); r[3] = __uint_as_float(u.y & 0xffff0000u); return r; }
; __device__ __forceinline__ float sigm(float x) { return __builtin_amdgcn_rcpf(1.f + __expf(-x)); }
; __device__ __forceinline__ uint4 pk8(f32x4 a, f32x4 b) { return make_uint4(cvt_pk_bf16(a[0], a[1]), cvt_pk_bf16(a[2], a[3]), cvt_pk_bf16(b[0], b[1]), cvt_pk_bf16(b[2], b[3])); }
;     __device__ __forceinline__ void operator()(AccRef acc, const Unit& u, int wr, int wc, int fr, int fq) const {
;         const int c0 = u.pn * 256 + wc * 32 + 8 * fq;
; #pragma unroll
;         for (int ai = 0; ai < 2; ++ai)
; #pragma unroll
;             for (int m = 0; m < 4; ++m) {
;                 const int r = u.pm * 256 + ai * 128 + wr * 64 + m * 16 + fr;
;                 const float s = rinv[r];
;                 float ss = 0.f;
; #pragma unroll
;                 for (int bj = 0; bj < 2; ++bj) {
;                     const size_t o = (size_t)r * D + c0 + bj * 128;
;                     const uint4 h8 = *(const uint4*)(H2 + o);
;                     f32x4 v0 = unpk4(make_uint2(h8.x, h8.y)), v1 = unpk4(make_uint2(h8.z, h8.w));
;                     const uint4 pp8 = *(const uint4*)(PPb + o);
;                     const f32x4 p0 = unpk4(make_uint2(pp8.x, pp8.y)), p1 = unpk4(make_uint2(pp8.z, pp8.w));
; #pragma unroll
;                     for (int e = 0; e < 4; ++e) { v0[e] += sigm(acc[ai][bj][m][0][e] * s) * p0[e]; v1[e] += sigm(acc[ai][bj][m][1][e] * s) * p1[e]; }
;                     ss += v0[0] * v0[0] + v0[1] * v0[1] + v0[2] * v0[2] + v0[3] * v0[3] + v1[0] * v1[0] + v1[1] * v1[1] + v1[2] * v1[2] + v1[3] * v1[3];
;                     *(uint4*)(H3 + o) = pk8(v0, v1);
;                 }
	v_mul_f32_e32 v120, v120, v170
	v_mul_f32_e32 v125, v125, v170
	v_mul_f32_e32 v121, v121, v170
	v_mul_f32_e32 v127, v127, v170
	v_mul_f32_e32 v123, v123, v170
	v_mul_f32_e32 v124, v124, v170
	v_mul_f32_e32 v126, v126, v170
	v_mul_f32_e32 v122, v122, v170
	v_mul_f32_e32 v120, 0xbfb8aa3b, v120
	v_mul_f32_e32 v125, 0xbfb8aa3b, v125
	v_mul_f32_e32 v121, 0xbfb8aa3b, v121
	v_mul_f32_e32 v127, 0xbfb8aa3b, v127
	v_mul_f32_e32 v123, 0xbfb8aa3b, v123
	v_mul_f32_e32 v124, 0xbfb8aa3b, v124
	v_mul_f32_e32 v126, 0xbfb8aa3b, v126
	v_mul_f32_e32 v122, 0xbfb8aa3b, v122
	v_exp_f32_e32 v120, v120
	v_exp_f32_e32 v125, v125
	v_exp_f32_e32 v121, v121
	v_exp_f32_e32 v127, v127
	v_exp_f32_e32 v123, v123
	v_exp_f32_e32 v124, v124
	v_exp_f32_e32 v126, v126
	v_exp_f32_e32 v122, v122
	v_add_f32_e32 v120, 1.0, v120
	v_add_f32_e32 v125, 1.0, v125
	v_add_f32_e32 v121, 1.0, v121
	v_add_f32_e32 v127, 1.0, v127
	v_add_f32_e32 v123, 1.0, v123
	v_add_f32_e32 v124, 1.0, v124
	v_add_f32_e32 v126, 1.0, v126
	v_add_f32_e32 v122, 1.0, v122
	v_rcp_f32_e32 v120, v120
	v_rcp_f32_e32 v125, v125
	v_rcp_f32_e32 v121, v121
	v_rcp_f32_e32 v127, v127
	v_rcp_f32_e32 v123, v123
	v_rcp_f32_e32 v124, v124
	v_rcp_f32_e32 v126, v126
	v_rcp_f32_e32 v122, v122
	v_lshlrev_b32_e32 v149, 16, v156
	v_and_b32_e32 v156, 0xffff0000, v156
	v_lshlrev_b32_e32 v171, 16, v157
	v_and_b32_e32 v157, 0xffff0000, v157
	v_lshlrev_b32_e32 v172, 16, v158
	v_and_b32_e32 v158, 0xffff0000, v158
	v_lshlrev_b32_e32 v173, 16, v159
	v_and_b32_e32 v159, 0xffff0000, v159
	v_lshlrev_b32_e32 v174, 16, v160
	v_and_b32_e32 v160, 0xffff0000, v160
	v_lshlrev_b32_e32 v175, 16, v161
	v_and_b32_e32 v161, 0xffff0000, v161
	v_lshlrev_b32_e32 v176, 16, v162
	v_and_b32_e32 v162, 0xffff0000, v162
	v_lshlrev_b32_e32 v177, 16, v163
	v_and_b32_e32 v163, 0xffff0000, v163
	v_fmac_f32_e32 v172, v120, v176
	v_fmac_f32_e32 v156, v125, v160
	v_fmac_f32_e32 v158, v121, v162
	v_fmac_f32_e32 v157, v127, v161
	v_fmac_f32_e32 v159, v123, v163
	v_lshl_add_u64 v[120:121], s[36:37], 0, v[164:165]
	v_fmac_f32_e32 v149, v124, v174
	v_fmac_f32_e32 v171, v126, v175
	v_fmac_f32_e32 v173, v122, v177
	v_cvt_pk_bf16_f32 v122, v149, v156
	v_cvt_pk_bf16_f32 v123, v171, v157
	v_cvt_pk_bf16_f32 v124, v172, v158
	v_cvt_pk_bf16_f32 v125, v173, v159
	v_mul_f32_e32 v116, v116, v170
	v_mul_f32_e32 v117, v117, v170
	v_mul_f32_e32 v112, v112, v170
	v_mul_f32_e32 v113, v113, v170
	v_mul_f32_e32 v118, v118, v170
	v_mul_f32_e32 v114, v114, v170
	v_mul_f32_e32 v119, v119, v170
	v_mul_f32_e32 v115, v115, v170
	v_mul_f32_e32 v116, 0xbfb8aa3b, v116
	v_mul_f32_e32 v117, 0xbfb8aa3b, v117
	v_mul_f32_e32 v112, 0xbfb8aa3b, v112
	v_mul_f32_e32 v113, 0xbfb8aa3b, v113
	v_mul_f32_e32 v118, 0xbfb8aa3b, v118
	v_mul_f32_e32 v114, 0xbfb8aa3b, v114
	v_mul_f32_e32 v119, 0xbfb8aa3b, v119
	v_mul_f32_e32 v115, 0xbfb8aa3b, v115
	v_exp_f32_e32 v116, v116
	v_exp_f32_e32 v117, v117
	v_exp_f32_e32 v112, v112
	v_exp_f32_e32 v113, v113
	v_exp_f32_e32 v118, v118
	v_exp_f32_e32 v114, v114
	v_exp_f32_e32 v119, v119
	v_exp_f32_e32 v115, v115
	v_add_f32_e32 v116, 1.0, v116
	v_add_f32_e32 v117, 1.0, v117
	v_or_b32_e32 v126, 16, v148
	v_add_f32_e32 v112, 1.0, v112
	v_add_f32_e32 v113, 1.0, v113
	v_add_f32_e32 v118, 1.0, v118
	v_add_f32_e32 v114, 1.0, v114
	v_add_f32_e32 v119, 1.0, v119
	v_add_f32_e32 v115, 1.0, v115
	v_rcp_f32_e32 v116, v116
	v_rcp_f32_e32 v117, v117
	v_ashrrev_i32_e32 v127, 31, v126
	v_rcp_f32_e32 v112, v112
	v_rcp_f32_e32 v113, v113
	v_rcp_f32_e32 v118, v118
	v_rcp_f32_e32 v114, v114
	v_rcp_f32_e32 v119, v119
	v_rcp_f32_e32 v115, v115
	v_lshlrev_b64 v[120:121], 11, v[126:127]
	v_lshl_add_u64 v[120:121], v[120:121], 0, v[150:151]
	global_store_dwordx4 v[166:167], v[122:125], off
	v_lshlrev_b64 v[120:121], 1, v[120:121]
	v_lshl_add_u64 v[164:165], s[40:41], 0, v[164:165]
	v_lshl_add_u64 v[168:169], s[34:35], 0, v[120:121]
	v_or_b32_e32 v240, 48, v148
	v_ashrrev_i32_e32 v241, 31, v240
	v_lshlrev_b64 v[238:239], 11, v[240:241]
	v_lshl_add_u64 v[238:239], v[238:239], 0, v[150:151]
	v_lshlrev_b64 v[238:239], 1, v[238:239]
	v_lshl_add_u64 v[236:237], s[36:37], 0, v[238:239]
	global_load_dwordx4 v[220:223], v[236:237], off
	v_or_b32_e32 v238, 48, v148
	v_ashrrev_i32_e32 v239, 31, v238
	v_lshl_add_u64 v[236:237], v[238:239], 2, s[26:27]
	global_load_dword v224, v[236:237], off
	v_or_b32_e32 v238, 48, v148
	v_ashrrev_i32_e32 v239, 31, v238
	v_lshlrev_b64 v[236:237], 11, v[238:239]
	v_lshl_add_u64 v[236:237], v[236:237], 0, v[150:151]
	v_lshlrev_b64 v[236:237], 1, v[236:237]
	v_lshl_add_u64 v[240:241], s[34:35], 0, v[236:237]
	global_load_dwordx4 v[226:229], v[240:241], off
	s_waitcnt vmcnt(14)
	v_lshlrev_b32_e32 v122, 16, v178
	v_and_b32_e32 v123, 0xffff0000, v178
	v_lshlrev_b32_e32 v124, 16, v179
	v_and_b32_e32 v125, 0xffff0000, v179
	v_lshlrev_b32_e32 v149, 16, v180
	v_and_b32_e32 v156, 0xffff0000, v180
	v_lshlrev_b32_e32 v157, 16, v181
	v_and_b32_e32 v158, 0xffff0000, v181
	v_lshlrev_b32_e32 v159, 16, v182
	v_and_b32_e32 v160, 0xffff0000, v182
	v_lshlrev_b32_e32 v166, 16, v183
	v_and_b32_e32 v161, 0xffff0000, v183
	v_lshlrev_b32_e32 v167, 16, v184
	v_and_b32_e32 v162, 0xffff0000, v184
	v_lshlrev_b32_e32 v170, 16, v185
	v_and_b32_e32 v163, 0xffff0000, v185
	v_fmac_f32_e32 v122, v116, v159
	v_fmac_f32_e32 v123, v117, v160
	v_fmac_f32_e32 v149, v112, v167
	v_fmac_f32_e32 v156, v113, v162
	v_fmac_f32_e32 v124, v118, v166
	v_fmac_f32_e32 v157, v114, v170
	v_fmac_f32_e32 v125, v119, v161
	v_fmac_f32_e32 v158, v115, v163
	v_cvt_pk_bf16_f32 v112, v122, v123
	v_cvt_pk_bf16_f32 v113, v124, v125
	v_cvt_pk_bf16_f32 v114, v149, v156
	v_cvt_pk_bf16_f32 v115, v157, v158
	global_store_dwordx4 v[164:165], v[112:115], off
	v_lshl_add_u64 v[116:117], s[36:37], 0, v[120:121]
	v_lshl_add_u64 v[122:123], v[126:127], 2, s[26:27]
	s_nop 0
	v_lshl_add_u64 v[122:123], s[40:41], 0, v[120:121]
	v_or_b32_e32 v120, 0x100, v120
	v_lshl_add_u64 v[124:125], s[34:35], 0, v[120:121]
	v_or_b32_e32 v240, 48, v148
	v_ashrrev_i32_e32 v241, 31, v240
	v_lshlrev_b64 v[236:237], 11, v[240:241]
	v_lshl_add_u64 v[236:237], v[236:237], 0, v[150:151]
	v_lshlrev_b64 v[236:237], 1, v[236:237]
	v_or_b32_e32 v236, 0x100, v236
	v_lshl_add_u64 v[238:239], s[34:35], 0, v[236:237]
	global_load_dwordx4 v[178:181], v[238:239], off
	v_or_b32_e32 v240, 48, v148
	v_ashrrev_i32_e32 v241, 31, v240
	v_lshlrev_b64 v[238:239], 11, v[240:241]
	v_lshl_add_u64 v[238:239], v[238:239], 0, v[150:151]
	v_lshlrev_b64 v[238:239], 1, v[238:239]
	v_or_b32_e32 v238, 0x100, v238
	v_lshl_add_u64 v[236:237], s[36:37], 0, v[238:239]
	global_load_dwordx4 v[182:185], v[236:237], off
	s_waitcnt vmcnt(14)
; __device__ __forceinline__ f32x4 unpk4(uint2 u) { f32x4 r; r[0] = __uint_as_float(u.x << 16); r[1] = __uint_as_float(u.x & 0xffff0000u); r[2] = __uint_as_float(u.y << 16); r[3] = __uint_as_float(u.y & 0xffff0000u); return r; }
; __device__ __forceinline__ float sigm(float x) { return __builtin_amdgcn_rcpf(1.f + __expf(-x)); }
; __device__ __forceinline__ uint4 pk8(f32x4 a, f32x4 b) { return make_uint4(cvt_pk_bf16(a[0], a[1]), cvt_pk_bf16(a[2], a[3]), cvt_pk_bf16(b[0], b[1]), cvt_pk_bf16(b[2], b[3])); }
;     __device__ __forceinline__ void operator()(AccRef acc, const Unit& u, int wr, int wc, int fr, int fq) const {
;         const int c0 = u.pn * 256 + wc * 32 + 8 * fq;
; #pragma unroll
;         for (int ai = 0; ai < 2; ++ai)
; #pragma unroll
;             for (int m = 0; m < 4; ++m) {
;                 const int r = u.pm * 256 + ai * 128 + wr * 64 + m * 16 + fr;
;                 const float s = rinv[r];
;                 float ss = 0.f;
; #pragma unroll
;                 for (int bj = 0; bj < 2; ++bj) {
;                     const size_t o = (size_t)r * D + c0 + bj * 128;
;                     const uint4 h8 = *(const uint4*)(H2 + o);
;                     f32x4 v0 = unpk4(make_uint2(h8.x, h8.y)), v1 = unpk4(make_uint2(h8.z, h8.w));
;                     const uint4 pp8 = *(const uint4*)(PPb + o);
;                     const f32x4 p0 = unpk4(make_uint2(pp8.x, pp8.y)), p1 = unpk4(make_uint2(pp8.z, pp8.w));
; #pragma unroll
;                     for (int e = 0; e < 4; ++e) { v0[e] += sigm(acc[ai][bj][m][0][e] * s) * p0[e]; v1[e] += sigm(acc[ai][bj][m][1][e] * s) * p1[e]; }
;                     ss += v0[0] * v0[0] + v0[1] * v0[1] + v0[2] * v0[2] + v0[3] * v0[3] + v1[0] * v1[0] + v1[1] * v1[1] + v1[2] * v1[2] + v1[3] * v1[3];
;                     *(uint4*)(H3 + o) = pk8(v0, v1);
;                 }
	v_lshlrev_b32_e32 v158, 16, v186
	v_and_b32_e32 v116, 0xffff0000, v186
	v_mul_f32_e32 v104, v104, v190
	v_mul_f32_e32 v109, v109, v190
	v_mul_f32_e32 v105, v105, v190
	v_mul_f32_e32 v111, v111, v190
	v_mul_f32_e32 v107, v107, v190
	v_mul_f32_e32 v108, v108, v190
	v_mul_f32_e32 v110, v110, v190
	v_mul_f32_e32 v106, v106, v190
	v_mul_f32_e32 v104, 0xbfb8aa3b, v104
	v_mul_f32_e32 v109, 0xbfb8aa3b, v109
	v_mul_f32_e32 v105, 0xbfb8aa3b, v105
	v_mul_f32_e32 v111, 0xbfb8aa3b, v111
	v_mul_f32_e32 v107, 0xbfb8aa3b, v107
	v_mul_f32_e32 v108, 0xbfb8aa3b, v108
	v_mul_f32_e32 v110, 0xbfb8aa3b, v110
	v_mul_f32_e32 v106, 0xbfb8aa3b, v106
	v_exp_f32_e32 v104, v104
	v_exp_f32_e32 v109, v109
	v_exp_f32_e32 v105, v105
	v_exp_f32_e32 v111, v111
	v_exp_f32_e32 v107, v107
	v_exp_f32_e32 v108, v108
	v_exp_f32_e32 v110, v110
	v_exp_f32_e32 v106, v106
	v_add_f32_e32 v104, 1.0, v104
	v_add_f32_e32 v109, 1.0, v109
	v_add_f32_e32 v105, 1.0, v105
	v_add_f32_e32 v111, 1.0, v111
	v_add_f32_e32 v107, 1.0, v107
	v_add_f32_e32 v108, 1.0, v108
	v_add_f32_e32 v110, 1.0, v110
	v_add_f32_e32 v106, 1.0, v106
	v_rcp_f32_e32 v104, v104
	v_rcp_f32_e32 v109, v109
	v_rcp_f32_e32 v105, v105
	v_rcp_f32_e32 v111, v111
	v_rcp_f32_e32 v107, v107
	v_rcp_f32_e32 v108, v108
	v_rcp_f32_e32 v110, v110
	v_rcp_f32_e32 v106, v106
	v_lshlrev_b32_e32 v127, 16, v192
	v_and_b32_e32 v112, 0xffff0000, v192
	v_lshlrev_b32_e32 v149, 16, v193
	v_and_b32_e32 v113, 0xffff0000, v193
	v_lshlrev_b32_e32 v156, 16, v194
	v_and_b32_e32 v114, 0xffff0000, v194
	v_lshlrev_b32_e32 v157, 16, v195
	v_and_b32_e32 v115, 0xffff0000, v195
	v_lshlrev_b32_e32 v159, 16, v187
	v_and_b32_e32 v117, 0xffff0000, v187
	v_lshlrev_b32_e32 v160, 16, v188
	v_and_b32_e32 v118, 0xffff0000, v188
	v_lshlrev_b32_e32 v161, 16, v189
	v_and_b32_e32 v119, 0xffff0000, v189
	v_fmac_f32_e32 v156, v104, v160
	v_fmac_f32_e32 v112, v109, v116
	v_fmac_f32_e32 v114, v105, v118
	v_fmac_f32_e32 v113, v111, v117
	v_fmac_f32_e32 v115, v107, v119
	v_lshl_add_u64 v[104:105], s[36:37], 0, v[120:121]
	v_fmac_f32_e32 v127, v108, v158
	v_fmac_f32_e32 v149, v110, v159
	v_fmac_f32_e32 v157, v106, v161
	v_cvt_pk_bf16_f32 v106, v127, v112
	v_cvt_pk_bf16_f32 v107, v149, v113
	v_cvt_pk_bf16_f32 v108, v156, v114
	v_cvt_pk_bf16_f32 v109, v157, v115
	v_mul_f32_e32 v100, v100, v190
	v_mul_f32_e32 v101, v101, v190
	v_mul_f32_e32 v96, v96, v190
	v_mul_f32_e32 v97, v97, v190
	v_mul_f32_e32 v102, v102, v190
	v_mul_f32_e32 v98, v98, v190
	v_mul_f32_e32 v103, v103, v190
	v_mul_f32_e32 v99, v99, v190
	v_mul_f32_e32 v100, 0xbfb8aa3b, v100
	v_mul_f32_e32 v101, 0xbfb8aa3b, v101
	v_mul_f32_e32 v96, 0xbfb8aa3b, v96
	v_mul_f32_e32 v97, 0xbfb8aa3b, v97
	v_mul_f32_e32 v102, 0xbfb8aa3b, v102
	v_mul_f32_e32 v98, 0xbfb8aa3b, v98
	v_mul_f32_e32 v103, 0xbfb8aa3b, v103
	v_mul_f32_e32 v99, 0xbfb8aa3b, v99
	v_exp_f32_e32 v100, v100
	v_exp_f32_e32 v101, v101
	v_exp_f32_e32 v96, v96
	v_exp_f32_e32 v97, v97
	v_exp_f32_e32 v102, v102
	v_exp_f32_e32 v98, v98
	v_exp_f32_e32 v103, v103
	v_exp_f32_e32 v99, v99
	v_add_f32_e32 v100, 1.0, v100
	v_add_f32_e32 v101, 1.0, v101
	v_or_b32_e32 v118, 32, v148
	v_add_f32_e32 v96, 1.0, v96
	v_add_f32_e32 v97, 1.0, v97
	v_add_f32_e32 v102, 1.0, v102
	v_add_f32_e32 v98, 1.0, v98
	v_add_f32_e32 v103, 1.0, v103
	v_add_f32_e32 v99, 1.0, v99
	v_rcp_f32_e32 v100, v100
	v_rcp_f32_e32 v101, v101
	v_ashrrev_i32_e32 v119, 31, v118
	v_rcp_f32_e32 v96, v96
	v_rcp_f32_e32 v97, v97
	v_rcp_f32_e32 v102, v102
	v_rcp_f32_e32 v98, v98
	v_rcp_f32_e32 v103, v103
	v_rcp_f32_e32 v99, v99
	v_lshlrev_b64 v[104:105], 11, v[118:119]
	v_lshl_add_u64 v[104:105], v[104:105], 0, v[150:151]
	global_store_dwordx4 v[122:123], v[106:109], off
	v_lshlrev_b64 v[104:105], 1, v[104:105]
	v_lshl_add_u64 v[120:121], s[40:41], 0, v[120:121]
	v_lshl_add_u64 v[124:125], s[34:35], 0, v[104:105]
	v_add_u32_e32 v240, 0x80, v148
	v_ashrrev_i32_e32 v241, 31, v240
	v_lshlrev_b64 v[238:239], 11, v[240:241]
	v_lshl_add_u64 v[238:239], v[238:239], 0, v[150:151]
	v_lshlrev_b64 v[238:239], 1, v[238:239]
	v_lshl_add_u64 v[236:237], s[36:37], 0, v[238:239]
	global_load_dwordx4 v[186:189], v[236:237], off
	v_add_u32_e32 v238, 0x80, v148
	v_ashrrev_i32_e32 v239, 31, v238
	v_lshl_add_u64 v[236:237], v[238:239], 2, s[26:27]
	global_load_dword v190, v[236:237], off
	v_add_u32_e32 v238, 0x80, v148
	v_ashrrev_i32_e32 v239, 31, v238
	v_lshlrev_b64 v[236:237], 11, v[238:239]
	v_lshl_add_u64 v[236:237], v[236:237], 0, v[150:151]
	v_lshlrev_b64 v[236:237], 1, v[236:237]
	v_lshl_add_u64 v[240:241], s[34:35], 0, v[236:237]
	global_load_dwordx4 v[192:195], v[240:241], off
	s_waitcnt vmcnt(16)
	v_lshlrev_b32_e32 v106, 16, v196
	v_and_b32_e32 v107, 0xffff0000, v196
	v_lshlrev_b32_e32 v122, 16, v200
	v_and_b32_e32 v114, 0xffff0000, v200
	v_lshlrev_b32_e32 v108, 16, v197
	v_and_b32_e32 v109, 0xffff0000, v197
	v_lshlrev_b32_e32 v110, 16, v198
	v_and_b32_e32 v111, 0xffff0000, v198
	v_lshlrev_b32_e32 v112, 16, v199
	v_and_b32_e32 v113, 0xffff0000, v199
	v_lshlrev_b32_e32 v123, 16, v201
	v_and_b32_e32 v115, 0xffff0000, v201
	v_lshlrev_b32_e32 v126, 16, v202
	v_and_b32_e32 v116, 0xffff0000, v202
	v_lshlrev_b32_e32 v127, 16, v203
	v_and_b32_e32 v117, 0xffff0000, v203
	v_fmac_f32_e32 v106, v100, v122
	v_fmac_f32_e32 v107, v101, v114
	v_fmac_f32_e32 v110, v96, v126
	v_fmac_f32_e32 v111, v97, v116
	v_fmac_f32_e32 v108, v102, v123
	v_fmac_f32_e32 v112, v98, v127
	v_fmac_f32_e32 v109, v103, v115
	v_fmac_f32_e32 v113, v99, v117
	v_cvt_pk_bf16_f32 v96, v106, v107
	v_cvt_pk_bf16_f32 v97, v108, v109
	v_cvt_pk_bf16_f32 v98, v110, v111
	v_cvt_pk_bf16_f32 v99, v112, v113
	global_store_dwordx4 v[120:121], v[96:99], off
	v_lshl_add_u64 v[100:101], s[36:37], 0, v[104:105]
	v_lshl_add_u64 v[106:107], v[118:119], 2, s[26:27]
	s_nop 0
	v_lshl_add_u64 v[106:107], s[40:41], 0, v[104:105]
	v_or_b32_e32 v104, 0x100, v104
	v_lshl_add_u64 v[108:109], s[34:35], 0, v[104:105]
	v_add_u32_e32 v240, 0x80, v148
	v_ashrrev_i32_e32 v241, 31, v240
	v_lshlrev_b64 v[236:237], 11, v[240:241]
	v_lshl_add_u64 v[236:237], v[236:237], 0, v[150:151]
	v_lshlrev_b64 v[236:237], 1, v[236:237]
	v_or_b32_e32 v236, 0x100, v236
	v_lshl_add_u64 v[238:239], s[34:35], 0, v[236:237]
	global_load_dwordx4 v[196:199], v[238:239], off
	v_add_u32_e32 v240, 0x80, v148
	v_ashrrev_i32_e32 v241, 31, v240
	v_lshlrev_b64 v[238:239], 11, v[240:241]
	v_lshl_add_u64 v[238:239], v[238:239], 0, v[150:151]
	v_lshlrev_b64 v[238:239], 1, v[238:239]
	v_or_b32_e32 v238, 0x100, v238
	v_lshl_add_u64 v[236:237], s[36:37], 0, v[238:239]
	global_load_dwordx4 v[200:203], v[236:237], off
	s_waitcnt vmcnt(16)
; __device__ __forceinline__ f32x4 unpk4(uint2 u) { f32x4 r; r[0] = __uint_as_float(u.x << 16); r[1] = __uint_as_float(u.x & 0xffff0000u); r[2] = __uint_as_float(u.y << 16); r[3] = __uint_as_float(u.y & 0xffff0000u); return r; }
; __device__ __forceinline__ float sigm(float x) { return __builtin_amdgcn_rcpf(1.f + __expf(-x)); }
; __device__ __forceinline__ uint4 pk8(f32x4 a, f32x4 b) { return make_uint4(cvt_pk_bf16(a[0], a[1]), cvt_pk_bf16(a[2], a[3]), cvt_pk_bf16(b[0], b[1]), cvt_pk_bf16(b[2], b[3])); }
;     __device__ __forceinline__ void operator()(AccRef acc, const Unit& u, int wr, int wc, int fr, int fq) const {
;     ...
;         for (int ai = 0; ai < 2; ++ai)
; #pragma unroll
;             for (int m = 0; m < 4; ++m) {
;                 const int r = u.pm * 256 + ai * 128 + wr * 64 + m * 16 + fr;
;                 const float s = rinv[r];
;                 float ss = 0.f;
; #pragma unroll
;                 for (int bj = 0; bj < 2; ++bj) {
;                     const size_t o = (size_t)r * D + c0 + bj * 128;
;                     const uint4 h8 = *(const uint4*)(H2 + o);
;                     f32x4 v0 = unpk4(make_uint2(h8.x, h8.y)), v1 = unpk4(make_uint2(h8.z, h8.w));
;                     const uint4 pp8 = *(const uint4*)(PPb + o);
;                     const f32x4 p0 = unpk4(make_uint2(pp8.x, pp8.y)), p1 = unpk4(make_uint2(pp8.z, pp8.w));
; #pragma unroll
;                     for (int e = 0; e < 4; ++e) { v0[e] += sigm(acc[ai][bj][m][0][e] * s) * p0[e]; v1[e] += sigm(acc[ai][bj][m][1][e] * s) * p1[e]; }
;                     ss += v0[0] * v0[0] + v0[1] * v0[1] + v0[2] * v0[2] + v0[3] * v0[3] + v1[0] * v1[0] + v1[1] * v1[1] + v1[2] * v1[2] + v1[3] * v1[3];
;                     *(uint4*)(H3 + o) = pk8(v0, v1);
;                 }
	v_lshlrev_b32_e32 v115, 16, v204
	v_and_b32_e32 v100, 0xffff0000, v204
	v_mul_f32_e32 v88, v88, v191
	v_mul_f32_e32 v93, v93, v191
	v_mul_f32_e32 v89, v89, v191
	v_mul_f32_e32 v95, v95, v191
	v_mul_f32_e32 v91, v91, v191
	v_mul_f32_e32 v92, v92, v191
	v_mul_f32_e32 v94, v94, v191
	v_mul_f32_e32 v90, v90, v191
	v_mul_f32_e32 v88, 0xbfb8aa3b, v88
	v_mul_f32_e32 v93, 0xbfb8aa3b, v93
	v_mul_f32_e32 v89, 0xbfb8aa3b, v89
	v_mul_f32_e32 v95, 0xbfb8aa3b, v95
	v_mul_f32_e32 v91, 0xbfb8aa3b, v91
	v_mul_f32_e32 v92, 0xbfb8aa3b, v92
	v_mul_f32_e32 v94, 0xbfb8aa3b, v94
	v_mul_f32_e32 v90, 0xbfb8aa3b, v90
	v_exp_f32_e32 v88, v88
	v_exp_f32_e32 v93, v93
	v_exp_f32_e32 v89, v89
	v_exp_f32_e32 v95, v95
	v_exp_f32_e32 v91, v91
	v_exp_f32_e32 v92, v92
	v_exp_f32_e32 v94, v94
	v_exp_f32_e32 v90, v90
	v_add_f32_e32 v88, 1.0, v88
	v_add_f32_e32 v93, 1.0, v93
	v_add_f32_e32 v89, 1.0, v89
	v_add_f32_e32 v95, 1.0, v95
	v_add_f32_e32 v91, 1.0, v91
	v_add_f32_e32 v92, 1.0, v92
	v_add_f32_e32 v94, 1.0, v94
	v_add_f32_e32 v90, 1.0, v90
	v_rcp_f32_e32 v88, v88
	v_rcp_f32_e32 v93, v93
	v_rcp_f32_e32 v89, v89
	v_rcp_f32_e32 v95, v95
	v_rcp_f32_e32 v91, v91
	v_rcp_f32_e32 v92, v92
	v_rcp_f32_e32 v94, v94
	v_rcp_f32_e32 v90, v90
	v_lshlrev_b32_e32 v111, 16, v208
	v_and_b32_e32 v96, 0xffff0000, v208
	v_lshlrev_b32_e32 v112, 16, v209
	v_and_b32_e32 v97, 0xffff0000, v209
	v_lshlrev_b32_e32 v113, 16, v210
	v_and_b32_e32 v98, 0xffff0000, v210
	v_lshlrev_b32_e32 v114, 16, v211
	v_and_b32_e32 v99, 0xffff0000, v211
	v_lshlrev_b32_e32 v116, 16, v205
	v_and_b32_e32 v101, 0xffff0000, v205
	v_lshlrev_b32_e32 v117, 16, v206
	v_and_b32_e32 v102, 0xffff0000, v206
	v_lshlrev_b32_e32 v118, 16, v207
	v_and_b32_e32 v103, 0xffff0000, v207
	v_fmac_f32_e32 v113, v88, v117
	v_fmac_f32_e32 v96, v93, v100
	v_fmac_f32_e32 v98, v89, v102
	v_fmac_f32_e32 v97, v95, v101
	v_fmac_f32_e32 v99, v91, v103
	v_lshl_add_u64 v[88:89], s[36:37], 0, v[104:105]
	v_fmac_f32_e32 v111, v92, v115
	v_fmac_f32_e32 v112, v94, v116
	v_fmac_f32_e32 v114, v90, v118
	v_cvt_pk_bf16_f32 v90, v111, v96
	v_cvt_pk_bf16_f32 v91, v112, v97
	v_cvt_pk_bf16_f32 v92, v113, v98
	v_cvt_pk_bf16_f32 v93, v114, v99
	v_mul_f32_e32 v84, v84, v191
	v_mul_f32_e32 v85, v85, v191
	v_mul_f32_e32 v80, v80, v191
	v_mul_f32_e32 v81, v81, v191
	v_mul_f32_e32 v86, v86, v191
	v_mul_f32_e32 v82, v82, v191
	v_mul_f32_e32 v87, v87, v191
	v_mul_f32_e32 v83, v83, v191
	v_mul_f32_e32 v84, 0xbfb8aa3b, v84
	v_mul_f32_e32 v85, 0xbfb8aa3b, v85
	v_mul_f32_e32 v80, 0xbfb8aa3b, v80
	v_mul_f32_e32 v81, 0xbfb8aa3b, v81
	v_mul_f32_e32 v86, 0xbfb8aa3b, v86
	v_mul_f32_e32 v82, 0xbfb8aa3b, v82
	v_mul_f32_e32 v87, 0xbfb8aa3b, v87
	v_mul_f32_e32 v83, 0xbfb8aa3b, v83
	v_exp_f32_e32 v84, v84
	v_exp_f32_e32 v85, v85
	v_exp_f32_e32 v80, v80
	v_exp_f32_e32 v81, v81
	v_exp_f32_e32 v86, v86
	v_exp_f32_e32 v82, v82
	v_exp_f32_e32 v87, v87
	v_exp_f32_e32 v83, v83
	v_add_f32_e32 v84, 1.0, v84
	v_add_f32_e32 v85, 1.0, v85
	v_or_b32_e32 v102, 48, v148
	v_add_f32_e32 v80, 1.0, v80
	v_add_f32_e32 v81, 1.0, v81
	v_add_f32_e32 v86, 1.0, v86
	v_add_f32_e32 v82, 1.0, v82
	v_add_f32_e32 v87, 1.0, v87
	v_add_f32_e32 v83, 1.0, v83
	v_rcp_f32_e32 v84, v84
	v_rcp_f32_e32 v85, v85
	v_ashrrev_i32_e32 v103, 31, v102
	v_rcp_f32_e32 v80, v80
	v_rcp_f32_e32 v81, v81
	v_rcp_f32_e32 v86, v86
	v_rcp_f32_e32 v82, v82
	v_rcp_f32_e32 v87, v87
	v_rcp_f32_e32 v83, v83
	v_lshlrev_b64 v[88:89], 11, v[102:103]
	v_lshl_add_u64 v[88:89], v[88:89], 0, v[150:151]
	global_store_dwordx4 v[106:107], v[90:93], off
	v_lshlrev_b64 v[88:89], 1, v[88:89]
	v_lshl_add_u64 v[104:105], s[40:41], 0, v[104:105]
	v_lshl_add_u64 v[108:109], s[34:35], 0, v[88:89]
	v_add_u32_e32 v240, 0x90, v148
	v_ashrrev_i32_e32 v241, 31, v240
	v_lshlrev_b64 v[238:239], 11, v[240:241]
	v_lshl_add_u64 v[238:239], v[238:239], 0, v[150:151]
	v_lshlrev_b64 v[238:239], 1, v[238:239]
	v_lshl_add_u64 v[236:237], s[36:37], 0, v[238:239]
	global_load_dwordx4 v[204:207], v[236:237], off
	v_add_u32_e32 v238, 0x90, v148
	v_ashrrev_i32_e32 v239, 31, v238
	v_lshl_add_u64 v[236:237], v[238:239], 2, s[26:27]
	global_load_dword v191, v[236:237], off
	v_add_u32_e32 v238, 0x90, v148
	v_ashrrev_i32_e32 v239, 31, v238
	v_lshlrev_b64 v[236:237], 11, v[238:239]
	v_lshl_add_u64 v[236:237], v[236:237], 0, v[150:151]
	v_lshlrev_b64 v[236:237], 1, v[236:237]
	v_lshl_add_u64 v[240:241], s[34:35], 0, v[236:237]
	global_load_dwordx4 v[208:211], v[240:241], off
	s_waitcnt vmcnt(18)
	v_lshlrev_b32_e32 v90, 16, v212
	v_and_b32_e32 v91, 0xffff0000, v212
	v_lshlrev_b32_e32 v106, 16, v216
	v_and_b32_e32 v98, 0xffff0000, v216
	v_lshlrev_b32_e32 v92, 16, v213
	v_and_b32_e32 v93, 0xffff0000, v213
	v_lshlrev_b32_e32 v94, 16, v214
	v_and_b32_e32 v95, 0xffff0000, v214
	v_lshlrev_b32_e32 v96, 16, v215
	v_and_b32_e32 v97, 0xffff0000, v215
	v_lshlrev_b32_e32 v107, 16, v217
	v_and_b32_e32 v99, 0xffff0000, v217
	v_lshlrev_b32_e32 v110, 16, v218
	v_and_b32_e32 v100, 0xffff0000, v218
	v_lshlrev_b32_e32 v111, 16, v219
	v_and_b32_e32 v101, 0xffff0000, v219
	v_fmac_f32_e32 v90, v84, v106
	v_fmac_f32_e32 v91, v85, v98
	v_fmac_f32_e32 v94, v80, v110
	v_fmac_f32_e32 v95, v81, v100
	v_fmac_f32_e32 v92, v86, v107
	v_fmac_f32_e32 v96, v82, v111
	v_fmac_f32_e32 v93, v87, v99
	v_fmac_f32_e32 v97, v83, v101
	v_cvt_pk_bf16_f32 v80, v90, v91
	v_cvt_pk_bf16_f32 v81, v92, v93
	v_cvt_pk_bf16_f32 v82, v94, v95
	v_cvt_pk_bf16_f32 v83, v96, v97
	global_store_dwordx4 v[104:105], v[80:83], off
	v_lshl_add_u64 v[84:85], s[36:37], 0, v[88:89]
	v_lshl_add_u64 v[90:91], v[102:103], 2, s[26:27]
	s_nop 0
	v_lshl_add_u64 v[90:91], s[40:41], 0, v[88:89]
	v_or_b32_e32 v88, 0x100, v88
	v_lshl_add_u64 v[92:93], s[34:35], 0, v[88:89]
	v_add_u32_e32 v240, 0x90, v148
	v_ashrrev_i32_e32 v241, 31, v240
	v_lshlrev_b64 v[236:237], 11, v[240:241]
	v_lshl_add_u64 v[236:237], v[236:237], 0, v[150:151]
	v_lshlrev_b64 v[236:237], 1, v[236:237]
	v_or_b32_e32 v236, 0x100, v236
	v_lshl_add_u64 v[238:239], s[34:35], 0, v[236:237]
	global_load_dwordx4 v[212:215], v[238:239], off
	v_add_u32_e32 v240, 0x90, v148
	v_ashrrev_i32_e32 v241, 31, v240
	v_lshlrev_b64 v[238:239], 11, v[240:241]
	v_lshl_add_u64 v[238:239], v[238:239], 0, v[150:151]
	v_lshlrev_b64 v[238:239], 1, v[238:239]
	v_or_b32_e32 v238, 0x100, v238
	v_lshl_add_u64 v[236:237], s[36:37], 0, v[238:239]
	global_load_dwordx4 v[216:219], v[236:237], off
	s_waitcnt vmcnt(17)
; __device__ __forceinline__ f32x4 unpk4(uint2 u) { f32x4 r; r[0] = __uint_as_float(u.x << 16); r[1] = __uint_as_float(u.x & 0xffff0000u); r[2] = __uint_as_float(u.y << 16); r[3] = __uint_as_float(u.y & 0xffff0000u); return r; }
; __device__ __forceinline__ float sigm(float x) { return __builtin_amdgcn_rcpf(1.f + __expf(-x)); }
; __device__ __forceinline__ uint4 pk8(f32x4 a, f32x4 b) { return make_uint4(cvt_pk_bf16(a[0], a[1]), cvt_pk_bf16(a[2], a[3]), cvt_pk_bf16(b[0], b[1]), cvt_pk_bf16(b[2], b[3])); }
;     __device__ __forceinline__ void operator()(AccRef acc, const Unit& u, int wr, int wc, int fr, int fq) const {
;     ...
;         for (int ai = 0; ai < 2; ++ai)
; #pragma unroll
;             for (int m = 0; m < 4; ++m) {
;                 const int r = u.pm * 256 + ai * 128 + wr * 64 + m * 16 + fr;
;                 const float s = rinv[r];
;                 float ss = 0.f;
; #pragma unroll
;                 for (int bj = 0; bj < 2; ++bj) {
;                     const size_t o = (size_t)r * D + c0 + bj * 128;
;                     const uint4 h8 = *(const uint4*)(H2 + o);
;                     f32x4 v0 = unpk4(make_uint2(h8.x, h8.y)), v1 = unpk4(make_uint2(h8.z, h8.w));
;                     const uint4 pp8 = *(const uint4*)(PPb + o);
;                     const f32x4 p0 = unpk4(make_uint2(pp8.x, pp8.y)), p1 = unpk4(make_uint2(pp8.z, pp8.w));
; #pragma unroll
;                     for (int e = 0; e < 4; ++e) { v0[e] += sigm(acc[ai][bj][m][0][e] * s) * p0[e]; v1[e] += sigm(acc[ai][bj][m][1][e] * s) * p1[e]; }
;                     ss += v0[0] * v0[0] + v0[1] * v0[1] + v0[2] * v0[2] + v0[3] * v0[3] + v1[0] * v1[0] + v1[1] * v1[1] + v1[2] * v1[2] + v1[3] * v1[3];
;                     *(uint4*)(H3 + o) = pk8(v0, v1);
;                 }
	v_lshlrev_b32_e32 v99, 16, v220
	v_and_b32_e32 v84, 0xffff0000, v220
	v_mul_f32_e32 v72, v72, v224
	v_mul_f32_e32 v77, v77, v224
	v_mul_f32_e32 v73, v73, v224
	v_mul_f32_e32 v79, v79, v224
	v_mul_f32_e32 v75, v75, v224
	v_mul_f32_e32 v76, v76, v224
	v_mul_f32_e32 v78, v78, v224
	v_mul_f32_e32 v74, v74, v224
	v_mul_f32_e32 v72, 0xbfb8aa3b, v72
	v_mul_f32_e32 v77, 0xbfb8aa3b, v77
	v_mul_f32_e32 v73, 0xbfb8aa3b, v73
	v_mul_f32_e32 v79, 0xbfb8aa3b, v79
	v_mul_f32_e32 v75, 0xbfb8aa3b, v75
	v_mul_f32_e32 v76, 0xbfb8aa3b, v76
	v_mul_f32_e32 v78, 0xbfb8aa3b, v78
	v_mul_f32_e32 v74, 0xbfb8aa3b, v74
	v_exp_f32_e32 v72, v72
	v_exp_f32_e32 v77, v77
	v_exp_f32_e32 v73, v73
	v_exp_f32_e32 v79, v79
	v_exp_f32_e32 v75, v75
	v_exp_f32_e32 v76, v76
	v_exp_f32_e32 v78, v78
	v_exp_f32_e32 v74, v74
	v_add_f32_e32 v72, 1.0, v72
	v_add_f32_e32 v77, 1.0, v77
	v_add_f32_e32 v73, 1.0, v73
	v_add_f32_e32 v79, 1.0, v79
	v_add_f32_e32 v75, 1.0, v75
	v_add_f32_e32 v76, 1.0, v76
	v_add_f32_e32 v78, 1.0, v78
	v_add_f32_e32 v74, 1.0, v74
	v_rcp_f32_e32 v72, v72
	v_rcp_f32_e32 v77, v77
	v_rcp_f32_e32 v73, v73
	v_rcp_f32_e32 v79, v79
	v_rcp_f32_e32 v75, v75
	v_rcp_f32_e32 v76, v76
	v_rcp_f32_e32 v78, v78
	v_rcp_f32_e32 v74, v74
	v_lshlrev_b32_e32 v95, 16, v226
	v_and_b32_e32 v80, 0xffff0000, v226
	v_lshlrev_b32_e32 v96, 16, v227
	v_and_b32_e32 v81, 0xffff0000, v227
	v_lshlrev_b32_e32 v97, 16, v228
	v_and_b32_e32 v82, 0xffff0000, v228
	v_lshlrev_b32_e32 v98, 16, v229
	v_and_b32_e32 v83, 0xffff0000, v229
	v_lshlrev_b32_e32 v100, 16, v221
	v_and_b32_e32 v85, 0xffff0000, v221
	v_lshlrev_b32_e32 v101, 16, v222
	v_and_b32_e32 v86, 0xffff0000, v222
	v_lshlrev_b32_e32 v102, 16, v223
	v_and_b32_e32 v87, 0xffff0000, v223
	v_fmac_f32_e32 v97, v72, v101
	v_fmac_f32_e32 v80, v77, v84
	v_fmac_f32_e32 v82, v73, v86
	v_fmac_f32_e32 v81, v79, v85
	v_fmac_f32_e32 v83, v75, v87
	v_lshl_add_u64 v[72:73], s[36:37], 0, v[88:89]
	v_fmac_f32_e32 v95, v76, v99
	v_fmac_f32_e32 v96, v78, v100
	v_fmac_f32_e32 v98, v74, v102
	v_cvt_pk_bf16_f32 v74, v95, v80
	v_cvt_pk_bf16_f32 v75, v96, v81
	v_cvt_pk_bf16_f32 v76, v97, v82
	v_cvt_pk_bf16_f32 v77, v98, v83
	v_mul_f32_e32 v68, v68, v224
	v_mul_f32_e32 v69, v69, v224
	v_mul_f32_e32 v64, v64, v224
	v_mul_f32_e32 v65, v65, v224
	v_mul_f32_e32 v70, v70, v224
	v_mul_f32_e32 v66, v66, v224
	v_mul_f32_e32 v71, v71, v224
	v_mul_f32_e32 v67, v67, v224
	v_mul_f32_e32 v68, 0xbfb8aa3b, v68
	v_mul_f32_e32 v69, 0xbfb8aa3b, v69
	v_mul_f32_e32 v64, 0xbfb8aa3b, v64
	v_mul_f32_e32 v65, 0xbfb8aa3b, v65
	v_mul_f32_e32 v70, 0xbfb8aa3b, v70
	v_mul_f32_e32 v66, 0xbfb8aa3b, v66
	v_mul_f32_e32 v71, 0xbfb8aa3b, v71
	v_mul_f32_e32 v67, 0xbfb8aa3b, v67
	v_exp_f32_e32 v68, v68
	v_exp_f32_e32 v69, v69
	v_exp_f32_e32 v64, v64
	v_exp_f32_e32 v65, v65
	v_exp_f32_e32 v70, v70
	v_exp_f32_e32 v66, v66
	v_exp_f32_e32 v71, v71
	v_exp_f32_e32 v67, v67
	v_add_f32_e32 v68, 1.0, v68
	v_add_f32_e32 v69, 1.0, v69
	v_add_u32_e32 v86, 0x80, v148
	v_add_f32_e32 v64, 1.0, v64
	v_add_f32_e32 v65, 1.0, v65
	v_add_f32_e32 v70, 1.0, v70
	v_add_f32_e32 v66, 1.0, v66
	v_add_f32_e32 v71, 1.0, v71
	v_add_f32_e32 v67, 1.0, v67
	v_rcp_f32_e32 v68, v68
	v_rcp_f32_e32 v69, v69
	v_ashrrev_i32_e32 v87, 31, v86
	v_rcp_f32_e32 v64, v64
	v_rcp_f32_e32 v65, v65
	v_rcp_f32_e32 v70, v70
	v_rcp_f32_e32 v66, v66
	v_rcp_f32_e32 v71, v71
	v_rcp_f32_e32 v67, v67
	v_lshlrev_b64 v[72:73], 11, v[86:87]
	v_lshl_add_u64 v[72:73], v[72:73], 0, v[150:151]
	global_store_dwordx4 v[90:91], v[74:77], off
	v_lshlrev_b64 v[72:73], 1, v[72:73]
	v_lshl_add_u64 v[88:89], s[40:41], 0, v[88:89]
	v_lshl_add_u64 v[92:93], s[34:35], 0, v[72:73]
	v_add_u32_e32 v240, 0xa0, v148
	v_ashrrev_i32_e32 v241, 31, v240
	v_lshlrev_b64 v[238:239], 11, v[240:241]
	v_lshl_add_u64 v[238:239], v[238:239], 0, v[150:151]
	v_lshlrev_b64 v[238:239], 1, v[238:239]
	v_lshl_add_u64 v[236:237], s[36:37], 0, v[238:239]
	global_load_dwordx4 v[220:223], v[236:237], off
	v_add_u32_e32 v238, 0xa0, v148
	v_ashrrev_i32_e32 v239, 31, v238
	v_lshl_add_u64 v[236:237], v[238:239], 2, s[26:27]
	global_load_dword v224, v[236:237], off
	v_add_u32_e32 v238, 0xa0, v148
	v_ashrrev_i32_e32 v239, 31, v238
	v_lshlrev_b64 v[236:237], 11, v[238:239]
	v_lshl_add_u64 v[236:237], v[236:237], 0, v[150:151]
	v_lshlrev_b64 v[236:237], 1, v[236:237]
	v_lshl_add_u64 v[240:241], s[34:35], 0, v[236:237]
	global_load_dwordx4 v[226:229], v[240:241], off
	s_waitcnt vmcnt(18)
	v_lshlrev_b32_e32 v74, 16, v178
	v_and_b32_e32 v75, 0xffff0000, v178
	v_lshlrev_b32_e32 v90, 16, v182
	v_and_b32_e32 v82, 0xffff0000, v182
	v_lshlrev_b32_e32 v76, 16, v179
	v_and_b32_e32 v77, 0xffff0000, v179
	v_lshlrev_b32_e32 v78, 16, v180
	v_and_b32_e32 v79, 0xffff0000, v180
	v_lshlrev_b32_e32 v80, 16, v181
	v_and_b32_e32 v81, 0xffff0000, v181
	v_lshlrev_b32_e32 v91, 16, v183
	v_and_b32_e32 v83, 0xffff0000, v183
	v_lshlrev_b32_e32 v94, 16, v184
	v_and_b32_e32 v84, 0xffff0000, v184
	v_lshlrev_b32_e32 v95, 16, v185
	v_and_b32_e32 v85, 0xffff0000, v185
	v_fmac_f32_e32 v74, v68, v90
	v_fmac_f32_e32 v75, v69, v82
	v_fmac_f32_e32 v78, v64, v94
	v_fmac_f32_e32 v79, v65, v84
	v_fmac_f32_e32 v76, v70, v91
	v_fmac_f32_e32 v80, v66, v95
	v_fmac_f32_e32 v77, v71, v83
	v_fmac_f32_e32 v81, v67, v85
	v_cvt_pk_bf16_f32 v64, v74, v75
	v_cvt_pk_bf16_f32 v65, v76, v77
	v_cvt_pk_bf16_f32 v66, v78, v79
	v_cvt_pk_bf16_f32 v67, v80, v81
	global_store_dwordx4 v[88:89], v[64:67], off
	v_lshl_add_u64 v[68:69], s[36:37], 0, v[72:73]
	v_lshl_add_u64 v[74:75], v[86:87], 2, s[26:27]
	s_nop 0
	v_lshl_add_u64 v[74:75], s[40:41], 0, v[72:73]
	v_or_b32_e32 v72, 0x100, v72
	v_lshl_add_u64 v[76:77], s[34:35], 0, v[72:73]
	v_add_u32_e32 v240, 0xa0, v148
	v_ashrrev_i32_e32 v241, 31, v240
	v_lshlrev_b64 v[236:237], 11, v[240:241]
	v_lshl_add_u64 v[236:237], v[236:237], 0, v[150:151]
	v_lshlrev_b64 v[236:237], 1, v[236:237]
	v_or_b32_e32 v236, 0x100, v236
	v_lshl_add_u64 v[238:239], s[34:35], 0, v[236:237]
	global_load_dwordx4 v[178:181], v[238:239], off
	v_add_u32_e32 v240, 0xa0, v148
	v_ashrrev_i32_e32 v241, 31, v240
	v_lshlrev_b64 v[238:239], 11, v[240:241]
	v_lshl_add_u64 v[238:239], v[238:239], 0, v[150:151]
	v_lshlrev_b64 v[238:239], 1, v[238:239]
	v_or_b32_e32 v238, 0x100, v238
	v_lshl_add_u64 v[236:237], s[36:37], 0, v[238:239]
	global_load_dwordx4 v[182:185], v[236:237], off
	s_waitcnt vmcnt(17)
; __device__ __forceinline__ f32x4 unpk4(uint2 u) { f32x4 r; r[0] = __uint_as_float(u.x << 16); r[1] = __uint_as_float(u.x & 0xffff0000u); r[2] = __uint_as_float(u.y << 16); r[3] = __uint_as_float(u.y & 0xffff0000u); return r; }
; __device__ __forceinline__ float sigm(float x) { return __builtin_amdgcn_rcpf(1.f + __expf(-x)); }
; __device__ __forceinline__ uint4 pk8(f32x4 a, f32x4 b) { return make_uint4(cvt_pk_bf16(a[0], a[1]), cvt_pk_bf16(a[2], a[3]), cvt_pk_bf16(b[0], b[1]), cvt_pk_bf16(b[2], b[3])); }
;     __device__ __forceinline__ void operator()(AccRef acc, const Unit& u, int wr, int wc, int fr, int fq) const {
;     ...
;         for (int ai = 0; ai < 2; ++ai)
; #pragma unroll
;             for (int m = 0; m < 4; ++m) {
;                 const int r = u.pm * 256 + ai * 128 + wr * 64 + m * 16 + fr;
;                 const float s = rinv[r];
;                 float ss = 0.f;
; #pragma unroll
;                 for (int bj = 0; bj < 2; ++bj) {
;                     const size_t o = (size_t)r * D + c0 + bj * 128;
;                     const uint4 h8 = *(const uint4*)(H2 + o);
;                     f32x4 v0 = unpk4(make_uint2(h8.x, h8.y)), v1 = unpk4(make_uint2(h8.z, h8.w));
;                     const uint4 pp8 = *(const uint4*)(PPb + o);
;                     const f32x4 p0 = unpk4(make_uint2(pp8.x, pp8.y)), p1 = unpk4(make_uint2(pp8.z, pp8.w));
; #pragma unroll
;                     for (int e = 0; e < 4; ++e) { v0[e] += sigm(acc[ai][bj][m][0][e] * s) * p0[e]; v1[e] += sigm(acc[ai][bj][m][1][e] * s) * p1[e]; }
;                     ss += v0[0] * v0[0] + v0[1] * v0[1] + v0[2] * v0[2] + v0[3] * v0[3] + v1[0] * v1[0] + v1[1] * v1[1] + v1[2] * v1[2] + v1[3] * v1[3];
;                     *(uint4*)(H3 + o) = pk8(v0, v1);
;                 }
	v_lshlrev_b32_e32 v83, 16, v186
	v_and_b32_e32 v68, 0xffff0000, v186
	v_mul_f32_e32 v56, v56, v190
	v_mul_f32_e32 v61, v61, v190
	v_mul_f32_e32 v57, v57, v190
	v_mul_f32_e32 v63, v63, v190
	v_mul_f32_e32 v59, v59, v190
	v_mul_f32_e32 v60, v60, v190
	v_mul_f32_e32 v62, v62, v190
	v_mul_f32_e32 v58, v58, v190
	v_mul_f32_e32 v56, 0xbfb8aa3b, v56
	v_mul_f32_e32 v61, 0xbfb8aa3b, v61
	v_mul_f32_e32 v57, 0xbfb8aa3b, v57
	v_mul_f32_e32 v63, 0xbfb8aa3b, v63
	v_mul_f32_e32 v59, 0xbfb8aa3b, v59
	v_mul_f32_e32 v60, 0xbfb8aa3b, v60
	v_mul_f32_e32 v62, 0xbfb8aa3b, v62
	v_mul_f32_e32 v58, 0xbfb8aa3b, v58
	v_exp_f32_e32 v56, v56
	v_exp_f32_e32 v61, v61
	v_exp_f32_e32 v57, v57
	v_exp_f32_e32 v63, v63
	v_exp_f32_e32 v59, v59
	v_exp_f32_e32 v60, v60
	v_exp_f32_e32 v62, v62
	v_exp_f32_e32 v58, v58
	v_add_f32_e32 v56, 1.0, v56
	v_add_f32_e32 v61, 1.0, v61
	v_add_f32_e32 v57, 1.0, v57
	v_add_f32_e32 v63, 1.0, v63
	v_add_f32_e32 v59, 1.0, v59
	v_add_f32_e32 v60, 1.0, v60
	v_add_f32_e32 v62, 1.0, v62
	v_add_f32_e32 v58, 1.0, v58
	v_rcp_f32_e32 v56, v56
	v_rcp_f32_e32 v61, v61
	v_rcp_f32_e32 v57, v57
	v_rcp_f32_e32 v63, v63
	v_rcp_f32_e32 v59, v59
	v_rcp_f32_e32 v60, v60
	v_rcp_f32_e32 v62, v62
	v_rcp_f32_e32 v58, v58
	v_lshlrev_b32_e32 v79, 16, v192
	v_and_b32_e32 v64, 0xffff0000, v192
	v_lshlrev_b32_e32 v80, 16, v193
	v_and_b32_e32 v65, 0xffff0000, v193
	v_lshlrev_b32_e32 v81, 16, v194
	v_and_b32_e32 v66, 0xffff0000, v194
	v_lshlrev_b32_e32 v82, 16, v195
	v_and_b32_e32 v67, 0xffff0000, v195
	v_lshlrev_b32_e32 v84, 16, v187
	v_and_b32_e32 v69, 0xffff0000, v187
	v_lshlrev_b32_e32 v85, 16, v188
	v_and_b32_e32 v70, 0xffff0000, v188
	v_lshlrev_b32_e32 v86, 16, v189
	v_and_b32_e32 v71, 0xffff0000, v189
	v_fmac_f32_e32 v81, v56, v85
	v_fmac_f32_e32 v64, v61, v68
	v_fmac_f32_e32 v66, v57, v70
	v_fmac_f32_e32 v65, v63, v69
	v_fmac_f32_e32 v67, v59, v71
	v_lshl_add_u64 v[56:57], s[36:37], 0, v[72:73]
	v_fmac_f32_e32 v79, v60, v83
	v_fmac_f32_e32 v80, v62, v84
	v_fmac_f32_e32 v82, v58, v86
	v_cvt_pk_bf16_f32 v58, v79, v64
	v_cvt_pk_bf16_f32 v59, v80, v65
	v_cvt_pk_bf16_f32 v60, v81, v66
	v_cvt_pk_bf16_f32 v61, v82, v67
	v_mul_f32_e32 v52, v52, v190
	v_mul_f32_e32 v53, v53, v190
	v_mul_f32_e32 v48, v48, v190
	v_mul_f32_e32 v49, v49, v190
	v_mul_f32_e32 v54, v54, v190
	v_mul_f32_e32 v50, v50, v190
	v_mul_f32_e32 v55, v55, v190
	v_mul_f32_e32 v51, v51, v190
	v_mul_f32_e32 v52, 0xbfb8aa3b, v52
	v_mul_f32_e32 v53, 0xbfb8aa3b, v53
	v_mul_f32_e32 v48, 0xbfb8aa3b, v48
	v_mul_f32_e32 v49, 0xbfb8aa3b, v49
	v_mul_f32_e32 v54, 0xbfb8aa3b, v54
	v_mul_f32_e32 v50, 0xbfb8aa3b, v50
	v_mul_f32_e32 v55, 0xbfb8aa3b, v55
	v_mul_f32_e32 v51, 0xbfb8aa3b, v51
	v_exp_f32_e32 v52, v52
	v_exp_f32_e32 v53, v53
	v_exp_f32_e32 v48, v48
	v_exp_f32_e32 v49, v49
	v_exp_f32_e32 v54, v54
	v_exp_f32_e32 v50, v50
	v_exp_f32_e32 v55, v55
	v_exp_f32_e32 v51, v51
	v_add_f32_e32 v52, 1.0, v52
	v_add_f32_e32 v53, 1.0, v53
	v_add_u32_e32 v70, 0x90, v148
	v_add_f32_e32 v48, 1.0, v48
	v_add_f32_e32 v49, 1.0, v49
	v_add_f32_e32 v54, 1.0, v54
	v_add_f32_e32 v50, 1.0, v50
	v_add_f32_e32 v55, 1.0, v55
	v_add_f32_e32 v51, 1.0, v51
	v_rcp_f32_e32 v52, v52
	v_rcp_f32_e32 v53, v53
	v_ashrrev_i32_e32 v71, 31, v70
	v_rcp_f32_e32 v48, v48
	v_rcp_f32_e32 v49, v49
	v_rcp_f32_e32 v54, v54
	v_rcp_f32_e32 v50, v50
	v_rcp_f32_e32 v55, v55
	v_rcp_f32_e32 v51, v51
	v_lshlrev_b64 v[56:57], 11, v[70:71]
	v_lshl_add_u64 v[56:57], v[56:57], 0, v[150:151]
	global_store_dwordx4 v[74:75], v[58:61], off
	v_lshlrev_b64 v[56:57], 1, v[56:57]
	v_lshl_add_u64 v[72:73], s[40:41], 0, v[72:73]
	v_lshl_add_u64 v[76:77], s[34:35], 0, v[56:57]
	v_add_u32_e32 v240, 0xb0, v148
	v_ashrrev_i32_e32 v241, 31, v240
	v_lshlrev_b64 v[238:239], 11, v[240:241]
	v_lshl_add_u64 v[238:239], v[238:239], 0, v[150:151]
	v_lshlrev_b64 v[238:239], 1, v[238:239]
	v_lshl_add_u64 v[236:237], s[36:37], 0, v[238:239]
	global_load_dwordx4 v[186:189], v[236:237], off
	v_add_u32_e32 v238, 0xb0, v148
	v_ashrrev_i32_e32 v239, 31, v238
	v_lshl_add_u64 v[236:237], v[238:239], 2, s[26:27]
	global_load_dword v190, v[236:237], off
	v_add_u32_e32 v238, 0xb0, v148
	v_ashrrev_i32_e32 v239, 31, v238
	v_lshlrev_b64 v[236:237], 11, v[238:239]
	v_lshl_add_u64 v[236:237], v[236:237], 0, v[150:151]
	v_lshlrev_b64 v[236:237], 1, v[236:237]
	v_lshl_add_u64 v[240:241], s[34:35], 0, v[236:237]
	global_load_dwordx4 v[192:195], v[240:241], off
	s_waitcnt vmcnt(18)
	v_lshlrev_b32_e32 v58, 16, v196
	v_and_b32_e32 v59, 0xffff0000, v196
	v_lshlrev_b32_e32 v74, 16, v200
	v_and_b32_e32 v66, 0xffff0000, v200
	v_lshlrev_b32_e32 v60, 16, v197
	v_and_b32_e32 v61, 0xffff0000, v197
	v_lshlrev_b32_e32 v62, 16, v198
	v_and_b32_e32 v63, 0xffff0000, v198
	v_lshlrev_b32_e32 v64, 16, v199
	v_and_b32_e32 v65, 0xffff0000, v199
	v_lshlrev_b32_e32 v75, 16, v201
	v_and_b32_e32 v67, 0xffff0000, v201
	v_lshlrev_b32_e32 v78, 16, v202
	v_and_b32_e32 v68, 0xffff0000, v202
	v_lshlrev_b32_e32 v79, 16, v203
	v_and_b32_e32 v69, 0xffff0000, v203
	v_fmac_f32_e32 v58, v52, v74
	v_fmac_f32_e32 v59, v53, v66
	v_fmac_f32_e32 v62, v48, v78
	v_fmac_f32_e32 v63, v49, v68
	v_fmac_f32_e32 v60, v54, v75
	v_fmac_f32_e32 v64, v50, v79
	v_fmac_f32_e32 v61, v55, v67
	v_fmac_f32_e32 v65, v51, v69
	v_cvt_pk_bf16_f32 v48, v58, v59
	v_cvt_pk_bf16_f32 v49, v60, v61
	v_cvt_pk_bf16_f32 v50, v62, v63
	v_cvt_pk_bf16_f32 v51, v64, v65
	global_store_dwordx4 v[72:73], v[48:51], off
	v_lshl_add_u64 v[52:53], s[36:37], 0, v[56:57]
	v_lshl_add_u64 v[58:59], v[70:71], 2, s[26:27]
	s_nop 0
	v_lshl_add_u64 v[58:59], s[40:41], 0, v[56:57]
	v_or_b32_e32 v56, 0x100, v56
	v_lshl_add_u64 v[60:61], s[34:35], 0, v[56:57]
	v_add_u32_e32 v240, 0xb0, v148
	v_ashrrev_i32_e32 v241, 31, v240
	v_lshlrev_b64 v[236:237], 11, v[240:241]
	v_lshl_add_u64 v[236:237], v[236:237], 0, v[150:151]
	v_lshlrev_b64 v[236:237], 1, v[236:237]
	v_or_b32_e32 v236, 0x100, v236
	v_lshl_add_u64 v[238:239], s[34:35], 0, v[236:237]
	global_load_dwordx4 v[196:199], v[238:239], off
	v_add_u32_e32 v240, 0xb0, v148
	v_ashrrev_i32_e32 v241, 31, v240
	v_lshlrev_b64 v[238:239], 11, v[240:241]
	v_lshl_add_u64 v[238:239], v[238:239], 0, v[150:151]
	v_lshlrev_b64 v[238:239], 1, v[238:239]
	v_or_b32_e32 v238, 0x100, v238
	v_lshl_add_u64 v[236:237], s[36:37], 0, v[238:239]
	global_load_dwordx4 v[200:203], v[236:237], off
	s_waitcnt vmcnt(17)
; __device__ __forceinline__ f32x4 unpk4(uint2 u) { f32x4 r; r[0] = __uint_as_float(u.x << 16); r[1] = __uint_as_float(u.x & 0xffff0000u); r[2] = __uint_as_float(u.y << 16); r[3] = __uint_as_float(u.y & 0xffff0000u); return r; }
; __device__ __forceinline__ float sigm(float x) { return __builtin_amdgcn_rcpf(1.f + __expf(-x)); }
; __device__ __forceinline__ uint4 pk8(f32x4 a, f32x4 b) { return make_uint4(cvt_pk_bf16(a[0], a[1]), cvt_pk_bf16(a[2], a[3]), cvt_pk_bf16(b[0], b[1]), cvt_pk_bf16(b[2], b[3])); }
;     __device__ __forceinline__ void operator()(AccRef acc, const Unit& u, int wr, int wc, int fr, int fq) const {
;     ...
;         for (int ai = 0; ai < 2; ++ai)
; #pragma unroll
;             for (int m = 0; m < 4; ++m) {
;                 const int r = u.pm * 256 + ai * 128 + wr * 64 + m * 16 + fr;
;                 const float s = rinv[r];
;                 float ss = 0.f;
; #pragma unroll
;                 for (int bj = 0; bj < 2; ++bj) {
;                     const size_t o = (size_t)r * D + c0 + bj * 128;
;                     const uint4 h8 = *(const uint4*)(H2 + o);
;                     f32x4 v0 = unpk4(make_uint2(h8.x, h8.y)), v1 = unpk4(make_uint2(h8.z, h8.w));
;                     const uint4 pp8 = *(const uint4*)(PPb + o);
;                     const f32x4 p0 = unpk4(make_uint2(pp8.x, pp8.y)), p1 = unpk4(make_uint2(pp8.z, pp8.w));
; #pragma unroll
;                     for (int e = 0; e < 4; ++e) { v0[e] += sigm(acc[ai][bj][m][0][e] * s) * p0[e]; v1[e] += sigm(acc[ai][bj][m][1][e] * s) * p1[e]; }
;                     ss += v0[0] * v0[0] + v0[1] * v0[1] + v0[2] * v0[2] + v0[3] * v0[3] + v1[0] * v1[0] + v1[1] * v1[1] + v1[2] * v1[2] + v1[3] * v1[3];
;                     *(uint4*)(H3 + o) = pk8(v0, v1);
;                 }
	v_lshlrev_b32_e32 v67, 16, v204
	v_and_b32_e32 v52, 0xffff0000, v204
	v_mul_f32_e32 v40, v40, v191
	v_mul_f32_e32 v45, v45, v191
	v_mul_f32_e32 v41, v41, v191
	v_mul_f32_e32 v47, v47, v191
	v_mul_f32_e32 v43, v43, v191
	v_mul_f32_e32 v44, v44, v191
	v_mul_f32_e32 v46, v46, v191
	v_mul_f32_e32 v42, v42, v191
	v_mul_f32_e32 v40, 0xbfb8aa3b, v40
	v_mul_f32_e32 v45, 0xbfb8aa3b, v45
	v_mul_f32_e32 v41, 0xbfb8aa3b, v41
	v_mul_f32_e32 v47, 0xbfb8aa3b, v47
	v_mul_f32_e32 v43, 0xbfb8aa3b, v43
	v_mul_f32_e32 v44, 0xbfb8aa3b, v44
	v_mul_f32_e32 v46, 0xbfb8aa3b, v46
	v_mul_f32_e32 v42, 0xbfb8aa3b, v42
	v_exp_f32_e32 v40, v40
	v_exp_f32_e32 v45, v45
	v_exp_f32_e32 v41, v41
	v_exp_f32_e32 v47, v47
	v_exp_f32_e32 v43, v43
	v_exp_f32_e32 v44, v44
	v_exp_f32_e32 v46, v46
	v_exp_f32_e32 v42, v42
	v_add_f32_e32 v40, 1.0, v40
	v_add_f32_e32 v45, 1.0, v45
	v_add_f32_e32 v41, 1.0, v41
	v_add_f32_e32 v47, 1.0, v47
	v_add_f32_e32 v43, 1.0, v43
	v_add_f32_e32 v44, 1.0, v44
	v_add_f32_e32 v46, 1.0, v46
	v_add_f32_e32 v42, 1.0, v42
	v_rcp_f32_e32 v40, v40
	v_rcp_f32_e32 v45, v45
	v_rcp_f32_e32 v41, v41
	v_rcp_f32_e32 v47, v47
	v_rcp_f32_e32 v43, v43
	v_rcp_f32_e32 v44, v44
	v_rcp_f32_e32 v46, v46
	v_rcp_f32_e32 v42, v42
	v_lshlrev_b32_e32 v63, 16, v208
	v_and_b32_e32 v48, 0xffff0000, v208
	v_lshlrev_b32_e32 v64, 16, v209
	v_and_b32_e32 v49, 0xffff0000, v209
	v_lshlrev_b32_e32 v65, 16, v210
	v_and_b32_e32 v50, 0xffff0000, v210
	v_lshlrev_b32_e32 v66, 16, v211
	v_and_b32_e32 v51, 0xffff0000, v211
	v_lshlrev_b32_e32 v68, 16, v205
	v_and_b32_e32 v53, 0xffff0000, v205
	v_lshlrev_b32_e32 v69, 16, v206
	v_and_b32_e32 v54, 0xffff0000, v206
	v_lshlrev_b32_e32 v70, 16, v207
	v_and_b32_e32 v55, 0xffff0000, v207
	v_fmac_f32_e32 v65, v40, v69
	v_fmac_f32_e32 v48, v45, v52
	v_fmac_f32_e32 v50, v41, v54
	v_fmac_f32_e32 v49, v47, v53
	v_fmac_f32_e32 v51, v43, v55
	v_lshl_add_u64 v[40:41], s[36:37], 0, v[56:57]
	v_fmac_f32_e32 v63, v44, v67
	v_fmac_f32_e32 v64, v46, v68
	v_fmac_f32_e32 v66, v42, v70
	v_cvt_pk_bf16_f32 v42, v63, v48
	v_cvt_pk_bf16_f32 v43, v64, v49
	v_cvt_pk_bf16_f32 v44, v65, v50
	v_cvt_pk_bf16_f32 v45, v66, v51
	v_mul_f32_e32 v36, v36, v191
	v_mul_f32_e32 v37, v37, v191
	v_mul_f32_e32 v32, v32, v191
	v_mul_f32_e32 v33, v33, v191
	v_mul_f32_e32 v38, v38, v191
	v_mul_f32_e32 v34, v34, v191
	v_mul_f32_e32 v39, v39, v191
	v_mul_f32_e32 v35, v35, v191
	v_mul_f32_e32 v36, 0xbfb8aa3b, v36
	v_mul_f32_e32 v37, 0xbfb8aa3b, v37
	v_mul_f32_e32 v32, 0xbfb8aa3b, v32
	v_mul_f32_e32 v33, 0xbfb8aa3b, v33
	v_mul_f32_e32 v38, 0xbfb8aa3b, v38
	v_mul_f32_e32 v34, 0xbfb8aa3b, v34
	v_mul_f32_e32 v39, 0xbfb8aa3b, v39
	v_mul_f32_e32 v35, 0xbfb8aa3b, v35
	v_exp_f32_e32 v36, v36
	v_exp_f32_e32 v37, v37
	v_exp_f32_e32 v32, v32
	v_exp_f32_e32 v33, v33
	v_exp_f32_e32 v38, v38
	v_exp_f32_e32 v34, v34
	v_exp_f32_e32 v39, v39
	v_exp_f32_e32 v35, v35
	v_add_f32_e32 v36, 1.0, v36
	v_add_f32_e32 v37, 1.0, v37
	v_add_u32_e32 v54, 0xa0, v148
	v_add_f32_e32 v32, 1.0, v32
	v_add_f32_e32 v33, 1.0, v33
	v_add_f32_e32 v38, 1.0, v38
	v_add_f32_e32 v34, 1.0, v34
	v_add_f32_e32 v39, 1.0, v39
	v_add_f32_e32 v35, 1.0, v35
	v_rcp_f32_e32 v36, v36
	v_rcp_f32_e32 v37, v37
	v_ashrrev_i32_e32 v55, 31, v54
	v_rcp_f32_e32 v32, v32
	v_rcp_f32_e32 v33, v33
	v_rcp_f32_e32 v38, v38
	v_rcp_f32_e32 v34, v34
	v_rcp_f32_e32 v39, v39
	v_rcp_f32_e32 v35, v35
	v_lshlrev_b64 v[40:41], 11, v[54:55]
	v_lshl_add_u64 v[40:41], v[40:41], 0, v[150:151]
	global_store_dwordx4 v[58:59], v[42:45], off
	v_lshlrev_b64 v[40:41], 1, v[40:41]
	v_lshl_add_u64 v[56:57], s[40:41], 0, v[56:57]
	v_lshl_add_u64 v[60:61], s[34:35], 0, v[40:41]
	s_waitcnt vmcnt(15)
	v_lshlrev_b32_e32 v42, 16, v212
	v_and_b32_e32 v43, 0xffff0000, v212
	v_lshlrev_b32_e32 v58, 16, v216
	v_and_b32_e32 v50, 0xffff0000, v216
	v_lshlrev_b32_e32 v44, 16, v213
	v_and_b32_e32 v45, 0xffff0000, v213
	v_lshlrev_b32_e32 v46, 16, v214
	v_and_b32_e32 v47, 0xffff0000, v214
	v_lshlrev_b32_e32 v48, 16, v215
	v_and_b32_e32 v49, 0xffff0000, v215
	v_lshlrev_b32_e32 v59, 16, v217
	v_and_b32_e32 v51, 0xffff0000, v217
	v_lshlrev_b32_e32 v62, 16, v218
	v_and_b32_e32 v52, 0xffff0000, v218
	v_lshlrev_b32_e32 v63, 16, v219
	v_and_b32_e32 v53, 0xffff0000, v219
	v_fmac_f32_e32 v42, v36, v58
	v_fmac_f32_e32 v43, v37, v50
	v_fmac_f32_e32 v46, v32, v62
	v_fmac_f32_e32 v47, v33, v52
	v_fmac_f32_e32 v44, v38, v59
	v_fmac_f32_e32 v48, v34, v63
	v_fmac_f32_e32 v45, v39, v51
	v_fmac_f32_e32 v49, v35, v53
	v_cvt_pk_bf16_f32 v32, v42, v43
	v_cvt_pk_bf16_f32 v33, v44, v45
	v_cvt_pk_bf16_f32 v34, v46, v47
	v_cvt_pk_bf16_f32 v35, v48, v49
	global_store_dwordx4 v[56:57], v[32:35], off
	v_lshl_add_u64 v[36:37], s[36:37], 0, v[40:41]
	v_lshl_add_u64 v[42:43], v[54:55], 2, s[26:27]
	s_nop 0
	v_lshl_add_u64 v[42:43], s[40:41], 0, v[40:41]
	v_or_b32_e32 v40, 0x100, v40
	v_lshl_add_u64 v[44:45], s[34:35], 0, v[40:41]
	s_waitcnt vmcnt(12)
; __device__ __forceinline__ f32x4 unpk4(uint2 u) { f32x4 r; r[0] = __uint_as_float(u.x << 16); r[1] = __uint_as_float(u.x & 0xffff0000u); r[2] = __uint_as_float(u.y << 16); r[3] = __uint_as_float(u.y & 0xffff0000u); return r; }
; __device__ __forceinline__ float sigm(float x) { return __builtin_amdgcn_rcpf(1.f + __expf(-x)); }
; __device__ __forceinline__ uint4 pk8(f32x4 a, f32x4 b) { return make_uint4(cvt_pk_bf16(a[0], a[1]), cvt_pk_bf16(a[2], a[3]), cvt_pk_bf16(b[0], b[1]), cvt_pk_bf16(b[2], b[3])); }
;     __device__ __forceinline__ void operator()(AccRef acc, const Unit& u, int wr, int wc, int fr, int fq) const {
;     ...
;         for (int ai = 0; ai < 2; ++ai)
; #pragma unroll
;             for (int m = 0; m < 4; ++m) {
;                 const int r = u.pm * 256 + ai * 128 + wr * 64 + m * 16 + fr;
;                 const float s = rinv[r];
;                 float ss = 0.f;
; #pragma unroll
;                 for (int bj = 0; bj < 2; ++bj) {
;                     const size_t o = (size_t)r * D + c0 + bj * 128;
;                     const uint4 h8 = *(const uint4*)(H2 + o);
;                     f32x4 v0 = unpk4(make_uint2(h8.x, h8.y)), v1 = unpk4(make_uint2(h8.z, h8.w));
;                     const uint4 pp8 = *(const uint4*)(PPb + o);
;                     const f32x4 p0 = unpk4(make_uint2(pp8.x, pp8.y)), p1 = unpk4(make_uint2(pp8.z, pp8.w));
; #pragma unroll
;                     for (int e = 0; e < 4; ++e) { v0[e] += sigm(acc[ai][bj][m][0][e] * s) * p0[e]; v1[e] += sigm(acc[ai][bj][m][1][e] * s) * p1[e]; }
;                     ss += v0[0] * v0[0] + v0[1] * v0[1] + v0[2] * v0[2] + v0[3] * v0[3] + v1[0] * v1[0] + v1[1] * v1[1] + v1[2] * v1[2] + v1[3] * v1[3];
;                     *(uint4*)(H3 + o) = pk8(v0, v1);
;                 }
	v_lshlrev_b32_e32 v51, 16, v220
	v_and_b32_e32 v36, 0xffff0000, v220
	v_mul_f32_e32 v24, v24, v224
	v_mul_f32_e32 v29, v29, v224
	v_mul_f32_e32 v25, v25, v224
	v_mul_f32_e32 v31, v31, v224
	v_mul_f32_e32 v27, v27, v224
	v_mul_f32_e32 v28, v28, v224
	v_mul_f32_e32 v30, v30, v224
	v_mul_f32_e32 v26, v26, v224
	v_mul_f32_e32 v24, 0xbfb8aa3b, v24
	v_mul_f32_e32 v29, 0xbfb8aa3b, v29
	v_mul_f32_e32 v25, 0xbfb8aa3b, v25
	v_mul_f32_e32 v31, 0xbfb8aa3b, v31
	v_mul_f32_e32 v27, 0xbfb8aa3b, v27
	v_mul_f32_e32 v28, 0xbfb8aa3b, v28
	v_mul_f32_e32 v30, 0xbfb8aa3b, v30
	v_mul_f32_e32 v26, 0xbfb8aa3b, v26
	v_exp_f32_e32 v24, v24
	v_exp_f32_e32 v29, v29
	v_exp_f32_e32 v25, v25
	v_exp_f32_e32 v31, v31
	v_exp_f32_e32 v27, v27
	v_exp_f32_e32 v28, v28
	v_exp_f32_e32 v30, v30
	v_exp_f32_e32 v26, v26
	v_add_f32_e32 v24, 1.0, v24
	v_add_f32_e32 v29, 1.0, v29
	v_add_f32_e32 v25, 1.0, v25
	v_add_f32_e32 v31, 1.0, v31
	v_add_f32_e32 v27, 1.0, v27
	v_add_f32_e32 v28, 1.0, v28
	v_add_f32_e32 v30, 1.0, v30
	v_add_f32_e32 v26, 1.0, v26
	v_rcp_f32_e32 v24, v24
	v_rcp_f32_e32 v29, v29
	v_rcp_f32_e32 v25, v25
	v_rcp_f32_e32 v31, v31
	v_rcp_f32_e32 v27, v27
	v_rcp_f32_e32 v28, v28
	v_rcp_f32_e32 v30, v30
	v_rcp_f32_e32 v26, v26
	v_lshlrev_b32_e32 v47, 16, v226
	v_and_b32_e32 v32, 0xffff0000, v226
	v_lshlrev_b32_e32 v48, 16, v227
	v_and_b32_e32 v33, 0xffff0000, v227
	v_lshlrev_b32_e32 v49, 16, v228
	v_and_b32_e32 v34, 0xffff0000, v228
	v_lshlrev_b32_e32 v50, 16, v229
	v_and_b32_e32 v35, 0xffff0000, v229
	v_lshlrev_b32_e32 v52, 16, v221
	v_and_b32_e32 v37, 0xffff0000, v221
	v_lshlrev_b32_e32 v53, 16, v222
	v_and_b32_e32 v38, 0xffff0000, v222
	v_lshlrev_b32_e32 v54, 16, v223
	v_and_b32_e32 v39, 0xffff0000, v223
	v_fmac_f32_e32 v49, v24, v53
	v_fmac_f32_e32 v32, v29, v36
	v_fmac_f32_e32 v34, v25, v38
	v_fmac_f32_e32 v33, v31, v37
	v_fmac_f32_e32 v35, v27, v39
	v_lshl_add_u64 v[24:25], s[36:37], 0, v[40:41]
	v_fmac_f32_e32 v47, v28, v51
	v_fmac_f32_e32 v48, v30, v52
	v_fmac_f32_e32 v50, v26, v54
	v_cvt_pk_bf16_f32 v26, v47, v32
	v_cvt_pk_bf16_f32 v27, v48, v33
	v_cvt_pk_bf16_f32 v28, v49, v34
	v_cvt_pk_bf16_f32 v29, v50, v35
	v_mul_f32_e32 v20, v20, v224
	v_mul_f32_e32 v21, v21, v224
	v_mul_f32_e32 v16, v16, v224
	v_mul_f32_e32 v17, v17, v224
	v_mul_f32_e32 v22, v22, v224
	v_mul_f32_e32 v18, v18, v224
	v_mul_f32_e32 v23, v23, v224
	v_mul_f32_e32 v19, v19, v224
	v_mul_f32_e32 v20, 0xbfb8aa3b, v20
	v_mul_f32_e32 v21, 0xbfb8aa3b, v21
	v_mul_f32_e32 v16, 0xbfb8aa3b, v16
	v_mul_f32_e32 v17, 0xbfb8aa3b, v17
	v_mul_f32_e32 v22, 0xbfb8aa3b, v22
	v_mul_f32_e32 v18, 0xbfb8aa3b, v18
	v_mul_f32_e32 v23, 0xbfb8aa3b, v23
	v_mul_f32_e32 v19, 0xbfb8aa3b, v19
	v_exp_f32_e32 v20, v20
	v_exp_f32_e32 v21, v21
	v_exp_f32_e32 v16, v16
	v_exp_f32_e32 v17, v17
	v_exp_f32_e32 v22, v22
	v_exp_f32_e32 v18, v18
	v_exp_f32_e32 v23, v23
	v_exp_f32_e32 v19, v19
	v_add_f32_e32 v20, 1.0, v20
	v_add_f32_e32 v21, 1.0, v21
	v_add_u32_e32 v38, 0xb0, v148
	v_add_f32_e32 v16, 1.0, v16
	v_add_f32_e32 v17, 1.0, v17
	v_add_f32_e32 v22, 1.0, v22
	v_add_f32_e32 v18, 1.0, v18
	v_add_f32_e32 v23, 1.0, v23
	v_add_f32_e32 v19, 1.0, v19
	v_rcp_f32_e32 v20, v20
	v_rcp_f32_e32 v21, v21
	v_ashrrev_i32_e32 v39, 31, v38
	v_rcp_f32_e32 v16, v16
	v_rcp_f32_e32 v17, v17
	v_rcp_f32_e32 v22, v22
	v_rcp_f32_e32 v18, v18
	v_rcp_f32_e32 v23, v23
	v_rcp_f32_e32 v19, v19
	v_lshlrev_b64 v[24:25], 11, v[38:39]
	v_lshl_add_u64 v[24:25], v[24:25], 0, v[150:151]
	global_store_dwordx4 v[42:43], v[26:29], off
	v_lshlrev_b64 v[24:25], 1, v[24:25]
	v_lshl_add_u64 v[40:41], s[40:41], 0, v[40:41]
	v_lshl_add_u64 v[44:45], s[34:35], 0, v[24:25]
	s_waitcnt vmcnt(10)
	v_lshlrev_b32_e32 v26, 16, v178
	v_and_b32_e32 v27, 0xffff0000, v178
	v_lshlrev_b32_e32 v42, 16, v182
	v_and_b32_e32 v34, 0xffff0000, v182
	v_lshlrev_b32_e32 v28, 16, v179
	v_and_b32_e32 v29, 0xffff0000, v179
	v_lshlrev_b32_e32 v30, 16, v180
	v_and_b32_e32 v31, 0xffff0000, v180
	v_lshlrev_b32_e32 v32, 16, v181
	v_and_b32_e32 v33, 0xffff0000, v181
	v_lshlrev_b32_e32 v43, 16, v183
	v_and_b32_e32 v35, 0xffff0000, v183
	v_lshlrev_b32_e32 v46, 16, v184
	v_and_b32_e32 v36, 0xffff0000, v184
	v_lshlrev_b32_e32 v47, 16, v185
	v_and_b32_e32 v37, 0xffff0000, v185
	v_fmac_f32_e32 v26, v20, v42
	v_fmac_f32_e32 v27, v21, v34
	v_fmac_f32_e32 v30, v16, v46
	v_fmac_f32_e32 v31, v17, v36
	v_fmac_f32_e32 v28, v22, v43
	v_fmac_f32_e32 v32, v18, v47
	v_fmac_f32_e32 v29, v23, v35
	v_fmac_f32_e32 v33, v19, v37
	v_cvt_pk_bf16_f32 v16, v26, v27
	v_cvt_pk_bf16_f32 v17, v28, v29
	v_cvt_pk_bf16_f32 v18, v30, v31
	v_cvt_pk_bf16_f32 v19, v32, v33
	global_store_dwordx4 v[40:41], v[16:19], off
	v_lshl_add_u64 v[20:21], s[36:37], 0, v[24:25]
	v_lshl_add_u64 v[26:27], v[38:39], 2, s[26:27]
	s_nop 0
	v_lshl_add_u64 v[26:27], s[40:41], 0, v[24:25]
	v_or_b32_e32 v24, 0x100, v24
	v_lshl_add_u64 v[28:29], s[34:35], 0, v[24:25]
	s_waitcnt vmcnt(7)
; #define PG8_WAIT_V(n) asm volatile("s_waitcnt vmcnt(" #n ")" ::: "memory")
; #define PG8_BAR __builtin_amdgcn_s_barrier()
; __device__ __forceinline__ f32x4 unpk4(uint2 u) { f32x4 r; r[0] = __uint_as_float(u.x << 16); r[1] = __uint_as_float(u.x & 0xffff0000u); r[2] = __uint_as_float(u.y << 16); r[3] = __uint_as_float(u.y & 0xffff0000u); return r; }
; __device__ __forceinline__ float sigm(float x) { return __builtin_amdgcn_rcpf(1.f + __expf(-x)); }
; __device__ __forceinline__ uint4 pk8(f32x4 a, f32x4 b) { return make_uint4(cvt_pk_bf16(a[0], a[1]), cvt_pk_bf16(a[2], a[3]), cvt_pk_bf16(b[0], b[1]), cvt_pk_bf16(b[2], b[3])); }
; template <class Epi, class Sched>
; __device__ __forceinline__ void gemm_phase(PG8_LAS unsigned char* lds, const Gemm g, const Sched& S, const Epi& E) {
;     ...
;     PG8_WAIT_V(0);
;     if (wr == 0) PG8_BAR;
;     PG8_BAR;
;     __device__ __forceinline__ void operator()(AccRef acc, const Unit& u, int wr, int wc, int fr, int fq) const {
;     ...
;         for (int ai = 0; ai < 2; ++ai)
; #pragma unroll
;             for (int m = 0; m < 4; ++m) {
;                 const int r = u.pm * 256 + ai * 128 + wr * 64 + m * 16 + fr;
;                 const float s = rinv[r];
;                 float ss = 0.f;
; #pragma unroll
;                 for (int bj = 0; bj < 2; ++bj) {
;                     const size_t o = (size_t)r * D + c0 + bj * 128;
;                     const uint4 h8 = *(const uint4*)(H2 + o);
;                     f32x4 v0 = unpk4(make_uint2(h8.x, h8.y)), v1 = unpk4(make_uint2(h8.z, h8.w));
;                     const uint4 pp8 = *(const uint4*)(PPb + o);
;                     const f32x4 p0 = unpk4(make_uint2(pp8.x, pp8.y)), p1 = unpk4(make_uint2(pp8.z, pp8.w));
; #pragma unroll
;                     for (int e = 0; e < 4; ++e) { v0[e] += sigm(acc[ai][bj][m][0][e] * s) * p0[e]; v1[e] += sigm(acc[ai][bj][m][1][e] * s) * p1[e]; }
;                     ss += v0[0] * v0[0] + v0[1] * v0[1] + v0[2] * v0[2] + v0[3] * v0[3] + v1[0] * v1[0] + v1[1] * v1[1] + v1[2] * v1[2] + v1[3] * v1[3];
;                     *(uint4*)(H3 + o) = pk8(v0, v1);
;                 }
	v_lshlrev_b32_e32 v35, 16, v186
	v_and_b32_e32 v20, 0xffff0000, v186
	v_mul_f32_e32 v13, v13, v190
	v_mul_f32_e32 v15, v15, v190
	v_mul_f32_e32 v12, v12, v190
	v_mul_f32_e32 v8, v8, v190
	v_mul_f32_e32 v9, v9, v190
	v_mul_f32_e32 v14, v14, v190
	v_mul_f32_e32 v11, v11, v190
	v_mul_f32_e32 v13, 0xbfb8aa3b, v13
	v_mul_f32_e32 v15, 0xbfb8aa3b, v15
	v_mul_f32_e32 v10, v10, v190
	v_mul_f32_e32 v12, 0xbfb8aa3b, v12
	v_mul_f32_e32 v8, 0xbfb8aa3b, v8
	v_mul_f32_e32 v9, 0xbfb8aa3b, v9
	v_mul_f32_e32 v14, 0xbfb8aa3b, v14
	v_mul_f32_e32 v11, 0xbfb8aa3b, v11
	v_exp_f32_e32 v13, v13
	v_exp_f32_e32 v15, v15
	v_mul_f32_e32 v10, 0xbfb8aa3b, v10
	v_exp_f32_e32 v12, v12
	v_exp_f32_e32 v8, v8
	v_exp_f32_e32 v9, v9
	v_exp_f32_e32 v14, v14
	v_exp_f32_e32 v11, v11
	v_exp_f32_e32 v10, v10
	v_add_f32_e32 v13, 1.0, v13
	v_add_f32_e32 v15, 1.0, v15
	v_add_f32_e32 v12, 1.0, v12
	v_add_f32_e32 v8, 1.0, v8
	v_add_f32_e32 v9, 1.0, v9
	v_add_f32_e32 v14, 1.0, v14
	v_add_f32_e32 v11, 1.0, v11
	v_rcp_f32_e32 v13, v13
	v_rcp_f32_e32 v15, v15
	v_add_f32_e32 v10, 1.0, v10
	v_rcp_f32_e32 v12, v12
	v_rcp_f32_e32 v8, v8
	v_rcp_f32_e32 v9, v9
	v_rcp_f32_e32 v14, v14
	v_rcp_f32_e32 v11, v11
	v_rcp_f32_e32 v10, v10
	v_lshlrev_b32_e32 v31, 16, v192
	v_and_b32_e32 v16, 0xffff0000, v192
	v_lshlrev_b32_e32 v32, 16, v193
	v_and_b32_e32 v17, 0xffff0000, v193
	v_lshlrev_b32_e32 v36, 16, v187
	v_and_b32_e32 v21, 0xffff0000, v187
	v_lshlrev_b32_e32 v33, 16, v194
	v_and_b32_e32 v18, 0xffff0000, v194
	v_lshlrev_b32_e32 v34, 16, v195
	v_and_b32_e32 v19, 0xffff0000, v195
	v_lshlrev_b32_e32 v37, 16, v188
	v_and_b32_e32 v22, 0xffff0000, v188
	v_lshlrev_b32_e32 v38, 16, v189
	v_and_b32_e32 v23, 0xffff0000, v189
	v_fmac_f32_e32 v16, v13, v20
	v_fmac_f32_e32 v17, v15, v21
	v_fmac_f32_e32 v31, v12, v35
	v_fmac_f32_e32 v33, v8, v37
	v_fmac_f32_e32 v18, v9, v22
	v_fmac_f32_e32 v32, v14, v36
	v_fmac_f32_e32 v19, v11, v23
	v_cvt_pk_bf16_f32 v8, v31, v16
	v_cvt_pk_bf16_f32 v9, v32, v17
	v_lshl_add_u64 v[16:17], s[36:37], 0, v[24:25]
	v_fmac_f32_e32 v34, v10, v38
	v_cvt_pk_bf16_f32 v10, v33, v18
	v_cvt_pk_bf16_f32 v11, v34, v19
	v_mul_f32_e32 v4, v4, v190
	v_mul_f32_e32 v0, v0, v190
	v_mul_f32_e32 v5, v5, v190
	v_mul_f32_e32 v1, v1, v190
	v_mul_f32_e32 v6, v6, v190
	v_mul_f32_e32 v2, v2, v190
	v_mul_f32_e32 v7, v7, v190
	v_mul_f32_e32 v3, v3, v190
	v_mul_f32_e32 v4, 0xbfb8aa3b, v4
	v_mul_f32_e32 v0, 0xbfb8aa3b, v0
	v_mul_f32_e32 v5, 0xbfb8aa3b, v5
	v_mul_f32_e32 v1, 0xbfb8aa3b, v1
	v_mul_f32_e32 v6, 0xbfb8aa3b, v6
	v_mul_f32_e32 v2, 0xbfb8aa3b, v2
	v_mul_f32_e32 v7, 0xbfb8aa3b, v7
	v_mul_f32_e32 v3, 0xbfb8aa3b, v3
	v_exp_f32_e32 v4, v4
	v_exp_f32_e32 v0, v0
	v_exp_f32_e32 v5, v5
	v_exp_f32_e32 v1, v1
	v_exp_f32_e32 v6, v6
	v_exp_f32_e32 v2, v2
	v_exp_f32_e32 v7, v7
	v_exp_f32_e32 v3, v3
	v_add_f32_e32 v4, 1.0, v4
	v_add_f32_e32 v0, 1.0, v0
	v_add_f32_e32 v5, 1.0, v5
	v_add_f32_e32 v1, 1.0, v1
	v_add_f32_e32 v6, 1.0, v6
	v_add_f32_e32 v2, 1.0, v2
	v_add_f32_e32 v7, 1.0, v7
	v_add_f32_e32 v3, 1.0, v3
	v_rcp_f32_e32 v4, v4
	v_rcp_f32_e32 v0, v0
	v_rcp_f32_e32 v5, v5
	v_rcp_f32_e32 v1, v1
	v_rcp_f32_e32 v6, v6
	v_rcp_f32_e32 v2, v2
	v_rcp_f32_e32 v7, v7
	v_rcp_f32_e32 v3, v3
	v_lshl_add_u64 v[20:21], s[40:41], 0, v[24:25]
	global_store_dwordx4 v[26:27], v[8:11], off
	s_waitcnt vmcnt(5)
	v_lshlrev_b32_e32 v22, 16, v200
	v_lshlrev_b32_e32 v8, 16, v196
	v_and_b32_e32 v9, 0xffff0000, v196
	v_lshlrev_b32_e32 v10, 16, v197
	v_and_b32_e32 v11, 0xffff0000, v197
	v_lshlrev_b32_e32 v12, 16, v198
	v_and_b32_e32 v13, 0xffff0000, v198
	v_lshlrev_b32_e32 v14, 16, v199
	v_and_b32_e32 v15, 0xffff0000, v199
	v_and_b32_e32 v16, 0xffff0000, v200
	v_lshlrev_b32_e32 v23, 16, v201
	v_and_b32_e32 v17, 0xffff0000, v201
	v_lshlrev_b32_e32 v24, 16, v202
	v_and_b32_e32 v18, 0xffff0000, v202
	v_lshlrev_b32_e32 v25, 16, v203
	v_and_b32_e32 v19, 0xffff0000, v203
	v_fmac_f32_e32 v8, v4, v22
	v_fmac_f32_e32 v12, v0, v24
	v_fmac_f32_e32 v9, v5, v16
	v_fmac_f32_e32 v13, v1, v18
	v_fmac_f32_e32 v10, v6, v23
	v_fmac_f32_e32 v14, v2, v25
	v_fmac_f32_e32 v11, v7, v17
	v_fmac_f32_e32 v15, v3, v19
	v_cvt_pk_bf16_f32 v0, v8, v9
	v_cvt_pk_bf16_f32 v1, v10, v11
	v_cvt_pk_bf16_f32 v2, v12, v13
	v_cvt_pk_bf16_f32 v3, v14, v15
	global_store_dwordx4 v[20:21], v[0:3], off
	s_cbranch_vccz .LBB0_1052
	s_waitcnt vmcnt(0)
	s_cmpk_gt_u32 s3, 0xff
	s_cbranch_scc1 .LBB0_1063
	s_barrier
